# E21 variant: accumulate chains ordered so that consecutive chains share the weight fragment registers (4 chains per weight fragment pair)
# speedup vs baseline: 1.0283x; 1.0054x over previous
;     __device__ __forceinline__ int nt(const Unit& u) const { return (u.pn >> 1) < 2 ? 22 : 20; }
; #define PG8_STAGE(bufoff, gbase, voff) do { _Pragma("unroll") for (int _i = 0; _i < 2; ++_i) \
;         __builtin_amdgcn_global_load_lds((const unsigned*)((const char*)(gbase) + (voff)[_i]), (LAS unsigned*)(lds + (bufoff) + ldsw + _i * 8192), 16, 0, 0); } while (0)
; #define PG8_LDA(dst, b, h) do { _Pragma("unroll") for (int m = 0; m < 4; ++m) _Pragma("unroll") for (int k = 0; k < 2; ++k) dst[m][k] = *(const LAS bf16x8*)(pA + PG8_SA(b, h) + m * 2048 + k * 1024); } while (0)
; #define PG8_LDB(dst, b, h) do { _Pragma("unroll") for (int n = 0; n < 2; ++n) _Pragma("unroll") for (int k = 0; k < 2; ++k) dst[n][k] = *(const LAS bf16x8*)(pB + (PG8_SB(b, h) - 4 * HTB) + n * 2048 + k * 1024); } while (0)
; #define PG8_MMA(ai, bj, At, Bt) do { __builtin_amdgcn_s_setprio(1); _Pragma("unroll") for (int m = 0; m < 4; ++m) _Pragma("unroll") for (int n = 0; n < 2; ++n) _Pragma("unroll") for (int k = 0; k < 2; ++k) \
;         acc[ai][bj][m][n] = __builtin_amdgcn_mfma_f32_16x16x32_bf16(Bt[n][k], At[m][k], acc[ai][bj][m][n], 0, 0, 0); __builtin_amdgcn_s_setprio(0); } while (0)
; #define PG8_WAIT_V(n) asm volatile("s_waitcnt vmcnt(" #n ")" ::: "memory")
; #define PG8_WAIT_L(n) asm volatile("s_waitcnt lgkmcnt(" #n ")" ::: "memory")
; #define PG8_BAR __builtin_amdgcn_s_barrier()
; template <class Desc, class Epi, bool ALIGN_EPI>
; __device__ __forceinline__ void gemm_phase(LAS unsigned char* lds, const Desc& D, const Epi& E, int G, int c) {
;     ...
;         for (int t = 0; t < nt; t += 2) {
;             const bool last = (t == nt - 2);
;             if (last && has_next) PG8_AWAIT(nxt);
;             const char* a1 = cA + (size_t)(t + 1) * kstep;
;             const char* a2 = last ? nA : cA + (size_t)(t + 2) * kstep; const char* b2 = last ? nB : cB + (size_t)(t + 2) * kstep;
;             const char* a3 = a2 + kstep; const char* b3 = b2 + kstep;
;             PG8_LDB(B0, 0, 0); PG8_LDB(B1, 0, 1); PG8_SCHED; PG8_LDA(At, 0, 0); PG8_STAGE(PG8_SA(1, 1), a1 + hstepA, voffA);
;             PG8_WAIT_V(8); PG8_WAIT_L(0); PG8_BAR; PG8_MMA(0, 0, At, B0); PG8_MMA(0, 1, At, B1); PG8_BAR; PG8_SCHED;
;             PG8_LDA(At, 0, 1); PG8_STAGE(PG8_SB(0, 0), b2, voffB); PG8_STAGE(PG8_SB(0, 1), b2 + hstepB, voffB); PG8_STAGE(PG8_SA(0, 0), a2, voffA);
.LBB0_172:
	s_or_b32 s14, s17, 1
	s_lshl_b64 s[26:27], s[14:15], 7
	s_add_i32 s14, s17, 2
	s_lshl_b64 s[40:41], s[14:15], 7
	s_add_u32 s17, s12, s40
	ds_read_b128 v[134:137], v169
	ds_read_b128 v[138:141], v169 offset:1024
	ds_read_b128 v[142:145], v169 offset:2048
	ds_read_b128 v[146:149], v169 offset:3072
	ds_read_b128 v[160:163], v169 offset:16384
	ds_read_b128 v[164:167], v169 offset:17408
	ds_read_b128 v[174:177], v169 offset:18432
	ds_read_b128 v[178:181], v169 offset:19456
	s_addc_u32 s21, s13, s41
	s_and_b64 s[38:39], s[30:31], exec
	s_cselect_b32 s39, s61, s21
	s_cselect_b32 s38, s60, s17
	s_add_u32 s17, s18, s40
	s_addc_u32 s21, s19, s41
	s_and_b64 s[30:31], s[30:31], exec
	s_cselect_b32 s31, s63, s21
	s_cselect_b32 s30, s62, s17
	s_add_u32 s17, s12, s26
	s_addc_u32 s21, s13, s27
	s_add_u32 s26, s17, 0x100000
	s_addc_u32 s27, s21, 0
	s_mov_b32 m0, s50
	v_lshl_add_u64 v[150:151], s[26:27], 0, v[152:153]
	ds_read_b128 v[182:185], v168
	ds_read_b128 v[186:189], v168 offset:1024
	ds_read_b128 v[190:193], v168 offset:2048
	ds_read_b128 v[194:197], v168 offset:3072
	ds_read_b128 v[198:201], v168 offset:4096
	ds_read_b128 v[202:205], v168 offset:5120
	ds_read_b128 v[206:209], v168 offset:6144
	ds_read_b128 v[210:213], v168 offset:7168
	global_load_lds_dwordx4 v[150:151], off
	v_lshl_add_u64 v[150:151], s[26:27], 0, v[156:157]
	s_mov_b32 m0, s51
	s_nop 0
	global_load_lds_dwordx4 v[150:151], off
	s_waitcnt vmcnt(8)
	s_waitcnt lgkmcnt(0)
	s_barrier
	v_mfma_f32_16x16x32_bf16 v[128:131], v[134:137], v[182:185], v[128:131]
	v_mfma_f32_16x16x32_bf16 v[128:131], v[138:141], v[186:189], v[128:131]
	v_mfma_f32_16x16x32_bf16 v[120:123], v[134:137], v[190:193], v[120:123]
	v_mfma_f32_16x16x32_bf16 v[120:123], v[138:141], v[194:197], v[120:123]
	v_mfma_f32_16x16x32_bf16 v[112:115], v[134:137], v[198:201], v[112:115]
	v_mfma_f32_16x16x32_bf16 v[112:115], v[138:141], v[202:205], v[112:115]
	v_mfma_f32_16x16x32_bf16 v[104:107], v[134:137], v[206:209], v[104:107]
	v_mfma_f32_16x16x32_bf16 v[104:107], v[138:141], v[210:213], v[104:107]
	v_mfma_f32_16x16x32_bf16 v[124:127], v[142:145], v[182:185], v[124:127]
	v_mfma_f32_16x16x32_bf16 v[124:127], v[146:149], v[186:189], v[124:127]
	v_mfma_f32_16x16x32_bf16 v[116:119], v[142:145], v[190:193], v[116:119]
	v_mfma_f32_16x16x32_bf16 v[116:119], v[146:149], v[194:197], v[116:119]
	v_mfma_f32_16x16x32_bf16 v[108:111], v[142:145], v[198:201], v[108:111]
	v_mfma_f32_16x16x32_bf16 v[108:111], v[146:149], v[202:205], v[108:111]
	v_mfma_f32_16x16x32_bf16 v[100:103], v[142:145], v[206:209], v[100:103]
	v_mfma_f32_16x16x32_bf16 v[100:103], v[146:149], v[210:213], v[100:103]
	v_mfma_f32_16x16x32_bf16 v[96:99], v[160:163], v[182:185], v[96:99]
	v_mfma_f32_16x16x32_bf16 v[96:99], v[164:167], v[186:189], v[96:99]
	v_mfma_f32_16x16x32_bf16 v[88:91], v[160:163], v[190:193], v[88:91]
	v_mfma_f32_16x16x32_bf16 v[88:91], v[164:167], v[194:197], v[88:91]
	v_mfma_f32_16x16x32_bf16 v[80:83], v[160:163], v[198:201], v[80:83]
	v_mfma_f32_16x16x32_bf16 v[80:83], v[164:167], v[202:205], v[80:83]
	v_mfma_f32_16x16x32_bf16 v[72:75], v[160:163], v[206:209], v[72:75]
	v_mfma_f32_16x16x32_bf16 v[72:75], v[164:167], v[210:213], v[72:75]
	v_mfma_f32_16x16x32_bf16 v[92:95], v[174:177], v[182:185], v[92:95]
	v_mfma_f32_16x16x32_bf16 v[92:95], v[178:181], v[186:189], v[92:95]
	v_mfma_f32_16x16x32_bf16 v[84:87], v[174:177], v[190:193], v[84:87]
	v_mfma_f32_16x16x32_bf16 v[84:87], v[178:181], v[194:197], v[84:87]
	v_mfma_f32_16x16x32_bf16 v[76:79], v[174:177], v[198:201], v[76:79]
	v_mfma_f32_16x16x32_bf16 v[76:79], v[178:181], v[202:205], v[76:79]
	v_mfma_f32_16x16x32_bf16 v[68:71], v[174:177], v[206:209], v[68:71]
	v_mfma_f32_16x16x32_bf16 v[68:71], v[178:181], v[210:213], v[68:71]
	s_barrier
	s_mov_b32 m0, s84
	v_lshl_add_u64 v[150:151], s[30:31], 0, v[154:155]
	s_add_u32 s26, s30, 0x100000
	ds_read_b128 v[182:185], v168 offset:16384
	ds_read_b128 v[186:189], v168 offset:17408
	ds_read_b128 v[190:193], v168 offset:18432
	ds_read_b128 v[194:197], v168 offset:19456
	ds_read_b128 v[198:201], v168 offset:20480
	ds_read_b128 v[202:205], v168 offset:21504
	ds_read_b128 v[206:209], v168 offset:22528
	ds_read_b128 v[210:213], v168 offset:23552
	global_load_lds_dwordx4 v[150:151], off
	v_lshl_add_u64 v[214:215], s[30:31], 0, v[158:159]
	s_mov_b32 m0, s85
	s_addc_u32 s27, s31, 0
	global_load_lds_dwordx4 v[214:215], off
	v_lshl_add_u64 v[216:217], s[26:27], 0, v[154:155]
	s_mov_b32 m0, s86
	v_lshl_add_u64 v[218:219], s[38:39], 0, v[156:157]
	global_load_lds_dwordx4 v[216:217], off
	v_lshl_add_u64 v[216:217], s[26:27], 0, v[158:159]
	s_mov_b32 m0, s87
	s_nop 0
	global_load_lds_dwordx4 v[216:217], off
	v_lshl_add_u64 v[216:217], s[38:39], 0, v[152:153]
	s_mov_b32 m0, s83
	s_nop 0
	global_load_lds_dwordx4 v[216:217], off
	s_mov_b32 m0, s88
	s_nop 0
	global_load_lds_dwordx4 v[218:219], off
	s_waitcnt vmcnt(8)
	s_waitcnt lgkmcnt(0)
	s_barrier
; #define PG8_STAGE(bufoff, gbase, voff) do { _Pragma("unroll") for (int _i = 0; _i < 2; ++_i) \
;         __builtin_amdgcn_global_load_lds((const unsigned*)((const char*)(gbase) + (voff)[_i]), (LAS unsigned*)(lds + (bufoff) + ldsw + _i * 8192), 16, 0, 0); } while (0)
; #define PG8_LDA(dst, b, h) do { _Pragma("unroll") for (int m = 0; m < 4; ++m) _Pragma("unroll") for (int k = 0; k < 2; ++k) dst[m][k] = *(const LAS bf16x8*)(pA + PG8_SA(b, h) + m * 2048 + k * 1024); } while (0)
; #define PG8_LDB(dst, b, h) do { _Pragma("unroll") for (int n = 0; n < 2; ++n) _Pragma("unroll") for (int k = 0; k < 2; ++k) dst[n][k] = *(const LAS bf16x8*)(pB + (PG8_SB(b, h) - 4 * HTB) + n * 2048 + k * 1024); } while (0)
; #define PG8_MMA(ai, bj, At, Bt) do { __builtin_amdgcn_s_setprio(1); _Pragma("unroll") for (int m = 0; m < 4; ++m) _Pragma("unroll") for (int n = 0; n < 2; ++n) _Pragma("unroll") for (int k = 0; k < 2; ++k) \
;         acc[ai][bj][m][n] = __builtin_amdgcn_mfma_f32_16x16x32_bf16(Bt[n][k], At[m][k], acc[ai][bj][m][n], 0, 0, 0); __builtin_amdgcn_s_setprio(0); } while (0)
; #define PG8_WAIT_V(n) asm volatile("s_waitcnt vmcnt(" #n ")" ::: "memory")
; #define PG8_WAIT_L(n) asm volatile("s_waitcnt lgkmcnt(" #n ")" ::: "memory")
; #define PG8_BAR __builtin_amdgcn_s_barrier()
; #define PG8_SCHED __builtin_amdgcn_sched_barrier(0)
; template <class Desc, class Epi, bool ALIGN_EPI>
; __device__ __forceinline__ void gemm_phase(LAS unsigned char* lds, const Desc& D, const Epi& E, int G, int c) {
;     ...
;             PG8_WAIT_V(8); PG8_WAIT_L(0); PG8_BAR; PG8_MMA(0, 0, At, B0); PG8_MMA(0, 1, At, B1); PG8_BAR; PG8_SCHED;
;             PG8_LDA(At, 0, 1); PG8_STAGE(PG8_SB(0, 0), b2, voffB); PG8_STAGE(PG8_SB(0, 1), b2 + hstepB, voffB); PG8_STAGE(PG8_SA(0, 0), a2, voffA);
;             PG8_WAIT_V(8); PG8_WAIT_L(0); PG8_BAR; PG8_MMA(1, 0, At, B0); PG8_MMA(1, 1, At, B1); PG8_BAR; PG8_SCHED;
;             PG8_LDB(B0, 1, 0); PG8_LDB(B1, 1, 1); PG8_SCHED; PG8_LDA(At, 1, 0); PG8_STAGE(PG8_SA(0, 1), a2 + hstepA, voffA);
;             PG8_WAIT_V(8); PG8_WAIT_L(0); PG8_BAR; PG8_MMA(0, 0, At, B0); PG8_MMA(0, 1, At, B1); PG8_BAR; PG8_SCHED;
	v_mfma_f32_16x16x32_bf16 v[64:67], v[134:137], v[182:185], v[64:67]
	v_mfma_f32_16x16x32_bf16 v[64:67], v[138:141], v[186:189], v[64:67]
	v_mfma_f32_16x16x32_bf16 v[32:35], v[134:137], v[190:193], v[32:35]
	v_mfma_f32_16x16x32_bf16 v[32:35], v[138:141], v[194:197], v[32:35]
	v_mfma_f32_16x16x32_bf16 v[16:19], v[134:137], v[198:201], v[16:19]
	v_mfma_f32_16x16x32_bf16 v[16:19], v[138:141], v[202:205], v[16:19]
	v_mfma_f32_16x16x32_bf16 v[8:11], v[134:137], v[206:209], v[8:11]
	v_mfma_f32_16x16x32_bf16 v[8:11], v[138:141], v[210:213], v[8:11]
	v_mfma_f32_16x16x32_bf16 v[52:55], v[142:145], v[182:185], v[52:55]
	v_mfma_f32_16x16x32_bf16 v[52:55], v[146:149], v[186:189], v[52:55]
	v_mfma_f32_16x16x32_bf16 v[20:23], v[142:145], v[190:193], v[20:23]
	v_mfma_f32_16x16x32_bf16 v[20:23], v[146:149], v[194:197], v[20:23]
	v_mfma_f32_16x16x32_bf16 v[12:15], v[142:145], v[198:201], v[12:15]
	v_mfma_f32_16x16x32_bf16 v[12:15], v[146:149], v[202:205], v[12:15]
	v_mfma_f32_16x16x32_bf16 v[4:7], v[142:145], v[206:209], v[4:7]
	v_mfma_f32_16x16x32_bf16 v[4:7], v[146:149], v[210:213], v[4:7]
	v_mfma_f32_16x16x32_bf16 v[60:63], v[160:163], v[182:185], v[60:63]
	v_mfma_f32_16x16x32_bf16 v[60:63], v[164:167], v[186:189], v[60:63]
	v_mfma_f32_16x16x32_bf16 v[48:51], v[160:163], v[190:193], v[48:51]
	v_mfma_f32_16x16x32_bf16 v[48:51], v[164:167], v[194:197], v[48:51]
	v_mfma_f32_16x16x32_bf16 v[40:43], v[160:163], v[198:201], v[40:43]
	v_mfma_f32_16x16x32_bf16 v[40:43], v[164:167], v[202:205], v[40:43]
	v_mfma_f32_16x16x32_bf16 v[28:31], v[160:163], v[206:209], v[28:31]
	v_mfma_f32_16x16x32_bf16 v[28:31], v[164:167], v[210:213], v[28:31]
	v_mfma_f32_16x16x32_bf16 v[56:59], v[174:177], v[182:185], v[56:59]
	v_mfma_f32_16x16x32_bf16 v[56:59], v[178:181], v[186:189], v[56:59]
	v_mfma_f32_16x16x32_bf16 v[44:47], v[174:177], v[190:193], v[44:47]
	v_mfma_f32_16x16x32_bf16 v[44:47], v[178:181], v[194:197], v[44:47]
	v_mfma_f32_16x16x32_bf16 v[36:39], v[174:177], v[198:201], v[36:39]
	v_mfma_f32_16x16x32_bf16 v[36:39], v[178:181], v[202:205], v[36:39]
	v_mfma_f32_16x16x32_bf16 v[24:27], v[174:177], v[206:209], v[24:27]
	v_mfma_f32_16x16x32_bf16 v[24:27], v[178:181], v[210:213], v[24:27]
	s_barrier
	ds_read_b128 v[134:137], v169 offset:32768
	ds_read_b128 v[138:141], v169 offset:33792
	ds_read_b128 v[142:145], v169 offset:34816
	ds_read_b128 v[146:149], v169 offset:35840
	ds_read_b128 v[160:163], v169 offset:49152
	ds_read_b128 v[164:167], v169 offset:50176
	ds_read_b128 v[174:177], v169 offset:51200
	ds_read_b128 v[178:181], v169 offset:52224
	s_add_u32 s26, s38, 0x100000
	s_addc_u32 s27, s39, 0
	s_mov_b32 m0, s89
	v_lshl_add_u64 v[220:221], s[26:27], 0, v[152:153]
	ds_read_b128 v[182:185], v168 offset:32768
	ds_read_b128 v[186:189], v168 offset:33792
	ds_read_b128 v[190:193], v168 offset:34816
	ds_read_b128 v[194:197], v168 offset:35840
	ds_read_b128 v[198:201], v168 offset:36864
	ds_read_b128 v[202:205], v168 offset:37888
	ds_read_b128 v[206:209], v168 offset:38912
	ds_read_b128 v[210:213], v168 offset:39936
	global_load_lds_dwordx4 v[220:221], off
	v_lshl_add_u64 v[220:221], s[26:27], 0, v[156:157]
	s_mov_b32 m0, s90
	s_nop 0
	global_load_lds_dwordx4 v[220:221], off
	s_waitcnt vmcnt(8)
	s_waitcnt lgkmcnt(0)
	s_barrier
	v_mfma_f32_16x16x32_bf16 v[128:131], v[134:137], v[182:185], v[128:131]
	v_mfma_f32_16x16x32_bf16 v[128:131], v[138:141], v[186:189], v[128:131]
	v_mfma_f32_16x16x32_bf16 v[120:123], v[134:137], v[190:193], v[120:123]
	v_mfma_f32_16x16x32_bf16 v[120:123], v[138:141], v[194:197], v[120:123]
	v_mfma_f32_16x16x32_bf16 v[112:115], v[134:137], v[198:201], v[112:115]
	v_mfma_f32_16x16x32_bf16 v[112:115], v[138:141], v[202:205], v[112:115]
	v_mfma_f32_16x16x32_bf16 v[104:107], v[134:137], v[206:209], v[104:107]
	v_mfma_f32_16x16x32_bf16 v[104:107], v[138:141], v[210:213], v[104:107]
	v_mfma_f32_16x16x32_bf16 v[124:127], v[142:145], v[182:185], v[124:127]
	v_mfma_f32_16x16x32_bf16 v[124:127], v[146:149], v[186:189], v[124:127]
	v_mfma_f32_16x16x32_bf16 v[116:119], v[142:145], v[190:193], v[116:119]
	v_mfma_f32_16x16x32_bf16 v[116:119], v[146:149], v[194:197], v[116:119]
	v_mfma_f32_16x16x32_bf16 v[108:111], v[142:145], v[198:201], v[108:111]
	v_mfma_f32_16x16x32_bf16 v[108:111], v[146:149], v[202:205], v[108:111]
	v_mfma_f32_16x16x32_bf16 v[100:103], v[142:145], v[206:209], v[100:103]
	v_mfma_f32_16x16x32_bf16 v[100:103], v[146:149], v[210:213], v[100:103]
	v_mfma_f32_16x16x32_bf16 v[96:99], v[160:163], v[182:185], v[96:99]
	v_mfma_f32_16x16x32_bf16 v[96:99], v[164:167], v[186:189], v[96:99]
	v_mfma_f32_16x16x32_bf16 v[88:91], v[160:163], v[190:193], v[88:91]
	v_mfma_f32_16x16x32_bf16 v[88:91], v[164:167], v[194:197], v[88:91]
	v_mfma_f32_16x16x32_bf16 v[80:83], v[160:163], v[198:201], v[80:83]
	v_mfma_f32_16x16x32_bf16 v[80:83], v[164:167], v[202:205], v[80:83]
	v_mfma_f32_16x16x32_bf16 v[72:75], v[160:163], v[206:209], v[72:75]
	v_mfma_f32_16x16x32_bf16 v[72:75], v[164:167], v[210:213], v[72:75]
	v_mfma_f32_16x16x32_bf16 v[92:95], v[174:177], v[182:185], v[92:95]
	v_mfma_f32_16x16x32_bf16 v[92:95], v[178:181], v[186:189], v[92:95]
	v_mfma_f32_16x16x32_bf16 v[84:87], v[174:177], v[190:193], v[84:87]
	v_mfma_f32_16x16x32_bf16 v[84:87], v[178:181], v[194:197], v[84:87]
	v_mfma_f32_16x16x32_bf16 v[76:79], v[174:177], v[198:201], v[76:79]
	v_mfma_f32_16x16x32_bf16 v[76:79], v[178:181], v[202:205], v[76:79]
	v_mfma_f32_16x16x32_bf16 v[68:71], v[174:177], v[206:209], v[68:71]
	v_mfma_f32_16x16x32_bf16 v[68:71], v[178:181], v[210:213], v[68:71]
	s_barrier
; #define PG8_STAGE(bufoff, gbase, voff) do { _Pragma("unroll") for (int _i = 0; _i < 2; ++_i) \
;         __builtin_amdgcn_global_load_lds((const unsigned*)((const char*)(gbase) + (voff)[_i]), (LAS unsigned*)(lds + (bufoff) + ldsw + _i * 8192), 16, 0, 0); } while (0)
; #define PG8_LDA(dst, b, h) do { _Pragma("unroll") for (int m = 0; m < 4; ++m) _Pragma("unroll") for (int k = 0; k < 2; ++k) dst[m][k] = *(const LAS bf16x8*)(pA + PG8_SA(b, h) + m * 2048 + k * 1024); } while (0)
; #define PG8_MMA(ai, bj, At, Bt) do { __builtin_amdgcn_s_setprio(1); _Pragma("unroll") for (int m = 0; m < 4; ++m) _Pragma("unroll") for (int n = 0; n < 2; ++n) _Pragma("unroll") for (int k = 0; k < 2; ++k) \
;         acc[ai][bj][m][n] = __builtin_amdgcn_mfma_f32_16x16x32_bf16(Bt[n][k], At[m][k], acc[ai][bj][m][n], 0, 0, 0); __builtin_amdgcn_s_setprio(0); } while (0)
; #define PG8_WAIT_V(n) asm volatile("s_waitcnt vmcnt(" #n ")" ::: "memory")
; #define PG8_WAIT_L(n) asm volatile("s_waitcnt lgkmcnt(" #n ")" ::: "memory")
; #define PG8_BAR __builtin_amdgcn_s_barrier()
; #define PG8_SCHED __builtin_amdgcn_sched_barrier(0)
; template <class Desc, class Epi, bool ALIGN_EPI>
; __device__ __forceinline__ void gemm_phase(LAS unsigned char* lds, const Desc& D, const Epi& E, int G, int c) {
;     ...
;             PG8_LDA(At, 1, 1); PG8_STAGE(PG8_SB(1, 0), b3, voffB); PG8_STAGE(PG8_SB(1, 1), b3 + hstepB, voffB); PG8_STAGE(PG8_SA(1, 0), a3, voffA);
;             PG8_WAIT_V(8); PG8_WAIT_L(0); PG8_BAR; PG8_MMA(1, 0, At, B0); PG8_MMA(1, 1, At, B1); PG8_BAR; PG8_SCHED;
;         }
	s_mov_b32 m0, s92
	v_lshl_add_u64 v[150:151], v[150:151], 0, s[76:77]
	s_add_u32 s26, s30, 0x100080
	ds_read_b128 v[182:185], v168 offset:49152
	ds_read_b128 v[186:189], v168 offset:50176
	ds_read_b128 v[190:193], v168 offset:51200
	ds_read_b128 v[194:197], v168 offset:52224
	ds_read_b128 v[198:201], v168 offset:53248
	ds_read_b128 v[202:205], v168 offset:54272
	ds_read_b128 v[206:209], v168 offset:55296
	ds_read_b128 v[210:213], v168 offset:56320
	global_load_lds_dwordx4 v[150:151], off
	v_lshl_add_u64 v[150:151], v[214:215], 0, s[76:77]
	s_mov_b32 m0, s93
	s_addc_u32 s27, s31, 0
	global_load_lds_dwordx4 v[150:151], off
	v_lshl_add_u64 v[150:151], s[26:27], 0, v[154:155]
	s_mov_b32 m0, s97
	s_nop 0
	global_load_lds_dwordx4 v[150:151], off
	v_lshl_add_u64 v[150:151], s[26:27], 0, v[158:159]
	s_mov_b32 m0, s82
	s_nop 0
	global_load_lds_dwordx4 v[150:151], off
	v_lshl_add_u64 v[150:151], v[216:217], 0, s[76:77]
	s_mov_b32 m0, s94
	s_nop 0
	global_load_lds_dwordx4 v[150:151], off
	v_lshl_add_u64 v[150:151], v[218:219], 0, s[76:77]
	s_mov_b32 m0, s95
	s_nop 0
	global_load_lds_dwordx4 v[150:151], off
	s_waitcnt vmcnt(8)
	s_waitcnt lgkmcnt(0)
	s_barrier
	v_mfma_f32_16x16x32_bf16 v[64:67], v[134:137], v[182:185], v[64:67]
	v_mfma_f32_16x16x32_bf16 v[64:67], v[138:141], v[186:189], v[64:67]
	v_mfma_f32_16x16x32_bf16 v[32:35], v[134:137], v[190:193], v[32:35]
	v_mfma_f32_16x16x32_bf16 v[32:35], v[138:141], v[194:197], v[32:35]
	v_mfma_f32_16x16x32_bf16 v[16:19], v[134:137], v[198:201], v[16:19]
	v_mfma_f32_16x16x32_bf16 v[16:19], v[138:141], v[202:205], v[16:19]
	v_mfma_f32_16x16x32_bf16 v[8:11], v[134:137], v[206:209], v[8:11]
	v_mfma_f32_16x16x32_bf16 v[8:11], v[138:141], v[210:213], v[8:11]
	v_mfma_f32_16x16x32_bf16 v[52:55], v[142:145], v[182:185], v[52:55]
	v_mfma_f32_16x16x32_bf16 v[52:55], v[146:149], v[186:189], v[52:55]
	v_mfma_f32_16x16x32_bf16 v[20:23], v[142:145], v[190:193], v[20:23]
	v_mfma_f32_16x16x32_bf16 v[20:23], v[146:149], v[194:197], v[20:23]
	v_mfma_f32_16x16x32_bf16 v[12:15], v[142:145], v[198:201], v[12:15]
	v_mfma_f32_16x16x32_bf16 v[12:15], v[146:149], v[202:205], v[12:15]
	v_mfma_f32_16x16x32_bf16 v[4:7], v[142:145], v[206:209], v[4:7]
	v_mfma_f32_16x16x32_bf16 v[4:7], v[146:149], v[210:213], v[4:7]
	v_mfma_f32_16x16x32_bf16 v[60:63], v[160:163], v[182:185], v[60:63]
	v_mfma_f32_16x16x32_bf16 v[60:63], v[164:167], v[186:189], v[60:63]
	v_mfma_f32_16x16x32_bf16 v[48:51], v[160:163], v[190:193], v[48:51]
	v_mfma_f32_16x16x32_bf16 v[48:51], v[164:167], v[194:197], v[48:51]
	v_mfma_f32_16x16x32_bf16 v[40:43], v[160:163], v[198:201], v[40:43]
	v_mfma_f32_16x16x32_bf16 v[40:43], v[164:167], v[202:205], v[40:43]
	v_mfma_f32_16x16x32_bf16 v[28:31], v[160:163], v[206:209], v[28:31]
	v_mfma_f32_16x16x32_bf16 v[28:31], v[164:167], v[210:213], v[28:31]
	v_mfma_f32_16x16x32_bf16 v[56:59], v[174:177], v[182:185], v[56:59]
	v_mfma_f32_16x16x32_bf16 v[56:59], v[178:181], v[186:189], v[56:59]
	v_mfma_f32_16x16x32_bf16 v[44:47], v[174:177], v[190:193], v[44:47]
	v_mfma_f32_16x16x32_bf16 v[44:47], v[178:181], v[194:197], v[44:47]
	v_mfma_f32_16x16x32_bf16 v[36:39], v[174:177], v[198:201], v[36:39]
	v_mfma_f32_16x16x32_bf16 v[36:39], v[178:181], v[202:205], v[36:39]
	v_mfma_f32_16x16x32_bf16 v[24:27], v[174:177], v[206:209], v[24:27]
	v_mfma_f32_16x16x32_bf16 v[24:27], v[178:181], v[210:213], v[24:27]
	s_barrier
	s_cmp_ge_u32 s14, s3
	s_mov_b32 s17, s14
	s_cbranch_scc1 .LBB0_183

;     __device__ __forceinline__ int nt(const Unit& u) const { return (u.pn >> 1) < 2 ? 22 : 20; }
; #define PG8_STAGE(bufoff, gbase, voff) do { _Pragma("unroll") for (int _i = 0; _i < 2; ++_i) \
;         __builtin_amdgcn_global_load_lds((const unsigned*)((const char*)(gbase) + (voff)[_i]), (LAS unsigned*)(lds + (bufoff) + ldsw + _i * 8192), 16, 0, 0); } while (0)
; #define PG8_LDA(dst, b, h) do { _Pragma("unroll") for (int m = 0; m < 4; ++m) _Pragma("unroll") for (int k = 0; k < 2; ++k) dst[m][k] = *(const LAS bf16x8*)(pA + PG8_SA(b, h) + m * 2048 + k * 1024); } while (0)
; #define PG8_LDB(dst, b, h) do { _Pragma("unroll") for (int n = 0; n < 2; ++n) _Pragma("unroll") for (int k = 0; k < 2; ++k) dst[n][k] = *(const LAS bf16x8*)(pB + (PG8_SB(b, h) - 4 * HTB) + n * 2048 + k * 1024); } while (0)
; #define PG8_MMA(ai, bj, At, Bt) do { __builtin_amdgcn_s_setprio(1); _Pragma("unroll") for (int m = 0; m < 4; ++m) _Pragma("unroll") for (int n = 0; n < 2; ++n) _Pragma("unroll") for (int k = 0; k < 2; ++k) \
;         acc[ai][bj][m][n] = __builtin_amdgcn_mfma_f32_16x16x32_bf16(Bt[n][k], At[m][k], acc[ai][bj][m][n], 0, 0, 0); __builtin_amdgcn_s_setprio(0); } while (0)
; #define PG8_WAIT_V(n) asm volatile("s_waitcnt vmcnt(" #n ")" ::: "memory")
; #define PG8_BAR __builtin_amdgcn_s_barrier()
; template <class Desc, class Epi, bool ALIGN_EPI>
; __device__ __forceinline__ void gemm_phase(LAS unsigned char* lds, const Desc& D, const Epi& E, int G, int c) {
;     ...
;         for (int t = 0; t < nt; t += 2) {
;             const bool last = (t == nt - 2);
;             if (last && has_next) PG8_AWAIT(nxt);
;             const char* a1 = cA + (size_t)(t + 1) * kstep;
;             const char* a2 = last ? nA : cA + (size_t)(t + 2) * kstep; const char* b2 = last ? nB : cB + (size_t)(t + 2) * kstep;
;             const char* a3 = a2 + kstep; const char* b3 = b2 + kstep;
;             PG8_LDB(B0, 0, 0); PG8_LDB(B1, 0, 1); PG8_SCHED; PG8_LDA(At, 0, 0); PG8_STAGE(PG8_SA(1, 1), a1 + hstepA, voffA);
;             PG8_WAIT_V(8); PG8_WAIT_L(0); PG8_BAR; PG8_MMA(0, 0, At, B0); PG8_MMA(0, 1, At, B1); PG8_BAR; PG8_SCHED;
;             PG8_LDA(At, 0, 1); PG8_STAGE(PG8_SB(0, 0), b2, voffB); PG8_STAGE(PG8_SB(0, 1), b2 + hstepB, voffB); PG8_STAGE(PG8_SA(0, 0), a2, voffA);
;             PG8_WAIT_V(8); PG8_WAIT_L(0); PG8_BAR; PG8_MMA(1, 0, At, B0); PG8_MMA(1, 1, At, B1); PG8_BAR; PG8_SCHED;
.LBB0_603:
	ds_read_b128 v[144:147], v149
	ds_read_b128 v[152:155], v149 offset:1024
	ds_read_b128 v[156:159], v149 offset:2048
	ds_read_b128 v[160:163], v149 offset:3072
	ds_read_b128 v[164:167], v149 offset:16384
	ds_read_b128 v[168:171], v149 offset:17408
	ds_read_b128 v[172:175], v149 offset:18432
	ds_read_b128 v[176:179], v149 offset:19456
	s_add_u32 s16, s12, 0xfff80080
	s_addc_u32 s17, s13, -1
	s_cmp_eq_u32 s46, 4
	s_cselect_b32 s19, s9, s17
	s_cselect_b32 s18, s8, s16
	s_cselect_b32 s17, s11, s45
	s_cselect_b32 s16, s10, s7
	v_lshl_add_u64 v[212:213], s[12:13], 0, v[140:141]
	s_add_i32 m0, s20, 0xc000
	ds_read_b128 v[180:183], v148
	ds_read_b128 v[184:187], v148 offset:1024
	ds_read_b128 v[188:191], v148 offset:2048
	ds_read_b128 v[192:195], v148 offset:3072
	ds_read_b128 v[196:199], v148 offset:4096
	ds_read_b128 v[200:203], v148 offset:5120
	ds_read_b128 v[204:207], v148 offset:6144
	ds_read_b128 v[208:211], v148 offset:7168
	global_load_lds_dwordx4 v[212:213], off
	v_lshl_add_u64 v[212:213], s[12:13], 0, v[142:143]
	s_add_i32 m0, s20, 0xe000
	s_nop 0
	global_load_lds_dwordx4 v[212:213], off
	s_waitcnt vmcnt(8)
	s_waitcnt lgkmcnt(0)
	s_barrier
	v_mfma_f32_16x16x32_bf16 v[128:131], v[144:147], v[180:183], v[128:131]
	v_mfma_f32_16x16x32_bf16 v[128:131], v[152:155], v[184:187], v[128:131]
	v_mfma_f32_16x16x32_bf16 v[116:119], v[144:147], v[188:191], v[116:119]
	v_mfma_f32_16x16x32_bf16 v[116:119], v[152:155], v[192:195], v[116:119]
	v_mfma_f32_16x16x32_bf16 v[100:103], v[144:147], v[196:199], v[100:103]
	v_mfma_f32_16x16x32_bf16 v[100:103], v[152:155], v[200:203], v[100:103]
	v_mfma_f32_16x16x32_bf16 v[84:87], v[144:147], v[204:207], v[84:87]
	v_mfma_f32_16x16x32_bf16 v[84:87], v[152:155], v[208:211], v[84:87]
	v_mfma_f32_16x16x32_bf16 v[124:127], v[156:159], v[180:183], v[124:127]
	v_mfma_f32_16x16x32_bf16 v[124:127], v[160:163], v[184:187], v[124:127]
	v_mfma_f32_16x16x32_bf16 v[108:111], v[156:159], v[188:191], v[108:111]
	v_mfma_f32_16x16x32_bf16 v[108:111], v[160:163], v[192:195], v[108:111]
	v_mfma_f32_16x16x32_bf16 v[92:95], v[156:159], v[196:199], v[92:95]
	v_mfma_f32_16x16x32_bf16 v[92:95], v[160:163], v[200:203], v[92:95]
	v_mfma_f32_16x16x32_bf16 v[76:79], v[156:159], v[204:207], v[76:79]
	v_mfma_f32_16x16x32_bf16 v[76:79], v[160:163], v[208:211], v[76:79]
	v_mfma_f32_16x16x32_bf16 v[120:123], v[164:167], v[180:183], v[120:123]
	v_mfma_f32_16x16x32_bf16 v[120:123], v[168:171], v[184:187], v[120:123]
	v_mfma_f32_16x16x32_bf16 v[104:107], v[164:167], v[188:191], v[104:107]
	v_mfma_f32_16x16x32_bf16 v[104:107], v[168:171], v[192:195], v[104:107]
	v_mfma_f32_16x16x32_bf16 v[88:91], v[164:167], v[196:199], v[88:91]
	v_mfma_f32_16x16x32_bf16 v[88:91], v[168:171], v[200:203], v[88:91]
	v_mfma_f32_16x16x32_bf16 v[72:75], v[164:167], v[204:207], v[72:75]
	v_mfma_f32_16x16x32_bf16 v[72:75], v[168:171], v[208:211], v[72:75]
	v_mfma_f32_16x16x32_bf16 v[112:115], v[172:175], v[180:183], v[112:115]
	v_mfma_f32_16x16x32_bf16 v[112:115], v[176:179], v[184:187], v[112:115]
	v_mfma_f32_16x16x32_bf16 v[96:99], v[172:175], v[188:191], v[96:99]
	v_mfma_f32_16x16x32_bf16 v[96:99], v[176:179], v[192:195], v[96:99]
	v_mfma_f32_16x16x32_bf16 v[80:83], v[172:175], v[196:199], v[80:83]
	v_mfma_f32_16x16x32_bf16 v[80:83], v[176:179], v[200:203], v[80:83]
	v_mfma_f32_16x16x32_bf16 v[68:71], v[172:175], v[204:207], v[68:71]
	v_mfma_f32_16x16x32_bf16 v[68:71], v[176:179], v[208:211], v[68:71]
	s_barrier
	s_mov_b32 m0, s21
	v_lshl_add_u64 v[212:213], s[16:17], 0, v[136:137]
	s_add_u32 s48, s16, 0x20000
	ds_read_b128 v[180:183], v148 offset:16384
	ds_read_b128 v[184:187], v148 offset:17408
	ds_read_b128 v[188:191], v148 offset:18432
	ds_read_b128 v[192:195], v148 offset:19456
	ds_read_b128 v[196:199], v148 offset:20480
	ds_read_b128 v[200:203], v148 offset:21504
	ds_read_b128 v[204:207], v148 offset:22528
	ds_read_b128 v[208:211], v148 offset:23552
	global_load_lds_dwordx4 v[212:213], off
	v_lshl_add_u64 v[214:215], s[16:17], 0, v[132:133]
	s_mov_b32 m0, s23
	s_addc_u32 s49, s17, 0
	global_load_lds_dwordx4 v[214:215], off
	v_lshl_add_u64 v[216:217], s[48:49], 0, v[136:137]
	s_mov_b32 m0, s24
	v_lshl_add_u64 v[218:219], s[18:19], 0, v[134:135]
	global_load_lds_dwordx4 v[216:217], off
	v_lshl_add_u64 v[216:217], s[48:49], 0, v[132:133]
	s_mov_b32 m0, s25
	s_nop 0
	global_load_lds_dwordx4 v[216:217], off
	v_lshl_add_u64 v[216:217], s[18:19], 0, v[138:139]
	s_mov_b32 m0, s20
	s_nop 0
	global_load_lds_dwordx4 v[216:217], off
	s_mov_b32 m0, s26
	s_nop 0
	global_load_lds_dwordx4 v[218:219], off
	s_waitcnt vmcnt(8)
	s_waitcnt lgkmcnt(0)
	s_barrier
; #define PG8_STAGE(bufoff, gbase, voff) do { _Pragma("unroll") for (int _i = 0; _i < 2; ++_i) \
;         __builtin_amdgcn_global_load_lds((const unsigned*)((const char*)(gbase) + (voff)[_i]), (LAS unsigned*)(lds + (bufoff) + ldsw + _i * 8192), 16, 0, 0); } while (0)
; #define PG8_LDA(dst, b, h) do { _Pragma("unroll") for (int m = 0; m < 4; ++m) _Pragma("unroll") for (int k = 0; k < 2; ++k) dst[m][k] = *(const LAS bf16x8*)(pA + PG8_SA(b, h) + m * 2048 + k * 1024); } while (0)
; #define PG8_LDB(dst, b, h) do { _Pragma("unroll") for (int n = 0; n < 2; ++n) _Pragma("unroll") for (int k = 0; k < 2; ++k) dst[n][k] = *(const LAS bf16x8*)(pB + (PG8_SB(b, h) - 4 * HTB) + n * 2048 + k * 1024); } while (0)
; #define PG8_MMA(ai, bj, At, Bt) do { __builtin_amdgcn_s_setprio(1); _Pragma("unroll") for (int m = 0; m < 4; ++m) _Pragma("unroll") for (int n = 0; n < 2; ++n) _Pragma("unroll") for (int k = 0; k < 2; ++k) \
;         acc[ai][bj][m][n] = __builtin_amdgcn_mfma_f32_16x16x32_bf16(Bt[n][k], At[m][k], acc[ai][bj][m][n], 0, 0, 0); __builtin_amdgcn_s_setprio(0); } while (0)
; #define PG8_WAIT_V(n) asm volatile("s_waitcnt vmcnt(" #n ")" ::: "memory")
; #define PG8_WAIT_L(n) asm volatile("s_waitcnt lgkmcnt(" #n ")" ::: "memory")
; #define PG8_BAR __builtin_amdgcn_s_barrier()
; #define PG8_SCHED __builtin_amdgcn_sched_barrier(0)
; template <class Desc, class Epi, bool ALIGN_EPI>
; __device__ __forceinline__ void gemm_phase(LAS unsigned char* lds, const Desc& D, const Epi& E, int G, int c) {
;     ...
;             PG8_WAIT_V(8); PG8_WAIT_L(0); PG8_BAR; PG8_MMA(1, 0, At, B0); PG8_MMA(1, 1, At, B1); PG8_BAR; PG8_SCHED;
;             PG8_LDB(B0, 1, 0); PG8_LDB(B1, 1, 1); PG8_SCHED; PG8_LDA(At, 1, 0); PG8_STAGE(PG8_SA(0, 1), a2 + hstepA, voffA);
;             PG8_WAIT_V(8); PG8_WAIT_L(0); PG8_BAR; PG8_MMA(0, 0, At, B0); PG8_MMA(0, 1, At, B1); PG8_BAR; PG8_SCHED;
	v_mfma_f32_16x16x32_bf16 v[64:67], v[144:147], v[180:183], v[64:67]
	v_mfma_f32_16x16x32_bf16 v[64:67], v[152:155], v[184:187], v[64:67]
	v_mfma_f32_16x16x32_bf16 v[52:55], v[144:147], v[188:191], v[52:55]
	v_mfma_f32_16x16x32_bf16 v[52:55], v[152:155], v[192:195], v[52:55]
	v_mfma_f32_16x16x32_bf16 v[36:39], v[144:147], v[196:199], v[36:39]
	v_mfma_f32_16x16x32_bf16 v[36:39], v[152:155], v[200:203], v[36:39]
	v_mfma_f32_16x16x32_bf16 v[20:23], v[144:147], v[204:207], v[20:23]
	v_mfma_f32_16x16x32_bf16 v[20:23], v[152:155], v[208:211], v[20:23]
	v_mfma_f32_16x16x32_bf16 v[60:63], v[156:159], v[180:183], v[60:63]
	v_mfma_f32_16x16x32_bf16 v[60:63], v[160:163], v[184:187], v[60:63]
	v_mfma_f32_16x16x32_bf16 v[44:47], v[156:159], v[188:191], v[44:47]
	v_mfma_f32_16x16x32_bf16 v[44:47], v[160:163], v[192:195], v[44:47]
	v_mfma_f32_16x16x32_bf16 v[28:31], v[156:159], v[196:199], v[28:31]
	v_mfma_f32_16x16x32_bf16 v[28:31], v[160:163], v[200:203], v[28:31]
	v_mfma_f32_16x16x32_bf16 v[12:15], v[156:159], v[204:207], v[12:15]
	v_mfma_f32_16x16x32_bf16 v[12:15], v[160:163], v[208:211], v[12:15]
	v_mfma_f32_16x16x32_bf16 v[56:59], v[164:167], v[180:183], v[56:59]
	v_mfma_f32_16x16x32_bf16 v[56:59], v[168:171], v[184:187], v[56:59]
	v_mfma_f32_16x16x32_bf16 v[40:43], v[164:167], v[188:191], v[40:43]
	v_mfma_f32_16x16x32_bf16 v[40:43], v[168:171], v[192:195], v[40:43]
	v_mfma_f32_16x16x32_bf16 v[24:27], v[164:167], v[196:199], v[24:27]
	v_mfma_f32_16x16x32_bf16 v[24:27], v[168:171], v[200:203], v[24:27]
	v_mfma_f32_16x16x32_bf16 v[8:11], v[164:167], v[204:207], v[8:11]
	v_mfma_f32_16x16x32_bf16 v[8:11], v[168:171], v[208:211], v[8:11]
	v_mfma_f32_16x16x32_bf16 v[48:51], v[172:175], v[180:183], v[48:51]
	v_mfma_f32_16x16x32_bf16 v[48:51], v[176:179], v[184:187], v[48:51]
	v_mfma_f32_16x16x32_bf16 v[32:35], v[172:175], v[188:191], v[32:35]
	v_mfma_f32_16x16x32_bf16 v[32:35], v[176:179], v[192:195], v[32:35]
	v_mfma_f32_16x16x32_bf16 v[16:19], v[172:175], v[196:199], v[16:19]
	v_mfma_f32_16x16x32_bf16 v[16:19], v[176:179], v[200:203], v[16:19]
	v_mfma_f32_16x16x32_bf16 v[4:7], v[172:175], v[204:207], v[4:7]
	v_mfma_f32_16x16x32_bf16 v[4:7], v[176:179], v[208:211], v[4:7]
	s_barrier
	ds_read_b128 v[144:147], v149 offset:32768
	ds_read_b128 v[152:155], v149 offset:33792
	ds_read_b128 v[156:159], v149 offset:34816
	ds_read_b128 v[160:163], v149 offset:35840
	ds_read_b128 v[164:167], v149 offset:49152
	ds_read_b128 v[168:171], v149 offset:50176
	ds_read_b128 v[172:175], v149 offset:51200
	ds_read_b128 v[176:179], v149 offset:52224
	s_add_u32 s18, s18, 0x80000
	s_addc_u32 s19, s19, 0
	s_mov_b32 m0, s27
	v_lshl_add_u64 v[220:221], s[18:19], 0, v[138:139]
	ds_read_b128 v[180:183], v148 offset:32768
	ds_read_b128 v[184:187], v148 offset:33792
	ds_read_b128 v[188:191], v148 offset:34816
	ds_read_b128 v[192:195], v148 offset:35840
	ds_read_b128 v[196:199], v148 offset:36864
	ds_read_b128 v[200:203], v148 offset:37888
	ds_read_b128 v[204:207], v148 offset:38912
	ds_read_b128 v[208:211], v148 offset:39936
	global_load_lds_dwordx4 v[220:221], off
	v_lshl_add_u64 v[220:221], s[18:19], 0, v[134:135]
	s_mov_b32 m0, s30
	s_nop 0
	global_load_lds_dwordx4 v[220:221], off
	s_waitcnt vmcnt(8)
	s_waitcnt lgkmcnt(0)
	s_barrier
	v_mfma_f32_16x16x32_bf16 v[128:131], v[144:147], v[180:183], v[128:131]
	v_mfma_f32_16x16x32_bf16 v[128:131], v[152:155], v[184:187], v[128:131]
	v_mfma_f32_16x16x32_bf16 v[116:119], v[144:147], v[188:191], v[116:119]
	v_mfma_f32_16x16x32_bf16 v[116:119], v[152:155], v[192:195], v[116:119]
	v_mfma_f32_16x16x32_bf16 v[100:103], v[144:147], v[196:199], v[100:103]
	v_mfma_f32_16x16x32_bf16 v[100:103], v[152:155], v[200:203], v[100:103]
	v_mfma_f32_16x16x32_bf16 v[84:87], v[144:147], v[204:207], v[84:87]
	v_mfma_f32_16x16x32_bf16 v[84:87], v[152:155], v[208:211], v[84:87]
	v_mfma_f32_16x16x32_bf16 v[124:127], v[156:159], v[180:183], v[124:127]
	v_mfma_f32_16x16x32_bf16 v[124:127], v[160:163], v[184:187], v[124:127]
	v_mfma_f32_16x16x32_bf16 v[108:111], v[156:159], v[188:191], v[108:111]
	v_mfma_f32_16x16x32_bf16 v[108:111], v[160:163], v[192:195], v[108:111]
	v_mfma_f32_16x16x32_bf16 v[92:95], v[156:159], v[196:199], v[92:95]
	v_mfma_f32_16x16x32_bf16 v[92:95], v[160:163], v[200:203], v[92:95]
	v_mfma_f32_16x16x32_bf16 v[76:79], v[156:159], v[204:207], v[76:79]
	v_mfma_f32_16x16x32_bf16 v[76:79], v[160:163], v[208:211], v[76:79]
	v_mfma_f32_16x16x32_bf16 v[120:123], v[164:167], v[180:183], v[120:123]
	v_mfma_f32_16x16x32_bf16 v[120:123], v[168:171], v[184:187], v[120:123]
	v_mfma_f32_16x16x32_bf16 v[104:107], v[164:167], v[188:191], v[104:107]
	v_mfma_f32_16x16x32_bf16 v[104:107], v[168:171], v[192:195], v[104:107]
	v_mfma_f32_16x16x32_bf16 v[88:91], v[164:167], v[196:199], v[88:91]
	v_mfma_f32_16x16x32_bf16 v[88:91], v[168:171], v[200:203], v[88:91]
	v_mfma_f32_16x16x32_bf16 v[72:75], v[164:167], v[204:207], v[72:75]
	v_mfma_f32_16x16x32_bf16 v[72:75], v[168:171], v[208:211], v[72:75]
	v_mfma_f32_16x16x32_bf16 v[112:115], v[172:175], v[180:183], v[112:115]
	v_mfma_f32_16x16x32_bf16 v[112:115], v[176:179], v[184:187], v[112:115]
	v_mfma_f32_16x16x32_bf16 v[96:99], v[172:175], v[188:191], v[96:99]
	v_mfma_f32_16x16x32_bf16 v[96:99], v[176:179], v[192:195], v[96:99]
	v_mfma_f32_16x16x32_bf16 v[80:83], v[172:175], v[196:199], v[80:83]
	v_mfma_f32_16x16x32_bf16 v[80:83], v[176:179], v[200:203], v[80:83]
	v_mfma_f32_16x16x32_bf16 v[68:71], v[172:175], v[204:207], v[68:71]
	v_mfma_f32_16x16x32_bf16 v[68:71], v[176:179], v[208:211], v[68:71]
	s_barrier
; #define PG8_STAGE(bufoff, gbase, voff) do { _Pragma("unroll") for (int _i = 0; _i < 2; ++_i) \
;         __builtin_amdgcn_global_load_lds((const unsigned*)((const char*)(gbase) + (voff)[_i]), (LAS unsigned*)(lds + (bufoff) + ldsw + _i * 8192), 16, 0, 0); } while (0)
; #define PG8_LDA(dst, b, h) do { _Pragma("unroll") for (int m = 0; m < 4; ++m) _Pragma("unroll") for (int k = 0; k < 2; ++k) dst[m][k] = *(const LAS bf16x8*)(pA + PG8_SA(b, h) + m * 2048 + k * 1024); } while (0)
; #define PG8_MMA(ai, bj, At, Bt) do { __builtin_amdgcn_s_setprio(1); _Pragma("unroll") for (int m = 0; m < 4; ++m) _Pragma("unroll") for (int n = 0; n < 2; ++n) _Pragma("unroll") for (int k = 0; k < 2; ++k) \
;         acc[ai][bj][m][n] = __builtin_amdgcn_mfma_f32_16x16x32_bf16(Bt[n][k], At[m][k], acc[ai][bj][m][n], 0, 0, 0); __builtin_amdgcn_s_setprio(0); } while (0)
; #define PG8_WAIT_V(n) asm volatile("s_waitcnt vmcnt(" #n ")" ::: "memory")
; #define PG8_WAIT_L(n) asm volatile("s_waitcnt lgkmcnt(" #n ")" ::: "memory")
; #define PG8_BAR __builtin_amdgcn_s_barrier()
; #define PG8_SCHED __builtin_amdgcn_sched_barrier(0)
; template <class Desc, class Epi, bool ALIGN_EPI>
; __device__ __forceinline__ void gemm_phase(LAS unsigned char* lds, const Desc& D, const Epi& E, int G, int c) {
;     ...
;             PG8_WAIT_V(8); PG8_WAIT_L(0); PG8_BAR; PG8_MMA(0, 0, At, B0); PG8_MMA(0, 1, At, B1); PG8_BAR; PG8_SCHED;
;             PG8_LDA(At, 1, 1); PG8_STAGE(PG8_SB(1, 0), b3, voffB); PG8_STAGE(PG8_SB(1, 1), b3 + hstepB, voffB); PG8_STAGE(PG8_SA(1, 0), a3, voffA);
;             PG8_WAIT_V(8); PG8_WAIT_L(0); PG8_BAR; PG8_MMA(1, 0, At, B0); PG8_MMA(1, 1, At, B1); PG8_BAR; PG8_SCHED;
;         }
;         if constexpr (ALIGN_EPI) { if (wr == 0) PG8_BAR; }
	s_mov_b32 m0, s31
	v_lshl_add_u64 v[212:213], v[212:213], 0, s[76:77]
	s_add_u32 s16, s16, 0x20080
	ds_read_b128 v[180:183], v148 offset:49152
	ds_read_b128 v[184:187], v148 offset:50176
	ds_read_b128 v[188:191], v148 offset:51200
	ds_read_b128 v[192:195], v148 offset:52224
	ds_read_b128 v[196:199], v148 offset:53248
	ds_read_b128 v[200:203], v148 offset:54272
	ds_read_b128 v[204:207], v148 offset:55296
	ds_read_b128 v[208:211], v148 offset:56320
	global_load_lds_dwordx4 v[212:213], off
	v_lshl_add_u64 v[212:213], v[214:215], 0, s[76:77]
	s_mov_b32 m0, s33
	s_addc_u32 s17, s17, 0
	global_load_lds_dwordx4 v[212:213], off
	v_lshl_add_u64 v[212:213], s[16:17], 0, v[136:137]
	s_mov_b32 m0, s38
	s_nop 0
	global_load_lds_dwordx4 v[212:213], off
	v_lshl_add_u64 v[212:213], s[16:17], 0, v[132:133]
	s_mov_b32 m0, s39
	s_nop 0
	global_load_lds_dwordx4 v[212:213], off
	v_lshl_add_u64 v[212:213], v[216:217], 0, s[76:77]
	s_mov_b32 m0, s34
	s_nop 0
	global_load_lds_dwordx4 v[212:213], off
	v_lshl_add_u64 v[212:213], v[218:219], 0, s[76:77]
	s_mov_b32 m0, s35
	s_nop 0
	global_load_lds_dwordx4 v[212:213], off
	s_waitcnt vmcnt(8)
	s_waitcnt lgkmcnt(0)
	s_barrier
	v_mfma_f32_16x16x32_bf16 v[64:67], v[144:147], v[180:183], v[64:67]
	v_mfma_f32_16x16x32_bf16 v[64:67], v[152:155], v[184:187], v[64:67]
	v_mfma_f32_16x16x32_bf16 v[52:55], v[144:147], v[188:191], v[52:55]
	v_mfma_f32_16x16x32_bf16 v[52:55], v[152:155], v[192:195], v[52:55]
	v_mfma_f32_16x16x32_bf16 v[36:39], v[144:147], v[196:199], v[36:39]
	v_mfma_f32_16x16x32_bf16 v[36:39], v[152:155], v[200:203], v[36:39]
	v_mfma_f32_16x16x32_bf16 v[20:23], v[144:147], v[204:207], v[20:23]
	v_mfma_f32_16x16x32_bf16 v[20:23], v[152:155], v[208:211], v[20:23]
	v_mfma_f32_16x16x32_bf16 v[60:63], v[156:159], v[180:183], v[60:63]
	v_mfma_f32_16x16x32_bf16 v[60:63], v[160:163], v[184:187], v[60:63]
	v_mfma_f32_16x16x32_bf16 v[44:47], v[156:159], v[188:191], v[44:47]
	v_mfma_f32_16x16x32_bf16 v[44:47], v[160:163], v[192:195], v[44:47]
	v_mfma_f32_16x16x32_bf16 v[28:31], v[156:159], v[196:199], v[28:31]
	v_mfma_f32_16x16x32_bf16 v[28:31], v[160:163], v[200:203], v[28:31]
	v_mfma_f32_16x16x32_bf16 v[12:15], v[156:159], v[204:207], v[12:15]
	v_mfma_f32_16x16x32_bf16 v[12:15], v[160:163], v[208:211], v[12:15]
	v_mfma_f32_16x16x32_bf16 v[56:59], v[164:167], v[180:183], v[56:59]
	v_mfma_f32_16x16x32_bf16 v[56:59], v[168:171], v[184:187], v[56:59]
	v_mfma_f32_16x16x32_bf16 v[40:43], v[164:167], v[188:191], v[40:43]
	v_mfma_f32_16x16x32_bf16 v[40:43], v[168:171], v[192:195], v[40:43]
	v_mfma_f32_16x16x32_bf16 v[24:27], v[164:167], v[196:199], v[24:27]
	v_mfma_f32_16x16x32_bf16 v[24:27], v[168:171], v[200:203], v[24:27]
	v_mfma_f32_16x16x32_bf16 v[8:11], v[164:167], v[204:207], v[8:11]
	v_mfma_f32_16x16x32_bf16 v[8:11], v[168:171], v[208:211], v[8:11]
	v_mfma_f32_16x16x32_bf16 v[48:51], v[172:175], v[180:183], v[48:51]
	v_mfma_f32_16x16x32_bf16 v[48:51], v[176:179], v[184:187], v[48:51]
	v_mfma_f32_16x16x32_bf16 v[32:35], v[172:175], v[188:191], v[32:35]
	v_mfma_f32_16x16x32_bf16 v[32:35], v[176:179], v[192:195], v[32:35]
	v_mfma_f32_16x16x32_bf16 v[16:19], v[172:175], v[196:199], v[16:19]
	v_mfma_f32_16x16x32_bf16 v[16:19], v[176:179], v[200:203], v[16:19]
	v_mfma_f32_16x16x32_bf16 v[4:7], v[172:175], v[204:207], v[4:7]
	v_mfma_f32_16x16x32_bf16 v[4:7], v[176:179], v[208:211], v[4:7]
	s_barrier
	s_add_i32 s46, s46, 2
	s_add_u32 s12, s12, 0x100
	s_addc_u32 s13, s13, 0
	s_add_u32 s7, s7, 0x100
	s_addc_u32 s45, s45, 0
	s_cmp_gt_u32 s46, 5
	s_cbranch_scc0 .LBB0_603
	v_readlane_b32 s46, v255, 36
	s_and_b64 vcc, exec, s[4:5]
	v_readlane_b32 s47, v255, 37
	s_cbranch_vccz .LBB0_606
	s_barrier

;     __device__ __forceinline__ int nt(const Unit& u) const { return (u.pn >> 1) < 2 ? 22 : 20; }
; #define PG8_STAGE(bufoff, gbase, voff) do { _Pragma("unroll") for (int _i = 0; _i < 2; ++_i) \
;         __builtin_amdgcn_global_load_lds((const unsigned*)((const char*)(gbase) + (voff)[_i]), (LAS unsigned*)(lds + (bufoff) + ldsw + _i * 8192), 16, 0, 0); } while (0)
; #define PG8_LDA(dst, b, h) do { _Pragma("unroll") for (int m = 0; m < 4; ++m) _Pragma("unroll") for (int k = 0; k < 2; ++k) dst[m][k] = *(const LAS bf16x8*)(pA + PG8_SA(b, h) + m * 2048 + k * 1024); } while (0)
; #define PG8_LDB(dst, b, h) do { _Pragma("unroll") for (int n = 0; n < 2; ++n) _Pragma("unroll") for (int k = 0; k < 2; ++k) dst[n][k] = *(const LAS bf16x8*)(pB + (PG8_SB(b, h) - 4 * HTB) + n * 2048 + k * 1024); } while (0)
; #define PG8_MMA(ai, bj, At, Bt) do { __builtin_amdgcn_s_setprio(1); _Pragma("unroll") for (int m = 0; m < 4; ++m) _Pragma("unroll") for (int n = 0; n < 2; ++n) _Pragma("unroll") for (int k = 0; k < 2; ++k) \
;         acc[ai][bj][m][n] = __builtin_amdgcn_mfma_f32_16x16x32_bf16(Bt[n][k], At[m][k], acc[ai][bj][m][n], 0, 0, 0); __builtin_amdgcn_s_setprio(0); } while (0)
; #define PG8_WAIT_V(n) asm volatile("s_waitcnt vmcnt(" #n ")" ::: "memory")
; #define PG8_BAR __builtin_amdgcn_s_barrier()
; template <class Desc, class Epi, bool ALIGN_EPI>
; __device__ __forceinline__ void gemm_phase(LAS unsigned char* lds, const Desc& D, const Epi& E, int G, int c) {
;     ...
;         for (int t = 0; t < nt; t += 2) {
;             const bool last = (t == nt - 2);
;             if (last && has_next) PG8_AWAIT(nxt);
;             const char* a1 = cA + (size_t)(t + 1) * kstep;
;             const char* a2 = last ? nA : cA + (size_t)(t + 2) * kstep; const char* b2 = last ? nB : cB + (size_t)(t + 2) * kstep;
;             const char* a3 = a2 + kstep; const char* b3 = b2 + kstep;
;             PG8_LDB(B0, 0, 0); PG8_LDB(B1, 0, 1); PG8_SCHED; PG8_LDA(At, 0, 0); PG8_STAGE(PG8_SA(1, 1), a1 + hstepA, voffA);
;             PG8_WAIT_V(8); PG8_WAIT_L(0); PG8_BAR; PG8_MMA(0, 0, At, B0); PG8_MMA(0, 1, At, B1); PG8_BAR; PG8_SCHED;
;             PG8_LDA(At, 0, 1); PG8_STAGE(PG8_SB(0, 0), b2, voffB); PG8_STAGE(PG8_SB(0, 1), b2 + hstepB, voffB); PG8_STAGE(PG8_SA(0, 0), a2, voffA);
;             PG8_WAIT_V(8); PG8_WAIT_L(0); PG8_BAR; PG8_MMA(1, 0, At, B0); PG8_MMA(1, 1, At, B1); PG8_BAR; PG8_SCHED;
.LBB0_1164:
	s_waitcnt lgkmcnt(0)
	ds_read_b128 v[132:135], v229
	ds_read_b128 v[136:139], v229 offset:1024
	ds_read_b128 v[140:143], v229 offset:2048
	ds_read_b128 v[144:147], v229 offset:3072
	ds_read_b128 v[148:151], v229 offset:16384
	ds_read_b128 v[152:155], v229 offset:17408
	ds_read_b128 v[156:159], v229 offset:18432
	ds_read_b128 v[160:163], v229 offset:19456
	s_add_i32 s20, s14, 2
	s_add_u32 s16, s12, 0xfff00080
	s_addc_u32 s17, s13, -1
	s_cmp_eq_u32 s1, s14
	s_cselect_b32 s19, s39, s17
	s_cselect_b32 s18, s38, s16
	s_cselect_b32 s17, s41, s11
	s_cselect_b32 s16, s40, s3
	v_lshl_add_u64 v[208:209], s[12:13], 0, v[204:205]
	s_add_i32 m0, s35, 0xc000
	ds_read_b128 v[164:167], v228
	ds_read_b128 v[168:171], v228 offset:1024
	ds_read_b128 v[172:175], v228 offset:2048
	ds_read_b128 v[176:179], v228 offset:3072
	ds_read_b128 v[180:183], v228 offset:4096
	ds_read_b128 v[184:187], v228 offset:5120
	ds_read_b128 v[188:191], v228 offset:6144
	ds_read_b128 v[192:195], v228 offset:7168
	global_load_lds_dwordx4 v[208:209], off
	v_lshl_add_u64 v[208:209], s[12:13], 0, v[206:207]
	s_add_i32 m0, s35, 0xe000
	s_nop 0
	global_load_lds_dwordx4 v[208:209], off
	s_waitcnt vmcnt(8)
	s_waitcnt lgkmcnt(0)
	s_barrier
	v_mfma_f32_16x16x32_bf16 v[128:131], v[132:135], v[164:167], v[128:131]
	v_mfma_f32_16x16x32_bf16 v[128:131], v[136:139], v[168:171], v[128:131]
	v_mfma_f32_16x16x32_bf16 v[120:123], v[132:135], v[172:175], v[120:123]
	v_mfma_f32_16x16x32_bf16 v[120:123], v[136:139], v[176:179], v[120:123]
	v_mfma_f32_16x16x32_bf16 v[112:115], v[132:135], v[180:183], v[112:115]
	v_mfma_f32_16x16x32_bf16 v[112:115], v[136:139], v[184:187], v[112:115]
	v_mfma_f32_16x16x32_bf16 v[104:107], v[132:135], v[188:191], v[104:107]
	v_mfma_f32_16x16x32_bf16 v[104:107], v[136:139], v[192:195], v[104:107]
	v_mfma_f32_16x16x32_bf16 v[124:127], v[140:143], v[164:167], v[124:127]
	v_mfma_f32_16x16x32_bf16 v[124:127], v[144:147], v[168:171], v[124:127]
	v_mfma_f32_16x16x32_bf16 v[116:119], v[140:143], v[172:175], v[116:119]
	v_mfma_f32_16x16x32_bf16 v[116:119], v[144:147], v[176:179], v[116:119]
	v_mfma_f32_16x16x32_bf16 v[108:111], v[140:143], v[180:183], v[108:111]
	v_mfma_f32_16x16x32_bf16 v[108:111], v[144:147], v[184:187], v[108:111]
	v_mfma_f32_16x16x32_bf16 v[100:103], v[140:143], v[188:191], v[100:103]
	v_mfma_f32_16x16x32_bf16 v[100:103], v[144:147], v[192:195], v[100:103]
	v_mfma_f32_16x16x32_bf16 v[96:99], v[148:151], v[164:167], v[96:99]
	v_mfma_f32_16x16x32_bf16 v[96:99], v[152:155], v[168:171], v[96:99]
	v_mfma_f32_16x16x32_bf16 v[88:91], v[148:151], v[172:175], v[88:91]
	v_mfma_f32_16x16x32_bf16 v[88:91], v[152:155], v[176:179], v[88:91]
	v_mfma_f32_16x16x32_bf16 v[64:67], v[148:151], v[180:183], v[64:67]
	v_mfma_f32_16x16x32_bf16 v[64:67], v[152:155], v[184:187], v[64:67]
	v_mfma_f32_16x16x32_bf16 v[32:35], v[148:151], v[188:191], v[32:35]
	v_mfma_f32_16x16x32_bf16 v[32:35], v[152:155], v[192:195], v[32:35]
	v_mfma_f32_16x16x32_bf16 v[92:95], v[156:159], v[164:167], v[92:95]
	v_mfma_f32_16x16x32_bf16 v[92:95], v[160:163], v[168:171], v[92:95]
	v_mfma_f32_16x16x32_bf16 v[80:83], v[156:159], v[172:175], v[80:83]
	v_mfma_f32_16x16x32_bf16 v[80:83], v[160:163], v[176:179], v[80:83]
	v_mfma_f32_16x16x32_bf16 v[52:55], v[156:159], v[180:183], v[52:55]
	v_mfma_f32_16x16x32_bf16 v[52:55], v[160:163], v[184:187], v[52:55]
	v_mfma_f32_16x16x32_bf16 v[20:23], v[156:159], v[188:191], v[20:23]
	v_mfma_f32_16x16x32_bf16 v[20:23], v[160:163], v[192:195], v[20:23]
	s_barrier
	s_mov_b32 m0, s44
	v_lshl_add_u64 v[208:209], s[16:17], 0, v[198:199]
	s_add_u32 s62, s16, 0x100000
	ds_read_b128 v[164:167], v228 offset:16384
	ds_read_b128 v[168:171], v228 offset:17408
	ds_read_b128 v[172:175], v228 offset:18432
	ds_read_b128 v[176:179], v228 offset:19456
	ds_read_b128 v[180:183], v228 offset:20480
	ds_read_b128 v[184:187], v228 offset:21504
	ds_read_b128 v[188:191], v228 offset:22528
	ds_read_b128 v[192:195], v228 offset:23552
	global_load_lds_dwordx4 v[208:209], off
	v_lshl_add_u64 v[210:211], s[16:17], 0, v[202:203]
	s_mov_b32 m0, s45
	s_addc_u32 s63, s17, 0
	global_load_lds_dwordx4 v[210:211], off
	v_lshl_add_u64 v[212:213], s[62:63], 0, v[198:199]
	s_mov_b32 m0, s46
	v_lshl_add_u64 v[214:215], s[18:19], 0, v[200:201]
	global_load_lds_dwordx4 v[212:213], off
	v_lshl_add_u64 v[212:213], s[62:63], 0, v[202:203]
	s_mov_b32 m0, s47
	s_nop 0
	global_load_lds_dwordx4 v[212:213], off
	v_lshl_add_u64 v[212:213], s[18:19], 0, v[196:197]
	s_mov_b32 m0, s35
	s_nop 0
	global_load_lds_dwordx4 v[212:213], off
	s_mov_b32 m0, s48
	s_nop 0
	global_load_lds_dwordx4 v[214:215], off
	s_waitcnt vmcnt(8)
	s_waitcnt lgkmcnt(0)
	s_barrier
; #define PG8_STAGE(bufoff, gbase, voff) do { _Pragma("unroll") for (int _i = 0; _i < 2; ++_i) \
;         __builtin_amdgcn_global_load_lds((const unsigned*)((const char*)(gbase) + (voff)[_i]), (LAS unsigned*)(lds + (bufoff) + ldsw + _i * 8192), 16, 0, 0); } while (0)
; #define PG8_LDA(dst, b, h) do { _Pragma("unroll") for (int m = 0; m < 4; ++m) _Pragma("unroll") for (int k = 0; k < 2; ++k) dst[m][k] = *(const LAS bf16x8*)(pA + PG8_SA(b, h) + m * 2048 + k * 1024); } while (0)
; #define PG8_LDB(dst, b, h) do { _Pragma("unroll") for (int n = 0; n < 2; ++n) _Pragma("unroll") for (int k = 0; k < 2; ++k) dst[n][k] = *(const LAS bf16x8*)(pB + (PG8_SB(b, h) - 4 * HTB) + n * 2048 + k * 1024); } while (0)
; #define PG8_MMA(ai, bj, At, Bt) do { __builtin_amdgcn_s_setprio(1); _Pragma("unroll") for (int m = 0; m < 4; ++m) _Pragma("unroll") for (int n = 0; n < 2; ++n) _Pragma("unroll") for (int k = 0; k < 2; ++k) \
;         acc[ai][bj][m][n] = __builtin_amdgcn_mfma_f32_16x16x32_bf16(Bt[n][k], At[m][k], acc[ai][bj][m][n], 0, 0, 0); __builtin_amdgcn_s_setprio(0); } while (0)
; #define PG8_WAIT_V(n) asm volatile("s_waitcnt vmcnt(" #n ")" ::: "memory")
; #define PG8_WAIT_L(n) asm volatile("s_waitcnt lgkmcnt(" #n ")" ::: "memory")
; #define PG8_BAR __builtin_amdgcn_s_barrier()
; #define PG8_SCHED __builtin_amdgcn_sched_barrier(0)
; template <class Desc, class Epi, bool ALIGN_EPI>
; __device__ __forceinline__ void gemm_phase(LAS unsigned char* lds, const Desc& D, const Epi& E, int G, int c) {
;     ...
;             PG8_WAIT_V(8); PG8_WAIT_L(0); PG8_BAR; PG8_MMA(1, 0, At, B0); PG8_MMA(1, 1, At, B1); PG8_BAR; PG8_SCHED;
;             PG8_LDB(B0, 1, 0); PG8_LDB(B1, 1, 1); PG8_SCHED; PG8_LDA(At, 1, 0); PG8_STAGE(PG8_SA(0, 1), a2 + hstepA, voffA);
;             PG8_WAIT_V(8); PG8_WAIT_L(0); PG8_BAR; PG8_MMA(0, 0, At, B0); PG8_MMA(0, 1, At, B1); PG8_BAR; PG8_SCHED;
	v_mfma_f32_16x16x32_bf16 v[84:87], v[132:135], v[164:167], v[84:87]
	v_mfma_f32_16x16x32_bf16 v[84:87], v[136:139], v[168:171], v[84:87]
	v_mfma_f32_16x16x32_bf16 v[72:75], v[132:135], v[172:175], v[72:75]
	v_mfma_f32_16x16x32_bf16 v[72:75], v[136:139], v[176:179], v[72:75]
	v_mfma_f32_16x16x32_bf16 v[60:63], v[132:135], v[180:183], v[60:63]
	v_mfma_f32_16x16x32_bf16 v[60:63], v[136:139], v[184:187], v[60:63]
	v_mfma_f32_16x16x32_bf16 v[48:51], v[132:135], v[188:191], v[48:51]
	v_mfma_f32_16x16x32_bf16 v[48:51], v[136:139], v[192:195], v[48:51]
	v_mfma_f32_16x16x32_bf16 v[76:79], v[140:143], v[164:167], v[76:79]
	v_mfma_f32_16x16x32_bf16 v[76:79], v[144:147], v[168:171], v[76:79]
	v_mfma_f32_16x16x32_bf16 v[68:71], v[140:143], v[172:175], v[68:71]
	v_mfma_f32_16x16x32_bf16 v[68:71], v[144:147], v[176:179], v[68:71]
	v_mfma_f32_16x16x32_bf16 v[56:59], v[140:143], v[180:183], v[56:59]
	v_mfma_f32_16x16x32_bf16 v[56:59], v[144:147], v[184:187], v[56:59]
	v_mfma_f32_16x16x32_bf16 v[44:47], v[140:143], v[188:191], v[44:47]
	v_mfma_f32_16x16x32_bf16 v[44:47], v[144:147], v[192:195], v[44:47]
	v_mfma_f32_16x16x32_bf16 v[40:43], v[148:151], v[164:167], v[40:43]
	v_mfma_f32_16x16x32_bf16 v[40:43], v[152:155], v[168:171], v[40:43]
	v_mfma_f32_16x16x32_bf16 v[28:31], v[148:151], v[172:175], v[28:31]
	v_mfma_f32_16x16x32_bf16 v[28:31], v[152:155], v[176:179], v[28:31]
	v_mfma_f32_16x16x32_bf16 v[16:19], v[148:151], v[180:183], v[16:19]
	v_mfma_f32_16x16x32_bf16 v[16:19], v[152:155], v[184:187], v[16:19]
	v_mfma_f32_16x16x32_bf16 v[8:11], v[148:151], v[188:191], v[8:11]
	v_mfma_f32_16x16x32_bf16 v[8:11], v[152:155], v[192:195], v[8:11]
	v_mfma_f32_16x16x32_bf16 v[36:39], v[156:159], v[164:167], v[36:39]
	v_mfma_f32_16x16x32_bf16 v[36:39], v[160:163], v[168:171], v[36:39]
	v_mfma_f32_16x16x32_bf16 v[24:27], v[156:159], v[172:175], v[24:27]
	v_mfma_f32_16x16x32_bf16 v[24:27], v[160:163], v[176:179], v[24:27]
	v_mfma_f32_16x16x32_bf16 v[12:15], v[156:159], v[180:183], v[12:15]
	v_mfma_f32_16x16x32_bf16 v[12:15], v[160:163], v[184:187], v[12:15]
	v_mfma_f32_16x16x32_bf16 v[4:7], v[156:159], v[188:191], v[4:7]
	v_mfma_f32_16x16x32_bf16 v[4:7], v[160:163], v[192:195], v[4:7]
	s_barrier
	ds_read_b128 v[132:135], v229 offset:32768
	ds_read_b128 v[136:139], v229 offset:33792
	ds_read_b128 v[140:143], v229 offset:34816
	ds_read_b128 v[144:147], v229 offset:35840
	ds_read_b128 v[148:151], v229 offset:49152
	ds_read_b128 v[152:155], v229 offset:50176
	ds_read_b128 v[156:159], v229 offset:51200
	ds_read_b128 v[160:163], v229 offset:52224
	s_add_u32 s18, s18, 0x100000
	s_addc_u32 s19, s19, 0
	s_mov_b32 m0, s49
	v_lshl_add_u64 v[216:217], s[18:19], 0, v[196:197]
	ds_read_b128 v[164:167], v228 offset:32768
	ds_read_b128 v[168:171], v228 offset:33792
	ds_read_b128 v[172:175], v228 offset:34816
	ds_read_b128 v[176:179], v228 offset:35840
	ds_read_b128 v[180:183], v228 offset:36864
	ds_read_b128 v[184:187], v228 offset:37888
	ds_read_b128 v[188:191], v228 offset:38912
	ds_read_b128 v[192:195], v228 offset:39936
	global_load_lds_dwordx4 v[216:217], off
	v_lshl_add_u64 v[216:217], s[18:19], 0, v[200:201]
	s_mov_b32 m0, s50
	s_nop 0
	global_load_lds_dwordx4 v[216:217], off
	s_waitcnt vmcnt(8)
	s_waitcnt lgkmcnt(0)
	s_barrier
	v_mfma_f32_16x16x32_bf16 v[128:131], v[132:135], v[164:167], v[128:131]
	v_mfma_f32_16x16x32_bf16 v[128:131], v[136:139], v[168:171], v[128:131]
	v_mfma_f32_16x16x32_bf16 v[120:123], v[132:135], v[172:175], v[120:123]
	v_mfma_f32_16x16x32_bf16 v[120:123], v[136:139], v[176:179], v[120:123]
	v_mfma_f32_16x16x32_bf16 v[112:115], v[132:135], v[180:183], v[112:115]
	v_mfma_f32_16x16x32_bf16 v[112:115], v[136:139], v[184:187], v[112:115]
	v_mfma_f32_16x16x32_bf16 v[104:107], v[132:135], v[188:191], v[104:107]
	v_mfma_f32_16x16x32_bf16 v[104:107], v[136:139], v[192:195], v[104:107]
	v_mfma_f32_16x16x32_bf16 v[124:127], v[140:143], v[164:167], v[124:127]
	v_mfma_f32_16x16x32_bf16 v[124:127], v[144:147], v[168:171], v[124:127]
	v_mfma_f32_16x16x32_bf16 v[116:119], v[140:143], v[172:175], v[116:119]
	v_mfma_f32_16x16x32_bf16 v[116:119], v[144:147], v[176:179], v[116:119]
	v_mfma_f32_16x16x32_bf16 v[108:111], v[140:143], v[180:183], v[108:111]
	v_mfma_f32_16x16x32_bf16 v[108:111], v[144:147], v[184:187], v[108:111]
	v_mfma_f32_16x16x32_bf16 v[100:103], v[140:143], v[188:191], v[100:103]
	v_mfma_f32_16x16x32_bf16 v[100:103], v[144:147], v[192:195], v[100:103]
	v_mfma_f32_16x16x32_bf16 v[96:99], v[148:151], v[164:167], v[96:99]
	v_mfma_f32_16x16x32_bf16 v[96:99], v[152:155], v[168:171], v[96:99]
	v_mfma_f32_16x16x32_bf16 v[88:91], v[148:151], v[172:175], v[88:91]
	v_mfma_f32_16x16x32_bf16 v[88:91], v[152:155], v[176:179], v[88:91]
	v_mfma_f32_16x16x32_bf16 v[64:67], v[148:151], v[180:183], v[64:67]
	v_mfma_f32_16x16x32_bf16 v[64:67], v[152:155], v[184:187], v[64:67]
	v_mfma_f32_16x16x32_bf16 v[32:35], v[148:151], v[188:191], v[32:35]
	v_mfma_f32_16x16x32_bf16 v[32:35], v[152:155], v[192:195], v[32:35]
	v_mfma_f32_16x16x32_bf16 v[92:95], v[156:159], v[164:167], v[92:95]
	v_mfma_f32_16x16x32_bf16 v[92:95], v[160:163], v[168:171], v[92:95]
	v_mfma_f32_16x16x32_bf16 v[80:83], v[156:159], v[172:175], v[80:83]
	v_mfma_f32_16x16x32_bf16 v[80:83], v[160:163], v[176:179], v[80:83]
	v_mfma_f32_16x16x32_bf16 v[52:55], v[156:159], v[180:183], v[52:55]
	v_mfma_f32_16x16x32_bf16 v[52:55], v[160:163], v[184:187], v[52:55]
	v_mfma_f32_16x16x32_bf16 v[20:23], v[156:159], v[188:191], v[20:23]
	v_mfma_f32_16x16x32_bf16 v[20:23], v[160:163], v[192:195], v[20:23]
	s_barrier
; #define PG8_STAGE(bufoff, gbase, voff) do { _Pragma("unroll") for (int _i = 0; _i < 2; ++_i) \
;         __builtin_amdgcn_global_load_lds((const unsigned*)((const char*)(gbase) + (voff)[_i]), (LAS unsigned*)(lds + (bufoff) + ldsw + _i * 8192), 16, 0, 0); } while (0)
; #define PG8_LDA(dst, b, h) do { _Pragma("unroll") for (int m = 0; m < 4; ++m) _Pragma("unroll") for (int k = 0; k < 2; ++k) dst[m][k] = *(const LAS bf16x8*)(pA + PG8_SA(b, h) + m * 2048 + k * 1024); } while (0)
; #define PG8_MMA(ai, bj, At, Bt) do { __builtin_amdgcn_s_setprio(1); _Pragma("unroll") for (int m = 0; m < 4; ++m) _Pragma("unroll") for (int n = 0; n < 2; ++n) _Pragma("unroll") for (int k = 0; k < 2; ++k) \
;         acc[ai][bj][m][n] = __builtin_amdgcn_mfma_f32_16x16x32_bf16(Bt[n][k], At[m][k], acc[ai][bj][m][n], 0, 0, 0); __builtin_amdgcn_s_setprio(0); } while (0)
; #define PG8_WAIT_V(n) asm volatile("s_waitcnt vmcnt(" #n ")" ::: "memory")
; #define PG8_WAIT_L(n) asm volatile("s_waitcnt lgkmcnt(" #n ")" ::: "memory")
; #define PG8_BAR __builtin_amdgcn_s_barrier()
; #define PG8_SCHED __builtin_amdgcn_sched_barrier(0)
; template <class Desc, class Epi, bool ALIGN_EPI>
; __device__ __forceinline__ void gemm_phase(LAS unsigned char* lds, const Desc& D, const Epi& E, int G, int c) {
;     ...
;             PG8_WAIT_V(8); PG8_WAIT_L(0); PG8_BAR; PG8_MMA(0, 0, At, B0); PG8_MMA(0, 1, At, B1); PG8_BAR; PG8_SCHED;
;             PG8_LDA(At, 1, 1); PG8_STAGE(PG8_SB(1, 0), b3, voffB); PG8_STAGE(PG8_SB(1, 1), b3 + hstepB, voffB); PG8_STAGE(PG8_SA(1, 0), a3, voffA);
;             PG8_WAIT_V(8); PG8_WAIT_L(0); PG8_BAR; PG8_MMA(1, 0, At, B0); PG8_MMA(1, 1, At, B1); PG8_BAR; PG8_SCHED;
;         }
;         if constexpr (ALIGN_EPI) { if (wr == 0) PG8_BAR; }
	s_mov_b32 m0, s52
	v_lshl_add_u64 v[208:209], v[208:209], 0, s[76:77]
	s_add_u32 s16, s16, 0x100080
	ds_read_b128 v[164:167], v228 offset:49152
	ds_read_b128 v[168:171], v228 offset:50176
	ds_read_b128 v[172:175], v228 offset:51200
	ds_read_b128 v[176:179], v228 offset:52224
	ds_read_b128 v[180:183], v228 offset:53248
	ds_read_b128 v[184:187], v228 offset:54272
	ds_read_b128 v[188:191], v228 offset:55296
	ds_read_b128 v[192:195], v228 offset:56320
	global_load_lds_dwordx4 v[208:209], off
	v_lshl_add_u64 v[208:209], v[210:211], 0, s[76:77]
	s_mov_b32 m0, s53
	s_addc_u32 s17, s17, 0
	global_load_lds_dwordx4 v[208:209], off
	v_lshl_add_u64 v[208:209], s[16:17], 0, v[198:199]
	s_mov_b32 m0, s56
	s_nop 0
	global_load_lds_dwordx4 v[208:209], off
	v_lshl_add_u64 v[208:209], s[16:17], 0, v[202:203]
	s_mov_b32 m0, s57
	s_nop 0
	global_load_lds_dwordx4 v[208:209], off
	v_lshl_add_u64 v[208:209], v[212:213], 0, s[76:77]
	s_mov_b32 m0, s54
	s_nop 0
	global_load_lds_dwordx4 v[208:209], off
	v_lshl_add_u64 v[208:209], v[214:215], 0, s[76:77]
	s_mov_b32 m0, s55
	s_nop 0
	global_load_lds_dwordx4 v[208:209], off
	s_waitcnt vmcnt(8)
	s_waitcnt lgkmcnt(0)
	s_barrier
	v_mfma_f32_16x16x32_bf16 v[84:87], v[132:135], v[164:167], v[84:87]
	v_mfma_f32_16x16x32_bf16 v[84:87], v[136:139], v[168:171], v[84:87]
	v_mfma_f32_16x16x32_bf16 v[72:75], v[132:135], v[172:175], v[72:75]
	v_mfma_f32_16x16x32_bf16 v[72:75], v[136:139], v[176:179], v[72:75]
	v_mfma_f32_16x16x32_bf16 v[60:63], v[132:135], v[180:183], v[60:63]
	v_mfma_f32_16x16x32_bf16 v[60:63], v[136:139], v[184:187], v[60:63]
	v_mfma_f32_16x16x32_bf16 v[48:51], v[132:135], v[188:191], v[48:51]
	v_mfma_f32_16x16x32_bf16 v[48:51], v[136:139], v[192:195], v[48:51]
	v_mfma_f32_16x16x32_bf16 v[76:79], v[140:143], v[164:167], v[76:79]
	v_mfma_f32_16x16x32_bf16 v[76:79], v[144:147], v[168:171], v[76:79]
	v_mfma_f32_16x16x32_bf16 v[68:71], v[140:143], v[172:175], v[68:71]
	v_mfma_f32_16x16x32_bf16 v[68:71], v[144:147], v[176:179], v[68:71]
	v_mfma_f32_16x16x32_bf16 v[56:59], v[140:143], v[180:183], v[56:59]
	v_mfma_f32_16x16x32_bf16 v[56:59], v[144:147], v[184:187], v[56:59]
	v_mfma_f32_16x16x32_bf16 v[44:47], v[140:143], v[188:191], v[44:47]
	v_mfma_f32_16x16x32_bf16 v[44:47], v[144:147], v[192:195], v[44:47]
	v_mfma_f32_16x16x32_bf16 v[40:43], v[148:151], v[164:167], v[40:43]
	v_mfma_f32_16x16x32_bf16 v[40:43], v[152:155], v[168:171], v[40:43]
	v_mfma_f32_16x16x32_bf16 v[28:31], v[148:151], v[172:175], v[28:31]
	v_mfma_f32_16x16x32_bf16 v[28:31], v[152:155], v[176:179], v[28:31]
	v_mfma_f32_16x16x32_bf16 v[16:19], v[148:151], v[180:183], v[16:19]
	v_mfma_f32_16x16x32_bf16 v[16:19], v[152:155], v[184:187], v[16:19]
	v_mfma_f32_16x16x32_bf16 v[8:11], v[148:151], v[188:191], v[8:11]
	v_mfma_f32_16x16x32_bf16 v[8:11], v[152:155], v[192:195], v[8:11]
	v_mfma_f32_16x16x32_bf16 v[36:39], v[156:159], v[164:167], v[36:39]
	v_mfma_f32_16x16x32_bf16 v[36:39], v[160:163], v[168:171], v[36:39]
	v_mfma_f32_16x16x32_bf16 v[24:27], v[156:159], v[172:175], v[24:27]
	v_mfma_f32_16x16x32_bf16 v[24:27], v[160:163], v[176:179], v[24:27]
	v_mfma_f32_16x16x32_bf16 v[12:15], v[156:159], v[180:183], v[12:15]
	v_mfma_f32_16x16x32_bf16 v[12:15], v[160:163], v[184:187], v[12:15]
	v_mfma_f32_16x16x32_bf16 v[4:7], v[156:159], v[188:191], v[4:7]
	v_mfma_f32_16x16x32_bf16 v[4:7], v[160:163], v[192:195], v[4:7]
	s_barrier
	s_add_u32 s12, s12, 0x100
	s_addc_u32 s13, s13, 0
	s_add_u32 s3, s3, 0x100
	s_addc_u32 s11, s11, 0
	s_cmp_ge_u32 s20, s2
	s_mov_b32 s14, s20
	s_cbranch_scc0 .LBB0_1164
	s_and_b64 vcc, exec, s[8:9]
	s_cbranch_vccz .LBB0_1167
	s_barrier

;     __device__ __forceinline__ int nt(const Unit& u) const { return (u.pn >> 1) < 2 ? 22 : 20; }
; #define PG8_STAGE(bufoff, gbase, voff) do { _Pragma("unroll") for (int _i = 0; _i < 2; ++_i) \
;         __builtin_amdgcn_global_load_lds((const unsigned*)((const char*)(gbase) + (voff)[_i]), (LAS unsigned*)(lds + (bufoff) + ldsw + _i * 8192), 16, 0, 0); } while (0)
; #define PG8_LDA(dst, b, h) do { _Pragma("unroll") for (int m = 0; m < 4; ++m) _Pragma("unroll") for (int k = 0; k < 2; ++k) dst[m][k] = *(const LAS bf16x8*)(pA + PG8_SA(b, h) + m * 2048 + k * 1024); } while (0)
; #define PG8_LDB(dst, b, h) do { _Pragma("unroll") for (int n = 0; n < 2; ++n) _Pragma("unroll") for (int k = 0; k < 2; ++k) dst[n][k] = *(const LAS bf16x8*)(pB + (PG8_SB(b, h) - 4 * HTB) + n * 2048 + k * 1024); } while (0)
; #define PG8_MMA(ai, bj, At, Bt) do { __builtin_amdgcn_s_setprio(1); _Pragma("unroll") for (int m = 0; m < 4; ++m) _Pragma("unroll") for (int n = 0; n < 2; ++n) _Pragma("unroll") for (int k = 0; k < 2; ++k) \
;         acc[ai][bj][m][n] = __builtin_amdgcn_mfma_f32_16x16x32_bf16(Bt[n][k], At[m][k], acc[ai][bj][m][n], 0, 0, 0); __builtin_amdgcn_s_setprio(0); } while (0)
; #define PG8_WAIT_V(n) asm volatile("s_waitcnt vmcnt(" #n ")" ::: "memory")
; #define PG8_BAR __builtin_amdgcn_s_barrier()
; template <class Desc, class Epi, bool ALIGN_EPI>
; __device__ __forceinline__ void gemm_phase(LAS unsigned char* lds, const Desc& D, const Epi& E, int G, int c) {
;     ...
;         for (int t = 0; t < nt; t += 2) {
;             const bool last = (t == nt - 2);
;             if (last && has_next) PG8_AWAIT(nxt);
;             const char* a1 = cA + (size_t)(t + 1) * kstep;
;             const char* a2 = last ? nA : cA + (size_t)(t + 2) * kstep; const char* b2 = last ? nB : cB + (size_t)(t + 2) * kstep;
;             const char* a3 = a2 + kstep; const char* b3 = b2 + kstep;
;             PG8_LDB(B0, 0, 0); PG8_LDB(B1, 0, 1); PG8_SCHED; PG8_LDA(At, 0, 0); PG8_STAGE(PG8_SA(1, 1), a1 + hstepA, voffA);
;             PG8_WAIT_V(8); PG8_WAIT_L(0); PG8_BAR; PG8_MMA(0, 0, At, B0); PG8_MMA(0, 1, At, B1); PG8_BAR; PG8_SCHED;
;             PG8_LDA(At, 0, 1); PG8_STAGE(PG8_SB(0, 0), b2, voffB); PG8_STAGE(PG8_SB(0, 1), b2 + hstepB, voffB); PG8_STAGE(PG8_SA(0, 0), a2, voffA);
;             PG8_WAIT_V(8); PG8_WAIT_L(0); PG8_BAR; PG8_MMA(1, 0, At, B0); PG8_MMA(1, 1, At, B1); PG8_BAR; PG8_SCHED;
.LBB0_1324:
	ds_read_b128 v[144:147], v149
	ds_read_b128 v[152:155], v149 offset:1024
	ds_read_b128 v[156:159], v149 offset:2048
	ds_read_b128 v[160:163], v149 offset:3072
	ds_read_b128 v[164:167], v149 offset:16384
	ds_read_b128 v[168:171], v149 offset:17408
	ds_read_b128 v[172:175], v149 offset:18432
	ds_read_b128 v[176:179], v149 offset:19456
	s_add_i32 s50, s18, 2
	s_add_u32 s19, s16, 0xfff00080
	s_addc_u32 s20, s17, -1
	s_cmp_eq_u32 s9, s18
	s_cselect_b32 s18, s12, s48
	s_cselect_b32 s21, s11, s20
	s_cselect_b32 s20, s10, s19
	s_cselect_b32 s19, s13, s49
	v_lshl_add_u64 v[212:213], s[16:17], 0, v[140:141]
	s_add_i32 m0, s24, 0xc000
	ds_read_b128 v[180:183], v148
	ds_read_b128 v[184:187], v148 offset:1024
	ds_read_b128 v[188:191], v148 offset:2048
	ds_read_b128 v[192:195], v148 offset:3072
	ds_read_b128 v[196:199], v148 offset:4096
	ds_read_b128 v[200:203], v148 offset:5120
	ds_read_b128 v[204:207], v148 offset:6144
	ds_read_b128 v[208:211], v148 offset:7168
	global_load_lds_dwordx4 v[212:213], off
	v_lshl_add_u64 v[212:213], s[16:17], 0, v[142:143]
	s_add_i32 m0, s24, 0xe000
	s_nop 0
	global_load_lds_dwordx4 v[212:213], off
	s_waitcnt vmcnt(8)
	s_waitcnt lgkmcnt(0)
	s_barrier
	v_mfma_f32_16x16x32_bf16 v[128:131], v[144:147], v[180:183], v[128:131]
	v_mfma_f32_16x16x32_bf16 v[128:131], v[152:155], v[184:187], v[128:131]
	v_mfma_f32_16x16x32_bf16 v[120:123], v[144:147], v[188:191], v[120:123]
	v_mfma_f32_16x16x32_bf16 v[120:123], v[152:155], v[192:195], v[120:123]
	v_mfma_f32_16x16x32_bf16 v[104:107], v[144:147], v[196:199], v[104:107]
	v_mfma_f32_16x16x32_bf16 v[104:107], v[152:155], v[200:203], v[104:107]
	v_mfma_f32_16x16x32_bf16 v[88:91], v[144:147], v[204:207], v[88:91]
	v_mfma_f32_16x16x32_bf16 v[88:91], v[152:155], v[208:211], v[88:91]
	v_mfma_f32_16x16x32_bf16 v[124:127], v[156:159], v[180:183], v[124:127]
	v_mfma_f32_16x16x32_bf16 v[124:127], v[160:163], v[184:187], v[124:127]
	v_mfma_f32_16x16x32_bf16 v[112:115], v[156:159], v[188:191], v[112:115]
	v_mfma_f32_16x16x32_bf16 v[112:115], v[160:163], v[192:195], v[112:115]
	v_mfma_f32_16x16x32_bf16 v[96:99], v[156:159], v[196:199], v[96:99]
	v_mfma_f32_16x16x32_bf16 v[96:99], v[160:163], v[200:203], v[96:99]
	v_mfma_f32_16x16x32_bf16 v[80:83], v[156:159], v[204:207], v[80:83]
	v_mfma_f32_16x16x32_bf16 v[80:83], v[160:163], v[208:211], v[80:83]
	v_mfma_f32_16x16x32_bf16 v[116:119], v[164:167], v[180:183], v[116:119]
	v_mfma_f32_16x16x32_bf16 v[116:119], v[168:171], v[184:187], v[116:119]
	v_mfma_f32_16x16x32_bf16 v[100:103], v[164:167], v[188:191], v[100:103]
	v_mfma_f32_16x16x32_bf16 v[100:103], v[168:171], v[192:195], v[100:103]
	v_mfma_f32_16x16x32_bf16 v[84:87], v[164:167], v[196:199], v[84:87]
	v_mfma_f32_16x16x32_bf16 v[84:87], v[168:171], v[200:203], v[84:87]
	v_mfma_f32_16x16x32_bf16 v[72:75], v[164:167], v[204:207], v[72:75]
	v_mfma_f32_16x16x32_bf16 v[72:75], v[168:171], v[208:211], v[72:75]
	v_mfma_f32_16x16x32_bf16 v[108:111], v[172:175], v[180:183], v[108:111]
	v_mfma_f32_16x16x32_bf16 v[108:111], v[176:179], v[184:187], v[108:111]
	v_mfma_f32_16x16x32_bf16 v[92:95], v[172:175], v[188:191], v[92:95]
	v_mfma_f32_16x16x32_bf16 v[92:95], v[176:179], v[192:195], v[92:95]
	v_mfma_f32_16x16x32_bf16 v[76:79], v[172:175], v[196:199], v[76:79]
	v_mfma_f32_16x16x32_bf16 v[76:79], v[176:179], v[200:203], v[76:79]
	v_mfma_f32_16x16x32_bf16 v[68:71], v[172:175], v[204:207], v[68:71]
	v_mfma_f32_16x16x32_bf16 v[68:71], v[176:179], v[208:211], v[68:71]
	s_barrier
	s_mov_b32 m0, s25
	v_lshl_add_u64 v[212:213], s[18:19], 0, v[136:137]
	s_add_u32 s52, s18, 0x100000
	ds_read_b128 v[180:183], v148 offset:16384
	ds_read_b128 v[184:187], v148 offset:17408
	ds_read_b128 v[188:191], v148 offset:18432
	ds_read_b128 v[192:195], v148 offset:19456
	ds_read_b128 v[196:199], v148 offset:20480
	ds_read_b128 v[200:203], v148 offset:21504
	ds_read_b128 v[204:207], v148 offset:22528
	ds_read_b128 v[208:211], v148 offset:23552
	global_load_lds_dwordx4 v[212:213], off
	v_lshl_add_u64 v[214:215], s[18:19], 0, v[132:133]
	s_mov_b32 m0, s26
	s_addc_u32 s53, s19, 0
	global_load_lds_dwordx4 v[214:215], off
	v_lshl_add_u64 v[216:217], s[52:53], 0, v[136:137]
	s_mov_b32 m0, s27
	v_lshl_add_u64 v[218:219], s[20:21], 0, v[134:135]
	global_load_lds_dwordx4 v[216:217], off
	v_lshl_add_u64 v[216:217], s[52:53], 0, v[132:133]
	s_mov_b32 m0, s30
	s_nop 0
	global_load_lds_dwordx4 v[216:217], off
	v_lshl_add_u64 v[216:217], s[20:21], 0, v[138:139]
	s_mov_b32 m0, s24
	s_nop 0
	global_load_lds_dwordx4 v[216:217], off
	s_mov_b32 m0, s31
	s_nop 0
	global_load_lds_dwordx4 v[218:219], off
	s_waitcnt vmcnt(8)
	s_waitcnt lgkmcnt(0)
	s_barrier
; #define PG8_STAGE(bufoff, gbase, voff) do { _Pragma("unroll") for (int _i = 0; _i < 2; ++_i) \
;         __builtin_amdgcn_global_load_lds((const unsigned*)((const char*)(gbase) + (voff)[_i]), (LAS unsigned*)(lds + (bufoff) + ldsw + _i * 8192), 16, 0, 0); } while (0)
; #define PG8_LDA(dst, b, h) do { _Pragma("unroll") for (int m = 0; m < 4; ++m) _Pragma("unroll") for (int k = 0; k < 2; ++k) dst[m][k] = *(const LAS bf16x8*)(pA + PG8_SA(b, h) + m * 2048 + k * 1024); } while (0)
; #define PG8_LDB(dst, b, h) do { _Pragma("unroll") for (int n = 0; n < 2; ++n) _Pragma("unroll") for (int k = 0; k < 2; ++k) dst[n][k] = *(const LAS bf16x8*)(pB + (PG8_SB(b, h) - 4 * HTB) + n * 2048 + k * 1024); } while (0)
; #define PG8_MMA(ai, bj, At, Bt) do { __builtin_amdgcn_s_setprio(1); _Pragma("unroll") for (int m = 0; m < 4; ++m) _Pragma("unroll") for (int n = 0; n < 2; ++n) _Pragma("unroll") for (int k = 0; k < 2; ++k) \
;         acc[ai][bj][m][n] = __builtin_amdgcn_mfma_f32_16x16x32_bf16(Bt[n][k], At[m][k], acc[ai][bj][m][n], 0, 0, 0); __builtin_amdgcn_s_setprio(0); } while (0)
; #define PG8_WAIT_V(n) asm volatile("s_waitcnt vmcnt(" #n ")" ::: "memory")
; #define PG8_WAIT_L(n) asm volatile("s_waitcnt lgkmcnt(" #n ")" ::: "memory")
; #define PG8_BAR __builtin_amdgcn_s_barrier()
; #define PG8_SCHED __builtin_amdgcn_sched_barrier(0)
; template <class Desc, class Epi, bool ALIGN_EPI>
; __device__ __forceinline__ void gemm_phase(LAS unsigned char* lds, const Desc& D, const Epi& E, int G, int c) {
;     ...
;             PG8_WAIT_V(8); PG8_WAIT_L(0); PG8_BAR; PG8_MMA(1, 0, At, B0); PG8_MMA(1, 1, At, B1); PG8_BAR; PG8_SCHED;
;             PG8_LDB(B0, 1, 0); PG8_LDB(B1, 1, 1); PG8_SCHED; PG8_LDA(At, 1, 0); PG8_STAGE(PG8_SA(0, 1), a2 + hstepA, voffA);
;             PG8_WAIT_V(8); PG8_WAIT_L(0); PG8_BAR; PG8_MMA(0, 0, At, B0); PG8_MMA(0, 1, At, B1); PG8_BAR; PG8_SCHED;
	v_mfma_f32_16x16x32_bf16 v[64:67], v[144:147], v[180:183], v[64:67]
	v_mfma_f32_16x16x32_bf16 v[64:67], v[152:155], v[184:187], v[64:67]
	v_mfma_f32_16x16x32_bf16 v[56:59], v[144:147], v[188:191], v[56:59]
	v_mfma_f32_16x16x32_bf16 v[56:59], v[152:155], v[192:195], v[56:59]
	v_mfma_f32_16x16x32_bf16 v[40:43], v[144:147], v[196:199], v[40:43]
	v_mfma_f32_16x16x32_bf16 v[40:43], v[152:155], v[200:203], v[40:43]
	v_mfma_f32_16x16x32_bf16 v[24:27], v[144:147], v[204:207], v[24:27]
	v_mfma_f32_16x16x32_bf16 v[24:27], v[152:155], v[208:211], v[24:27]
	v_mfma_f32_16x16x32_bf16 v[60:63], v[156:159], v[180:183], v[60:63]
	v_mfma_f32_16x16x32_bf16 v[60:63], v[160:163], v[184:187], v[60:63]
	v_mfma_f32_16x16x32_bf16 v[48:51], v[156:159], v[188:191], v[48:51]
	v_mfma_f32_16x16x32_bf16 v[48:51], v[160:163], v[192:195], v[48:51]
	v_mfma_f32_16x16x32_bf16 v[32:35], v[156:159], v[196:199], v[32:35]
	v_mfma_f32_16x16x32_bf16 v[32:35], v[160:163], v[200:203], v[32:35]
	v_mfma_f32_16x16x32_bf16 v[16:19], v[156:159], v[204:207], v[16:19]
	v_mfma_f32_16x16x32_bf16 v[16:19], v[160:163], v[208:211], v[16:19]
	v_mfma_f32_16x16x32_bf16 v[52:55], v[164:167], v[180:183], v[52:55]
	v_mfma_f32_16x16x32_bf16 v[52:55], v[168:171], v[184:187], v[52:55]
	v_mfma_f32_16x16x32_bf16 v[36:39], v[164:167], v[188:191], v[36:39]
	v_mfma_f32_16x16x32_bf16 v[36:39], v[168:171], v[192:195], v[36:39]
	v_mfma_f32_16x16x32_bf16 v[20:23], v[164:167], v[196:199], v[20:23]
	v_mfma_f32_16x16x32_bf16 v[20:23], v[168:171], v[200:203], v[20:23]
	v_mfma_f32_16x16x32_bf16 v[8:11], v[164:167], v[204:207], v[8:11]
	v_mfma_f32_16x16x32_bf16 v[8:11], v[168:171], v[208:211], v[8:11]
	v_mfma_f32_16x16x32_bf16 v[44:47], v[172:175], v[180:183], v[44:47]
	v_mfma_f32_16x16x32_bf16 v[44:47], v[176:179], v[184:187], v[44:47]
	v_mfma_f32_16x16x32_bf16 v[28:31], v[172:175], v[188:191], v[28:31]
	v_mfma_f32_16x16x32_bf16 v[28:31], v[176:179], v[192:195], v[28:31]
	v_mfma_f32_16x16x32_bf16 v[12:15], v[172:175], v[196:199], v[12:15]
	v_mfma_f32_16x16x32_bf16 v[12:15], v[176:179], v[200:203], v[12:15]
	v_mfma_f32_16x16x32_bf16 v[4:7], v[172:175], v[204:207], v[4:7]
	v_mfma_f32_16x16x32_bf16 v[4:7], v[176:179], v[208:211], v[4:7]
	s_barrier
	ds_read_b128 v[144:147], v149 offset:32768
	ds_read_b128 v[152:155], v149 offset:33792
	ds_read_b128 v[156:159], v149 offset:34816
	ds_read_b128 v[160:163], v149 offset:35840
	ds_read_b128 v[164:167], v149 offset:49152
	ds_read_b128 v[168:171], v149 offset:50176
	ds_read_b128 v[172:175], v149 offset:51200
	ds_read_b128 v[176:179], v149 offset:52224
	s_add_u32 s20, s20, 0x100000
	s_addc_u32 s21, s21, 0
	s_mov_b32 m0, s33
	v_lshl_add_u64 v[220:221], s[20:21], 0, v[138:139]
	ds_read_b128 v[180:183], v148 offset:32768
	ds_read_b128 v[184:187], v148 offset:33792
	ds_read_b128 v[188:191], v148 offset:34816
	ds_read_b128 v[192:195], v148 offset:35840
	ds_read_b128 v[196:199], v148 offset:36864
	ds_read_b128 v[200:203], v148 offset:37888
	ds_read_b128 v[204:207], v148 offset:38912
	ds_read_b128 v[208:211], v148 offset:39936
	global_load_lds_dwordx4 v[220:221], off
	v_lshl_add_u64 v[220:221], s[20:21], 0, v[134:135]
	s_mov_b32 m0, s34
	s_nop 0
	global_load_lds_dwordx4 v[220:221], off
	s_waitcnt vmcnt(8)
	s_waitcnt lgkmcnt(0)
	s_barrier
	v_mfma_f32_16x16x32_bf16 v[128:131], v[144:147], v[180:183], v[128:131]
	v_mfma_f32_16x16x32_bf16 v[128:131], v[152:155], v[184:187], v[128:131]
	v_mfma_f32_16x16x32_bf16 v[120:123], v[144:147], v[188:191], v[120:123]
	v_mfma_f32_16x16x32_bf16 v[120:123], v[152:155], v[192:195], v[120:123]
	v_mfma_f32_16x16x32_bf16 v[104:107], v[144:147], v[196:199], v[104:107]
	v_mfma_f32_16x16x32_bf16 v[104:107], v[152:155], v[200:203], v[104:107]
	v_mfma_f32_16x16x32_bf16 v[88:91], v[144:147], v[204:207], v[88:91]
	v_mfma_f32_16x16x32_bf16 v[88:91], v[152:155], v[208:211], v[88:91]
	v_mfma_f32_16x16x32_bf16 v[124:127], v[156:159], v[180:183], v[124:127]
	v_mfma_f32_16x16x32_bf16 v[124:127], v[160:163], v[184:187], v[124:127]
	v_mfma_f32_16x16x32_bf16 v[112:115], v[156:159], v[188:191], v[112:115]
	v_mfma_f32_16x16x32_bf16 v[112:115], v[160:163], v[192:195], v[112:115]
	v_mfma_f32_16x16x32_bf16 v[96:99], v[156:159], v[196:199], v[96:99]
	v_mfma_f32_16x16x32_bf16 v[96:99], v[160:163], v[200:203], v[96:99]
	v_mfma_f32_16x16x32_bf16 v[80:83], v[156:159], v[204:207], v[80:83]
	v_mfma_f32_16x16x32_bf16 v[80:83], v[160:163], v[208:211], v[80:83]
	v_mfma_f32_16x16x32_bf16 v[116:119], v[164:167], v[180:183], v[116:119]
	v_mfma_f32_16x16x32_bf16 v[116:119], v[168:171], v[184:187], v[116:119]
	v_mfma_f32_16x16x32_bf16 v[100:103], v[164:167], v[188:191], v[100:103]
	v_mfma_f32_16x16x32_bf16 v[100:103], v[168:171], v[192:195], v[100:103]
	v_mfma_f32_16x16x32_bf16 v[84:87], v[164:167], v[196:199], v[84:87]
	v_mfma_f32_16x16x32_bf16 v[84:87], v[168:171], v[200:203], v[84:87]
	v_mfma_f32_16x16x32_bf16 v[72:75], v[164:167], v[204:207], v[72:75]
	v_mfma_f32_16x16x32_bf16 v[72:75], v[168:171], v[208:211], v[72:75]
	v_mfma_f32_16x16x32_bf16 v[108:111], v[172:175], v[180:183], v[108:111]
	v_mfma_f32_16x16x32_bf16 v[108:111], v[176:179], v[184:187], v[108:111]
	v_mfma_f32_16x16x32_bf16 v[92:95], v[172:175], v[188:191], v[92:95]
	v_mfma_f32_16x16x32_bf16 v[92:95], v[176:179], v[192:195], v[92:95]
	v_mfma_f32_16x16x32_bf16 v[76:79], v[172:175], v[196:199], v[76:79]
	v_mfma_f32_16x16x32_bf16 v[76:79], v[176:179], v[200:203], v[76:79]
	v_mfma_f32_16x16x32_bf16 v[68:71], v[172:175], v[204:207], v[68:71]
	v_mfma_f32_16x16x32_bf16 v[68:71], v[176:179], v[208:211], v[68:71]
	s_barrier
; #define PG8_STAGE(bufoff, gbase, voff) do { _Pragma("unroll") for (int _i = 0; _i < 2; ++_i) \
;         __builtin_amdgcn_global_load_lds((const unsigned*)((const char*)(gbase) + (voff)[_i]), (LAS unsigned*)(lds + (bufoff) + ldsw + _i * 8192), 16, 0, 0); } while (0)
; #define PG8_LDA(dst, b, h) do { _Pragma("unroll") for (int m = 0; m < 4; ++m) _Pragma("unroll") for (int k = 0; k < 2; ++k) dst[m][k] = *(const LAS bf16x8*)(pA + PG8_SA(b, h) + m * 2048 + k * 1024); } while (0)
; #define PG8_MMA(ai, bj, At, Bt) do { __builtin_amdgcn_s_setprio(1); _Pragma("unroll") for (int m = 0; m < 4; ++m) _Pragma("unroll") for (int n = 0; n < 2; ++n) _Pragma("unroll") for (int k = 0; k < 2; ++k) \
;         acc[ai][bj][m][n] = __builtin_amdgcn_mfma_f32_16x16x32_bf16(Bt[n][k], At[m][k], acc[ai][bj][m][n], 0, 0, 0); __builtin_amdgcn_s_setprio(0); } while (0)
; #define PG8_WAIT_V(n) asm volatile("s_waitcnt vmcnt(" #n ")" ::: "memory")
; #define PG8_WAIT_L(n) asm volatile("s_waitcnt lgkmcnt(" #n ")" ::: "memory")
; #define PG8_BAR __builtin_amdgcn_s_barrier()
; #define PG8_SCHED __builtin_amdgcn_sched_barrier(0)
; template <class Desc, class Epi, bool ALIGN_EPI>
; __device__ __forceinline__ void gemm_phase(LAS unsigned char* lds, const Desc& D, const Epi& E, int G, int c) {
;     ...
;             PG8_WAIT_V(8); PG8_WAIT_L(0); PG8_BAR; PG8_MMA(0, 0, At, B0); PG8_MMA(0, 1, At, B1); PG8_BAR; PG8_SCHED;
;             PG8_LDA(At, 1, 1); PG8_STAGE(PG8_SB(1, 0), b3, voffB); PG8_STAGE(PG8_SB(1, 1), b3 + hstepB, voffB); PG8_STAGE(PG8_SA(1, 0), a3, voffA);
;             PG8_WAIT_V(8); PG8_WAIT_L(0); PG8_BAR; PG8_MMA(1, 0, At, B0); PG8_MMA(1, 1, At, B1); PG8_BAR; PG8_SCHED;
;         }
;         if constexpr (ALIGN_EPI) { if (wr == 0) PG8_BAR; }
	s_mov_b32 m0, s35
	v_lshl_add_u64 v[212:213], v[212:213], 0, s[76:77]
	s_add_u32 s18, s18, 0x100080
	ds_read_b128 v[180:183], v148 offset:49152
	ds_read_b128 v[184:187], v148 offset:50176
	ds_read_b128 v[188:191], v148 offset:51200
	ds_read_b128 v[192:195], v148 offset:52224
	ds_read_b128 v[196:199], v148 offset:53248
	ds_read_b128 v[200:203], v148 offset:54272
	ds_read_b128 v[204:207], v148 offset:55296
	ds_read_b128 v[208:211], v148 offset:56320
	global_load_lds_dwordx4 v[212:213], off
	v_lshl_add_u64 v[212:213], v[214:215], 0, s[76:77]
	s_mov_b32 m0, s38
	s_addc_u32 s19, s19, 0
	global_load_lds_dwordx4 v[212:213], off
	v_lshl_add_u64 v[212:213], s[18:19], 0, v[136:137]
	s_mov_b32 m0, s41
	s_nop 0
	global_load_lds_dwordx4 v[212:213], off
	v_lshl_add_u64 v[212:213], s[18:19], 0, v[132:133]
	s_mov_b32 m0, s42
	s_nop 0
	global_load_lds_dwordx4 v[212:213], off
	v_lshl_add_u64 v[212:213], v[216:217], 0, s[76:77]
	s_mov_b32 m0, s39
	s_nop 0
	global_load_lds_dwordx4 v[212:213], off
	v_lshl_add_u64 v[212:213], v[218:219], 0, s[76:77]
	s_mov_b32 m0, s40
	s_nop 0
	global_load_lds_dwordx4 v[212:213], off
	s_waitcnt vmcnt(8)
	s_waitcnt lgkmcnt(0)
	s_barrier
	v_mfma_f32_16x16x32_bf16 v[64:67], v[144:147], v[180:183], v[64:67]
	v_mfma_f32_16x16x32_bf16 v[64:67], v[152:155], v[184:187], v[64:67]
	v_mfma_f32_16x16x32_bf16 v[56:59], v[144:147], v[188:191], v[56:59]
	v_mfma_f32_16x16x32_bf16 v[56:59], v[152:155], v[192:195], v[56:59]
	v_mfma_f32_16x16x32_bf16 v[40:43], v[144:147], v[196:199], v[40:43]
	v_mfma_f32_16x16x32_bf16 v[40:43], v[152:155], v[200:203], v[40:43]
	v_mfma_f32_16x16x32_bf16 v[24:27], v[144:147], v[204:207], v[24:27]
	v_mfma_f32_16x16x32_bf16 v[24:27], v[152:155], v[208:211], v[24:27]
	v_mfma_f32_16x16x32_bf16 v[60:63], v[156:159], v[180:183], v[60:63]
	v_mfma_f32_16x16x32_bf16 v[60:63], v[160:163], v[184:187], v[60:63]
	v_mfma_f32_16x16x32_bf16 v[48:51], v[156:159], v[188:191], v[48:51]
	v_mfma_f32_16x16x32_bf16 v[48:51], v[160:163], v[192:195], v[48:51]
	v_mfma_f32_16x16x32_bf16 v[32:35], v[156:159], v[196:199], v[32:35]
	v_mfma_f32_16x16x32_bf16 v[32:35], v[160:163], v[200:203], v[32:35]
	v_mfma_f32_16x16x32_bf16 v[16:19], v[156:159], v[204:207], v[16:19]
	v_mfma_f32_16x16x32_bf16 v[16:19], v[160:163], v[208:211], v[16:19]
	v_mfma_f32_16x16x32_bf16 v[52:55], v[164:167], v[180:183], v[52:55]
	v_mfma_f32_16x16x32_bf16 v[52:55], v[168:171], v[184:187], v[52:55]
	v_mfma_f32_16x16x32_bf16 v[36:39], v[164:167], v[188:191], v[36:39]
	v_mfma_f32_16x16x32_bf16 v[36:39], v[168:171], v[192:195], v[36:39]
	v_mfma_f32_16x16x32_bf16 v[20:23], v[164:167], v[196:199], v[20:23]
	v_mfma_f32_16x16x32_bf16 v[20:23], v[168:171], v[200:203], v[20:23]
	v_mfma_f32_16x16x32_bf16 v[8:11], v[164:167], v[204:207], v[8:11]
	v_mfma_f32_16x16x32_bf16 v[8:11], v[168:171], v[208:211], v[8:11]
	v_mfma_f32_16x16x32_bf16 v[44:47], v[172:175], v[180:183], v[44:47]
	v_mfma_f32_16x16x32_bf16 v[44:47], v[176:179], v[184:187], v[44:47]
	v_mfma_f32_16x16x32_bf16 v[28:31], v[172:175], v[188:191], v[28:31]
	v_mfma_f32_16x16x32_bf16 v[28:31], v[176:179], v[192:195], v[28:31]
	v_mfma_f32_16x16x32_bf16 v[12:15], v[172:175], v[196:199], v[12:15]
	v_mfma_f32_16x16x32_bf16 v[12:15], v[176:179], v[200:203], v[12:15]
	v_mfma_f32_16x16x32_bf16 v[4:7], v[172:175], v[204:207], v[4:7]
	v_mfma_f32_16x16x32_bf16 v[4:7], v[176:179], v[208:211], v[4:7]
	s_barrier
	s_add_u32 s16, s16, 0x100
	s_addc_u32 s17, s17, 0
	s_add_u32 s48, s48, 0x100
	s_addc_u32 s49, s49, 0
	s_cmp_ge_u32 s50, s46
	s_mov_b32 s18, s50
	s_cbranch_scc0 .LBB0_1324
	s_and_b64 vcc, exec, s[6:7]
	s_cbranch_vccz .LBB0_1327
	s_barrier

;     __device__ __forceinline__ int nt(const Unit& u) const { return (u.pn >> 1) < 2 ? 22 : 20; }
; #define PG8_STAGE(bufoff, gbase, voff) do { _Pragma("unroll") for (int _i = 0; _i < 2; ++_i) \
;         __builtin_amdgcn_global_load_lds((const unsigned*)((const char*)(gbase) + (voff)[_i]), (LAS unsigned*)(lds + (bufoff) + ldsw + _i * 8192), 16, 0, 0); } while (0)
; #define PG8_LDA(dst, b, h) do { _Pragma("unroll") for (int m = 0; m < 4; ++m) _Pragma("unroll") for (int k = 0; k < 2; ++k) dst[m][k] = *(const LAS bf16x8*)(pA + PG8_SA(b, h) + m * 2048 + k * 1024); } while (0)
; #define PG8_LDB(dst, b, h) do { _Pragma("unroll") for (int n = 0; n < 2; ++n) _Pragma("unroll") for (int k = 0; k < 2; ++k) dst[n][k] = *(const LAS bf16x8*)(pB + (PG8_SB(b, h) - 4 * HTB) + n * 2048 + k * 1024); } while (0)
; #define PG8_MMA(ai, bj, At, Bt) do { __builtin_amdgcn_s_setprio(1); _Pragma("unroll") for (int m = 0; m < 4; ++m) _Pragma("unroll") for (int n = 0; n < 2; ++n) _Pragma("unroll") for (int k = 0; k < 2; ++k) \
;         acc[ai][bj][m][n] = __builtin_amdgcn_mfma_f32_16x16x32_bf16(Bt[n][k], At[m][k], acc[ai][bj][m][n], 0, 0, 0); __builtin_amdgcn_s_setprio(0); } while (0)
; #define PG8_WAIT_V(n) asm volatile("s_waitcnt vmcnt(" #n ")" ::: "memory")
; #define PG8_BAR __builtin_amdgcn_s_barrier()
; template <class Desc, class Epi, bool ALIGN_EPI>
; __device__ __forceinline__ void gemm_phase(LAS unsigned char* lds, const Desc& D, const Epi& E, int G, int c) {
;     ...
;         for (int t = 0; t < nt; t += 2) {
;             const bool last = (t == nt - 2);
;             if (last && has_next) PG8_AWAIT(nxt);
;             const char* a1 = cA + (size_t)(t + 1) * kstep;
;             const char* a2 = last ? nA : cA + (size_t)(t + 2) * kstep; const char* b2 = last ? nB : cB + (size_t)(t + 2) * kstep;
;             const char* a3 = a2 + kstep; const char* b3 = b2 + kstep;
;             PG8_LDB(B0, 0, 0); PG8_LDB(B1, 0, 1); PG8_SCHED; PG8_LDA(At, 0, 0); PG8_STAGE(PG8_SA(1, 1), a1 + hstepA, voffA);
;             PG8_WAIT_V(8); PG8_WAIT_L(0); PG8_BAR; PG8_MMA(0, 0, At, B0); PG8_MMA(0, 1, At, B1); PG8_BAR; PG8_SCHED;
;             PG8_LDA(At, 0, 1); PG8_STAGE(PG8_SB(0, 0), b2, voffB); PG8_STAGE(PG8_SB(0, 1), b2 + hstepB, voffB); PG8_STAGE(PG8_SA(0, 0), a2, voffA);
;             PG8_WAIT_V(8); PG8_WAIT_L(0); PG8_BAR; PG8_MMA(1, 0, At, B0); PG8_MMA(1, 1, At, B1); PG8_BAR; PG8_SCHED;
.LBB0_1479:
	ds_read_b128 v[116:119], v225
	ds_read_b128 v[128:131], v225 offset:1024
	ds_read_b128 v[132:135], v225 offset:2048
	ds_read_b128 v[136:139], v225 offset:3072
	ds_read_b128 v[140:143], v225 offset:16384
	ds_read_b128 v[144:147], v225 offset:17408
	ds_read_b128 v[148:151], v225 offset:18432
	ds_read_b128 v[152:155], v225 offset:19456
	s_add_u32 s12, s0, 0xfffe0080
	s_addc_u32 s13, s1, -1
	s_cmp_eq_u32 s52, 4
	s_cselect_b32 s17, s37, s13
	s_cselect_b32 s16, s36, s12
	s_cselect_b32 s13, s21, s33
	s_cselect_b32 s12, s24, s27
	v_lshl_add_u64 v[208:209], s[0:1], 0, v[200:201]
	s_add_i32 m0, s31, 0xc000
	ds_read_b128 v[164:167], v224
	ds_read_b128 v[168:171], v224 offset:1024
	ds_read_b128 v[172:175], v224 offset:2048
	ds_read_b128 v[176:179], v224 offset:3072
	ds_read_b128 v[180:183], v224 offset:4096
	ds_read_b128 v[184:187], v224 offset:5120
	ds_read_b128 v[188:191], v224 offset:6144
	ds_read_b128 v[204:207], v224 offset:7168
	global_load_lds_dwordx4 v[208:209], off
	v_lshl_add_u64 v[208:209], s[0:1], 0, v[202:203]
	s_add_i32 m0, s31, 0xe000
	s_nop 0
	global_load_lds_dwordx4 v[208:209], off
	s_waitcnt vmcnt(8)
	s_waitcnt lgkmcnt(0)
	s_barrier
	v_mfma_f32_16x16x32_bf16 v[160:163], v[116:119], v[164:167], v[160:163]
	v_mfma_f32_16x16x32_bf16 v[160:163], v[128:131], v[168:171], v[160:163]
	v_mfma_f32_16x16x32_bf16 v[112:115], v[116:119], v[172:175], v[112:115]
	v_mfma_f32_16x16x32_bf16 v[112:115], v[128:131], v[176:179], v[112:115]
	v_mfma_f32_16x16x32_bf16 v[96:99], v[116:119], v[180:183], v[96:99]
	v_mfma_f32_16x16x32_bf16 v[96:99], v[128:131], v[184:187], v[96:99]
	v_mfma_f32_16x16x32_bf16 v[80:83], v[116:119], v[188:191], v[80:83]
	v_mfma_f32_16x16x32_bf16 v[80:83], v[128:131], v[204:207], v[80:83]
	v_mfma_f32_16x16x32_bf16 v[156:159], v[132:135], v[164:167], v[156:159]
	v_mfma_f32_16x16x32_bf16 v[156:159], v[136:139], v[168:171], v[156:159]
	v_mfma_f32_16x16x32_bf16 v[108:111], v[132:135], v[172:175], v[108:111]
	v_mfma_f32_16x16x32_bf16 v[108:111], v[136:139], v[176:179], v[108:111]
	v_mfma_f32_16x16x32_bf16 v[92:95], v[132:135], v[180:183], v[92:95]
	v_mfma_f32_16x16x32_bf16 v[92:95], v[136:139], v[184:187], v[92:95]
	v_mfma_f32_16x16x32_bf16 v[76:79], v[132:135], v[188:191], v[76:79]
	v_mfma_f32_16x16x32_bf16 v[76:79], v[136:139], v[204:207], v[76:79]
	v_mfma_f32_16x16x32_bf16 v[124:127], v[140:143], v[164:167], v[124:127]
	v_mfma_f32_16x16x32_bf16 v[124:127], v[144:147], v[168:171], v[124:127]
	v_mfma_f32_16x16x32_bf16 v[104:107], v[140:143], v[172:175], v[104:107]
	v_mfma_f32_16x16x32_bf16 v[104:107], v[144:147], v[176:179], v[104:107]
	v_mfma_f32_16x16x32_bf16 v[88:91], v[140:143], v[180:183], v[88:91]
	v_mfma_f32_16x16x32_bf16 v[88:91], v[144:147], v[184:187], v[88:91]
	v_mfma_f32_16x16x32_bf16 v[72:75], v[140:143], v[188:191], v[72:75]
	v_mfma_f32_16x16x32_bf16 v[72:75], v[144:147], v[204:207], v[72:75]
	v_mfma_f32_16x16x32_bf16 v[120:123], v[148:151], v[164:167], v[120:123]
	v_mfma_f32_16x16x32_bf16 v[120:123], v[152:155], v[168:171], v[120:123]
	v_mfma_f32_16x16x32_bf16 v[100:103], v[148:151], v[172:175], v[100:103]
	v_mfma_f32_16x16x32_bf16 v[100:103], v[152:155], v[176:179], v[100:103]
	v_mfma_f32_16x16x32_bf16 v[84:87], v[148:151], v[180:183], v[84:87]
	v_mfma_f32_16x16x32_bf16 v[84:87], v[152:155], v[184:187], v[84:87]
	v_mfma_f32_16x16x32_bf16 v[68:71], v[148:151], v[188:191], v[68:71]
	v_mfma_f32_16x16x32_bf16 v[68:71], v[152:155], v[204:207], v[68:71]
	s_barrier
	s_mov_b32 m0, s34
	v_lshl_add_u64 v[208:209], s[12:13], 0, v[196:197]
	s_add_u32 s54, s12, 0x20000
	ds_read_b128 v[164:167], v224 offset:16384
	ds_read_b128 v[168:171], v224 offset:17408
	ds_read_b128 v[172:175], v224 offset:18432
	ds_read_b128 v[176:179], v224 offset:19456
	ds_read_b128 v[180:183], v224 offset:20480
	ds_read_b128 v[184:187], v224 offset:21504
	ds_read_b128 v[188:191], v224 offset:22528
	ds_read_b128 v[204:207], v224 offset:23552
	global_load_lds_dwordx4 v[208:209], off
	v_lshl_add_u64 v[210:211], s[12:13], 0, v[192:193]
	s_mov_b32 m0, s35
	s_addc_u32 s55, s13, 0
	global_load_lds_dwordx4 v[210:211], off
	v_lshl_add_u64 v[212:213], s[54:55], 0, v[196:197]
	s_mov_b32 m0, s40
	v_lshl_add_u64 v[214:215], s[16:17], 0, v[194:195]
	global_load_lds_dwordx4 v[212:213], off
	v_lshl_add_u64 v[212:213], s[54:55], 0, v[192:193]
	s_mov_b32 m0, s41
	s_nop 0
	global_load_lds_dwordx4 v[212:213], off
	v_lshl_add_u64 v[212:213], s[16:17], 0, v[198:199]
	s_mov_b32 m0, s31
	s_nop 0
	global_load_lds_dwordx4 v[212:213], off
	s_mov_b32 m0, s42
	s_nop 0
	global_load_lds_dwordx4 v[214:215], off
	s_waitcnt vmcnt(8)
	s_waitcnt lgkmcnt(0)
	s_barrier
; #define PG8_STAGE(bufoff, gbase, voff) do { _Pragma("unroll") for (int _i = 0; _i < 2; ++_i) \
;         __builtin_amdgcn_global_load_lds((const unsigned*)((const char*)(gbase) + (voff)[_i]), (LAS unsigned*)(lds + (bufoff) + ldsw + _i * 8192), 16, 0, 0); } while (0)
; #define PG8_LDA(dst, b, h) do { _Pragma("unroll") for (int m = 0; m < 4; ++m) _Pragma("unroll") for (int k = 0; k < 2; ++k) dst[m][k] = *(const LAS bf16x8*)(pA + PG8_SA(b, h) + m * 2048 + k * 1024); } while (0)
; #define PG8_LDB(dst, b, h) do { _Pragma("unroll") for (int n = 0; n < 2; ++n) _Pragma("unroll") for (int k = 0; k < 2; ++k) dst[n][k] = *(const LAS bf16x8*)(pB + (PG8_SB(b, h) - 4 * HTB) + n * 2048 + k * 1024); } while (0)
; #define PG8_MMA(ai, bj, At, Bt) do { __builtin_amdgcn_s_setprio(1); _Pragma("unroll") for (int m = 0; m < 4; ++m) _Pragma("unroll") for (int n = 0; n < 2; ++n) _Pragma("unroll") for (int k = 0; k < 2; ++k) \
;         acc[ai][bj][m][n] = __builtin_amdgcn_mfma_f32_16x16x32_bf16(Bt[n][k], At[m][k], acc[ai][bj][m][n], 0, 0, 0); __builtin_amdgcn_s_setprio(0); } while (0)
; #define PG8_WAIT_V(n) asm volatile("s_waitcnt vmcnt(" #n ")" ::: "memory")
; #define PG8_WAIT_L(n) asm volatile("s_waitcnt lgkmcnt(" #n ")" ::: "memory")
; #define PG8_BAR __builtin_amdgcn_s_barrier()
; #define PG8_SCHED __builtin_amdgcn_sched_barrier(0)
; template <class Desc, class Epi, bool ALIGN_EPI>
; __device__ __forceinline__ void gemm_phase(LAS unsigned char* lds, const Desc& D, const Epi& E, int G, int c) {
;     ...
;             PG8_WAIT_V(8); PG8_WAIT_L(0); PG8_BAR; PG8_MMA(1, 0, At, B0); PG8_MMA(1, 1, At, B1); PG8_BAR; PG8_SCHED;
;             PG8_LDB(B0, 1, 0); PG8_LDB(B1, 1, 1); PG8_SCHED; PG8_LDA(At, 1, 0); PG8_STAGE(PG8_SA(0, 1), a2 + hstepA, voffA);
;             PG8_WAIT_V(8); PG8_WAIT_L(0); PG8_BAR; PG8_MMA(0, 0, At, B0); PG8_MMA(0, 1, At, B1); PG8_BAR; PG8_SCHED;
	v_mfma_f32_16x16x32_bf16 v[64:67], v[116:119], v[164:167], v[64:67]
	v_mfma_f32_16x16x32_bf16 v[64:67], v[128:131], v[168:171], v[64:67]
	v_mfma_f32_16x16x32_bf16 v[48:51], v[116:119], v[172:175], v[48:51]
	v_mfma_f32_16x16x32_bf16 v[48:51], v[128:131], v[176:179], v[48:51]
	v_mfma_f32_16x16x32_bf16 v[32:35], v[116:119], v[180:183], v[32:35]
	v_mfma_f32_16x16x32_bf16 v[32:35], v[128:131], v[184:187], v[32:35]
	v_mfma_f32_16x16x32_bf16 v[16:19], v[116:119], v[188:191], v[16:19]
	v_mfma_f32_16x16x32_bf16 v[16:19], v[128:131], v[204:207], v[16:19]
	v_mfma_f32_16x16x32_bf16 v[60:63], v[132:135], v[164:167], v[60:63]
	v_mfma_f32_16x16x32_bf16 v[60:63], v[136:139], v[168:171], v[60:63]
	v_mfma_f32_16x16x32_bf16 v[44:47], v[132:135], v[172:175], v[44:47]
	v_mfma_f32_16x16x32_bf16 v[44:47], v[136:139], v[176:179], v[44:47]
	v_mfma_f32_16x16x32_bf16 v[28:31], v[132:135], v[180:183], v[28:31]
	v_mfma_f32_16x16x32_bf16 v[28:31], v[136:139], v[184:187], v[28:31]
	v_mfma_f32_16x16x32_bf16 v[12:15], v[132:135], v[188:191], v[12:15]
	v_mfma_f32_16x16x32_bf16 v[12:15], v[136:139], v[204:207], v[12:15]
	v_mfma_f32_16x16x32_bf16 v[56:59], v[140:143], v[164:167], v[56:59]
	v_mfma_f32_16x16x32_bf16 v[56:59], v[144:147], v[168:171], v[56:59]
	v_mfma_f32_16x16x32_bf16 v[40:43], v[140:143], v[172:175], v[40:43]
	v_mfma_f32_16x16x32_bf16 v[40:43], v[144:147], v[176:179], v[40:43]
	v_mfma_f32_16x16x32_bf16 v[24:27], v[140:143], v[180:183], v[24:27]
	v_mfma_f32_16x16x32_bf16 v[24:27], v[144:147], v[184:187], v[24:27]
	v_mfma_f32_16x16x32_bf16 v[8:11], v[140:143], v[188:191], v[8:11]
	v_mfma_f32_16x16x32_bf16 v[8:11], v[144:147], v[204:207], v[8:11]
	v_mfma_f32_16x16x32_bf16 v[52:55], v[148:151], v[164:167], v[52:55]
	v_mfma_f32_16x16x32_bf16 v[52:55], v[152:155], v[168:171], v[52:55]
	v_mfma_f32_16x16x32_bf16 v[36:39], v[148:151], v[172:175], v[36:39]
	v_mfma_f32_16x16x32_bf16 v[36:39], v[152:155], v[176:179], v[36:39]
	v_mfma_f32_16x16x32_bf16 v[20:23], v[148:151], v[180:183], v[20:23]
	v_mfma_f32_16x16x32_bf16 v[20:23], v[152:155], v[184:187], v[20:23]
	v_mfma_f32_16x16x32_bf16 v[4:7], v[148:151], v[188:191], v[4:7]
	v_mfma_f32_16x16x32_bf16 v[4:7], v[152:155], v[204:207], v[4:7]
	s_barrier
	ds_read_b128 v[116:119], v225 offset:32768
	ds_read_b128 v[128:131], v225 offset:33792
	ds_read_b128 v[132:135], v225 offset:34816
	ds_read_b128 v[136:139], v225 offset:35840
	ds_read_b128 v[140:143], v225 offset:49152
	ds_read_b128 v[144:147], v225 offset:50176
	ds_read_b128 v[148:151], v225 offset:51200
	ds_read_b128 v[152:155], v225 offset:52224
	s_add_u32 s16, s16, 0x20000
	s_addc_u32 s17, s17, 0
	s_mov_b32 m0, s43
	v_lshl_add_u64 v[216:217], s[16:17], 0, v[198:199]
	ds_read_b128 v[164:167], v224 offset:32768
	ds_read_b128 v[168:171], v224 offset:33792
	ds_read_b128 v[172:175], v224 offset:34816
	ds_read_b128 v[176:179], v224 offset:35840
	ds_read_b128 v[180:183], v224 offset:36864
	ds_read_b128 v[184:187], v224 offset:37888
	ds_read_b128 v[188:191], v224 offset:38912
	ds_read_b128 v[204:207], v224 offset:39936
	global_load_lds_dwordx4 v[216:217], off
	v_lshl_add_u64 v[216:217], s[16:17], 0, v[194:195]
	s_mov_b32 m0, s44
	s_nop 0
	global_load_lds_dwordx4 v[216:217], off
	s_waitcnt vmcnt(8)
	s_waitcnt lgkmcnt(0)
	s_barrier
	v_mfma_f32_16x16x32_bf16 v[160:163], v[116:119], v[164:167], v[160:163]
	v_mfma_f32_16x16x32_bf16 v[160:163], v[128:131], v[168:171], v[160:163]
	v_mfma_f32_16x16x32_bf16 v[112:115], v[116:119], v[172:175], v[112:115]
	v_mfma_f32_16x16x32_bf16 v[112:115], v[128:131], v[176:179], v[112:115]
	v_mfma_f32_16x16x32_bf16 v[96:99], v[116:119], v[180:183], v[96:99]
	v_mfma_f32_16x16x32_bf16 v[96:99], v[128:131], v[184:187], v[96:99]
	v_mfma_f32_16x16x32_bf16 v[80:83], v[116:119], v[188:191], v[80:83]
	v_mfma_f32_16x16x32_bf16 v[80:83], v[128:131], v[204:207], v[80:83]
	v_mfma_f32_16x16x32_bf16 v[156:159], v[132:135], v[164:167], v[156:159]
	v_mfma_f32_16x16x32_bf16 v[156:159], v[136:139], v[168:171], v[156:159]
	v_mfma_f32_16x16x32_bf16 v[108:111], v[132:135], v[172:175], v[108:111]
	v_mfma_f32_16x16x32_bf16 v[108:111], v[136:139], v[176:179], v[108:111]
	v_mfma_f32_16x16x32_bf16 v[92:95], v[132:135], v[180:183], v[92:95]
	v_mfma_f32_16x16x32_bf16 v[92:95], v[136:139], v[184:187], v[92:95]
	v_mfma_f32_16x16x32_bf16 v[76:79], v[132:135], v[188:191], v[76:79]
	v_mfma_f32_16x16x32_bf16 v[76:79], v[136:139], v[204:207], v[76:79]
	v_mfma_f32_16x16x32_bf16 v[124:127], v[140:143], v[164:167], v[124:127]
	v_mfma_f32_16x16x32_bf16 v[124:127], v[144:147], v[168:171], v[124:127]
	v_mfma_f32_16x16x32_bf16 v[104:107], v[140:143], v[172:175], v[104:107]
	v_mfma_f32_16x16x32_bf16 v[104:107], v[144:147], v[176:179], v[104:107]
	v_mfma_f32_16x16x32_bf16 v[88:91], v[140:143], v[180:183], v[88:91]
	v_mfma_f32_16x16x32_bf16 v[88:91], v[144:147], v[184:187], v[88:91]
	v_mfma_f32_16x16x32_bf16 v[72:75], v[140:143], v[188:191], v[72:75]
	v_mfma_f32_16x16x32_bf16 v[72:75], v[144:147], v[204:207], v[72:75]
	v_mfma_f32_16x16x32_bf16 v[120:123], v[148:151], v[164:167], v[120:123]
	v_mfma_f32_16x16x32_bf16 v[120:123], v[152:155], v[168:171], v[120:123]
	v_mfma_f32_16x16x32_bf16 v[100:103], v[148:151], v[172:175], v[100:103]
	v_mfma_f32_16x16x32_bf16 v[100:103], v[152:155], v[176:179], v[100:103]
	v_mfma_f32_16x16x32_bf16 v[84:87], v[148:151], v[180:183], v[84:87]
	v_mfma_f32_16x16x32_bf16 v[84:87], v[152:155], v[184:187], v[84:87]
	v_mfma_f32_16x16x32_bf16 v[68:71], v[148:151], v[188:191], v[68:71]
	v_mfma_f32_16x16x32_bf16 v[68:71], v[152:155], v[204:207], v[68:71]
	s_barrier
; #define PG8_STAGE(bufoff, gbase, voff) do { _Pragma("unroll") for (int _i = 0; _i < 2; ++_i) \
;         __builtin_amdgcn_global_load_lds((const unsigned*)((const char*)(gbase) + (voff)[_i]), (LAS unsigned*)(lds + (bufoff) + ldsw + _i * 8192), 16, 0, 0); } while (0)
; #define PG8_LDA(dst, b, h) do { _Pragma("unroll") for (int m = 0; m < 4; ++m) _Pragma("unroll") for (int k = 0; k < 2; ++k) dst[m][k] = *(const LAS bf16x8*)(pA + PG8_SA(b, h) + m * 2048 + k * 1024); } while (0)
; #define PG8_MMA(ai, bj, At, Bt) do { __builtin_amdgcn_s_setprio(1); _Pragma("unroll") for (int m = 0; m < 4; ++m) _Pragma("unroll") for (int n = 0; n < 2; ++n) _Pragma("unroll") for (int k = 0; k < 2; ++k) \
;         acc[ai][bj][m][n] = __builtin_amdgcn_mfma_f32_16x16x32_bf16(Bt[n][k], At[m][k], acc[ai][bj][m][n], 0, 0, 0); __builtin_amdgcn_s_setprio(0); } while (0)
; #define PG8_WAIT_V(n) asm volatile("s_waitcnt vmcnt(" #n ")" ::: "memory")
; #define PG8_WAIT_L(n) asm volatile("s_waitcnt lgkmcnt(" #n ")" ::: "memory")
; #define PG8_BAR __builtin_amdgcn_s_barrier()
; #define PG8_SCHED __builtin_amdgcn_sched_barrier(0)
; template <class Desc, class Epi, bool ALIGN_EPI>
; __device__ __forceinline__ void gemm_phase(LAS unsigned char* lds, const Desc& D, const Epi& E, int G, int c) {
;     ...
;             PG8_WAIT_V(8); PG8_WAIT_L(0); PG8_BAR; PG8_MMA(0, 0, At, B0); PG8_MMA(0, 1, At, B1); PG8_BAR; PG8_SCHED;
;             PG8_LDA(At, 1, 1); PG8_STAGE(PG8_SB(1, 0), b3, voffB); PG8_STAGE(PG8_SB(1, 1), b3 + hstepB, voffB); PG8_STAGE(PG8_SA(1, 0), a3, voffA);
;             PG8_WAIT_V(8); PG8_WAIT_L(0); PG8_BAR; PG8_MMA(1, 0, At, B0); PG8_MMA(1, 1, At, B1); PG8_BAR; PG8_SCHED;
;         }
;         if constexpr (ALIGN_EPI) { if (wr == 0) PG8_BAR; }
	s_mov_b32 m0, s45
	v_lshl_add_u64 v[208:209], v[208:209], 0, s[76:77]
	s_add_u32 s12, s12, 0x20080
	ds_read_b128 v[164:167], v224 offset:49152
	ds_read_b128 v[168:171], v224 offset:50176
	ds_read_b128 v[172:175], v224 offset:51200
	ds_read_b128 v[176:179], v224 offset:52224
	ds_read_b128 v[180:183], v224 offset:53248
	ds_read_b128 v[184:187], v224 offset:54272
	ds_read_b128 v[188:191], v224 offset:55296
	ds_read_b128 v[204:207], v224 offset:56320
	global_load_lds_dwordx4 v[208:209], off
	v_lshl_add_u64 v[208:209], v[210:211], 0, s[76:77]
	s_mov_b32 m0, s46
	s_addc_u32 s13, s13, 0
	global_load_lds_dwordx4 v[208:209], off
	v_lshl_add_u64 v[208:209], s[12:13], 0, v[196:197]
	s_mov_b32 m0, s49
	s_nop 0
	global_load_lds_dwordx4 v[208:209], off
	v_lshl_add_u64 v[208:209], s[12:13], 0, v[192:193]
	s_mov_b32 m0, s50
	s_nop 0
	global_load_lds_dwordx4 v[208:209], off
	v_lshl_add_u64 v[208:209], v[212:213], 0, s[76:77]
	s_mov_b32 m0, s47
	s_nop 0
	global_load_lds_dwordx4 v[208:209], off
	v_lshl_add_u64 v[208:209], v[214:215], 0, s[76:77]
	s_mov_b32 m0, s48
	s_nop 0
	global_load_lds_dwordx4 v[208:209], off
	s_waitcnt vmcnt(8)
	s_waitcnt lgkmcnt(0)
	s_barrier
	v_mfma_f32_16x16x32_bf16 v[64:67], v[116:119], v[164:167], v[64:67]
	v_mfma_f32_16x16x32_bf16 v[64:67], v[128:131], v[168:171], v[64:67]
	v_mfma_f32_16x16x32_bf16 v[48:51], v[116:119], v[172:175], v[48:51]
	v_mfma_f32_16x16x32_bf16 v[48:51], v[128:131], v[176:179], v[48:51]
	v_mfma_f32_16x16x32_bf16 v[32:35], v[116:119], v[180:183], v[32:35]
	v_mfma_f32_16x16x32_bf16 v[32:35], v[128:131], v[184:187], v[32:35]
	v_mfma_f32_16x16x32_bf16 v[16:19], v[116:119], v[188:191], v[16:19]
	v_mfma_f32_16x16x32_bf16 v[16:19], v[128:131], v[204:207], v[16:19]
	v_mfma_f32_16x16x32_bf16 v[60:63], v[132:135], v[164:167], v[60:63]
	v_mfma_f32_16x16x32_bf16 v[60:63], v[136:139], v[168:171], v[60:63]
	v_mfma_f32_16x16x32_bf16 v[44:47], v[132:135], v[172:175], v[44:47]
	v_mfma_f32_16x16x32_bf16 v[44:47], v[136:139], v[176:179], v[44:47]
	v_mfma_f32_16x16x32_bf16 v[28:31], v[132:135], v[180:183], v[28:31]
	v_mfma_f32_16x16x32_bf16 v[28:31], v[136:139], v[184:187], v[28:31]
	v_mfma_f32_16x16x32_bf16 v[12:15], v[132:135], v[188:191], v[12:15]
	v_mfma_f32_16x16x32_bf16 v[12:15], v[136:139], v[204:207], v[12:15]
	v_mfma_f32_16x16x32_bf16 v[56:59], v[140:143], v[164:167], v[56:59]
	v_mfma_f32_16x16x32_bf16 v[56:59], v[144:147], v[168:171], v[56:59]
	v_mfma_f32_16x16x32_bf16 v[40:43], v[140:143], v[172:175], v[40:43]
	v_mfma_f32_16x16x32_bf16 v[40:43], v[144:147], v[176:179], v[40:43]
	v_mfma_f32_16x16x32_bf16 v[24:27], v[140:143], v[180:183], v[24:27]
	v_mfma_f32_16x16x32_bf16 v[24:27], v[144:147], v[184:187], v[24:27]
	v_mfma_f32_16x16x32_bf16 v[8:11], v[140:143], v[188:191], v[8:11]
	v_mfma_f32_16x16x32_bf16 v[8:11], v[144:147], v[204:207], v[8:11]
	v_mfma_f32_16x16x32_bf16 v[52:55], v[148:151], v[164:167], v[52:55]
	v_mfma_f32_16x16x32_bf16 v[52:55], v[152:155], v[168:171], v[52:55]
	v_mfma_f32_16x16x32_bf16 v[36:39], v[148:151], v[172:175], v[36:39]
	v_mfma_f32_16x16x32_bf16 v[36:39], v[152:155], v[176:179], v[36:39]
	v_mfma_f32_16x16x32_bf16 v[20:23], v[148:151], v[180:183], v[20:23]
	v_mfma_f32_16x16x32_bf16 v[20:23], v[152:155], v[184:187], v[20:23]
	v_mfma_f32_16x16x32_bf16 v[4:7], v[148:151], v[188:191], v[4:7]
	v_mfma_f32_16x16x32_bf16 v[4:7], v[152:155], v[204:207], v[4:7]
	s_barrier
	s_add_i32 s52, s52, 2
	s_add_u32 s0, s0, 0x100
	s_addc_u32 s1, s1, 0
	s_add_u32 s27, s27, 0x100
	s_addc_u32 s33, s33, 0
	s_cmp_gt_u32 s52, 5
	s_cbranch_scc0 .LBB0_1479
	s_and_b64 vcc, exec, s[8:9]
	s_cbranch_vccz .LBB0_1482
	s_barrier

;     __device__ __forceinline__ int nt(const Unit& u) const { return (u.pn >> 1) < 2 ? 22 : 20; }
; #define PG8_STAGE(bufoff, gbase, voff) do { _Pragma("unroll") for (int _i = 0; _i < 2; ++_i) \
;         __builtin_amdgcn_global_load_lds((const unsigned*)((const char*)(gbase) + (voff)[_i]), (LAS unsigned*)(lds + (bufoff) + ldsw + _i * 8192), 16, 0, 0); } while (0)
; #define PG8_LDA(dst, b, h) do { _Pragma("unroll") for (int m = 0; m < 4; ++m) _Pragma("unroll") for (int k = 0; k < 2; ++k) dst[m][k] = *(const LAS bf16x8*)(pA + PG8_SA(b, h) + m * 2048 + k * 1024); } while (0)
; #define PG8_LDB(dst, b, h) do { _Pragma("unroll") for (int n = 0; n < 2; ++n) _Pragma("unroll") for (int k = 0; k < 2; ++k) dst[n][k] = *(const LAS bf16x8*)(pB + (PG8_SB(b, h) - 4 * HTB) + n * 2048 + k * 1024); } while (0)
; #define PG8_MMA(ai, bj, At, Bt) do { __builtin_amdgcn_s_setprio(1); _Pragma("unroll") for (int m = 0; m < 4; ++m) _Pragma("unroll") for (int n = 0; n < 2; ++n) _Pragma("unroll") for (int k = 0; k < 2; ++k) \
;         acc[ai][bj][m][n] = __builtin_amdgcn_mfma_f32_16x16x32_bf16(Bt[n][k], At[m][k], acc[ai][bj][m][n], 0, 0, 0); __builtin_amdgcn_s_setprio(0); } while (0)
; #define PG8_WAIT_V(n) asm volatile("s_waitcnt vmcnt(" #n ")" ::: "memory")
; #define PG8_BAR __builtin_amdgcn_s_barrier()
; template <class Desc, class Epi, bool ALIGN_EPI>
; __device__ __forceinline__ void gemm_phase(LAS unsigned char* lds, const Desc& D, const Epi& E, int G, int c) {
;     ...
;         for (int t = 0; t < nt; t += 2) {
;             const bool last = (t == nt - 2);
;             if (last && has_next) PG8_AWAIT(nxt);
;             const char* a1 = cA + (size_t)(t + 1) * kstep;
;             const char* a2 = last ? nA : cA + (size_t)(t + 2) * kstep; const char* b2 = last ? nB : cB + (size_t)(t + 2) * kstep;
;             const char* a3 = a2 + kstep; const char* b3 = b2 + kstep;
;             PG8_LDB(B0, 0, 0); PG8_LDB(B1, 0, 1); PG8_SCHED; PG8_LDA(At, 0, 0); PG8_STAGE(PG8_SA(1, 1), a1 + hstepA, voffA);
;             PG8_WAIT_V(8); PG8_WAIT_L(0); PG8_BAR; PG8_MMA(0, 0, At, B0); PG8_MMA(0, 1, At, B1); PG8_BAR; PG8_SCHED;
;             PG8_LDA(At, 0, 1); PG8_STAGE(PG8_SB(0, 0), b2, voffB); PG8_STAGE(PG8_SB(0, 1), b2 + hstepB, voffB); PG8_STAGE(PG8_SA(0, 0), a2, voffA);
;             PG8_WAIT_V(8); PG8_WAIT_L(0); PG8_BAR; PG8_MMA(1, 0, At, B0); PG8_MMA(1, 1, At, B1); PG8_BAR; PG8_SCHED;
.LBB0_1517:
	ds_read_b128 v[116:119], v225
	ds_read_b128 v[128:131], v225 offset:1024
	ds_read_b128 v[132:135], v225 offset:2048
	ds_read_b128 v[136:139], v225 offset:3072
	ds_read_b128 v[140:143], v225 offset:16384
	ds_read_b128 v[144:147], v225 offset:17408
	ds_read_b128 v[148:151], v225 offset:18432
	ds_read_b128 v[152:155], v225 offset:19456
	s_add_u32 s12, s0, 0xfffe0080
	s_addc_u32 s13, s1, -1
	s_cmp_eq_u32 s54, 4
	s_cselect_b32 s17, s37, s13
	s_cselect_b32 s16, s36, s12
	s_cselect_b32 s13, s21, s33
	s_cselect_b32 s12, s24, s27
	v_lshl_add_u64 v[208:209], s[0:1], 0, v[200:201]
	s_add_i32 m0, s31, 0xc000
	ds_read_b128 v[164:167], v224
	ds_read_b128 v[168:171], v224 offset:1024
	ds_read_b128 v[172:175], v224 offset:2048
	ds_read_b128 v[176:179], v224 offset:3072
	ds_read_b128 v[180:183], v224 offset:4096
	ds_read_b128 v[184:187], v224 offset:5120
	ds_read_b128 v[188:191], v224 offset:6144
	ds_read_b128 v[204:207], v224 offset:7168
	global_load_lds_dwordx4 v[208:209], off
	v_lshl_add_u64 v[208:209], s[0:1], 0, v[202:203]
	s_add_i32 m0, s31, 0xe000
	s_nop 0
	global_load_lds_dwordx4 v[208:209], off
	s_waitcnt vmcnt(8)
	s_waitcnt lgkmcnt(0)
	s_barrier
	v_mfma_f32_16x16x32_bf16 v[160:163], v[116:119], v[164:167], v[160:163]
	v_mfma_f32_16x16x32_bf16 v[160:163], v[128:131], v[168:171], v[160:163]
	v_mfma_f32_16x16x32_bf16 v[112:115], v[116:119], v[172:175], v[112:115]
	v_mfma_f32_16x16x32_bf16 v[112:115], v[128:131], v[176:179], v[112:115]
	v_mfma_f32_16x16x32_bf16 v[96:99], v[116:119], v[180:183], v[96:99]
	v_mfma_f32_16x16x32_bf16 v[96:99], v[128:131], v[184:187], v[96:99]
	v_mfma_f32_16x16x32_bf16 v[80:83], v[116:119], v[188:191], v[80:83]
	v_mfma_f32_16x16x32_bf16 v[80:83], v[128:131], v[204:207], v[80:83]
	v_mfma_f32_16x16x32_bf16 v[156:159], v[132:135], v[164:167], v[156:159]
	v_mfma_f32_16x16x32_bf16 v[156:159], v[136:139], v[168:171], v[156:159]
	v_mfma_f32_16x16x32_bf16 v[108:111], v[132:135], v[172:175], v[108:111]
	v_mfma_f32_16x16x32_bf16 v[108:111], v[136:139], v[176:179], v[108:111]
	v_mfma_f32_16x16x32_bf16 v[92:95], v[132:135], v[180:183], v[92:95]
	v_mfma_f32_16x16x32_bf16 v[92:95], v[136:139], v[184:187], v[92:95]
	v_mfma_f32_16x16x32_bf16 v[76:79], v[132:135], v[188:191], v[76:79]
	v_mfma_f32_16x16x32_bf16 v[76:79], v[136:139], v[204:207], v[76:79]
	v_mfma_f32_16x16x32_bf16 v[124:127], v[140:143], v[164:167], v[124:127]
	v_mfma_f32_16x16x32_bf16 v[124:127], v[144:147], v[168:171], v[124:127]
	v_mfma_f32_16x16x32_bf16 v[104:107], v[140:143], v[172:175], v[104:107]
	v_mfma_f32_16x16x32_bf16 v[104:107], v[144:147], v[176:179], v[104:107]
	v_mfma_f32_16x16x32_bf16 v[88:91], v[140:143], v[180:183], v[88:91]
	v_mfma_f32_16x16x32_bf16 v[88:91], v[144:147], v[184:187], v[88:91]
	v_mfma_f32_16x16x32_bf16 v[72:75], v[140:143], v[188:191], v[72:75]
	v_mfma_f32_16x16x32_bf16 v[72:75], v[144:147], v[204:207], v[72:75]
	v_mfma_f32_16x16x32_bf16 v[120:123], v[148:151], v[164:167], v[120:123]
	v_mfma_f32_16x16x32_bf16 v[120:123], v[152:155], v[168:171], v[120:123]
	v_mfma_f32_16x16x32_bf16 v[100:103], v[148:151], v[172:175], v[100:103]
	v_mfma_f32_16x16x32_bf16 v[100:103], v[152:155], v[176:179], v[100:103]
	v_mfma_f32_16x16x32_bf16 v[84:87], v[148:151], v[180:183], v[84:87]
	v_mfma_f32_16x16x32_bf16 v[84:87], v[152:155], v[184:187], v[84:87]
	v_mfma_f32_16x16x32_bf16 v[68:71], v[148:151], v[188:191], v[68:71]
	v_mfma_f32_16x16x32_bf16 v[68:71], v[152:155], v[204:207], v[68:71]
	s_barrier
	s_mov_b32 m0, s34
	v_lshl_add_u64 v[208:209], s[12:13], 0, v[196:197]
	s_add_u32 s56, s12, 0x20000
	ds_read_b128 v[164:167], v224 offset:16384
	ds_read_b128 v[168:171], v224 offset:17408
	ds_read_b128 v[172:175], v224 offset:18432
	ds_read_b128 v[176:179], v224 offset:19456
	ds_read_b128 v[180:183], v224 offset:20480
	ds_read_b128 v[184:187], v224 offset:21504
	ds_read_b128 v[188:191], v224 offset:22528
	ds_read_b128 v[204:207], v224 offset:23552
	global_load_lds_dwordx4 v[208:209], off
	v_lshl_add_u64 v[210:211], s[12:13], 0, v[192:193]
	s_mov_b32 m0, s35
	s_addc_u32 s57, s13, 0
	global_load_lds_dwordx4 v[210:211], off
	v_lshl_add_u64 v[212:213], s[56:57], 0, v[196:197]
	s_mov_b32 m0, s42
	v_lshl_add_u64 v[214:215], s[16:17], 0, v[194:195]
	global_load_lds_dwordx4 v[212:213], off
	v_lshl_add_u64 v[212:213], s[56:57], 0, v[192:193]
	s_mov_b32 m0, s43
	s_nop 0
	global_load_lds_dwordx4 v[212:213], off
	v_lshl_add_u64 v[212:213], s[16:17], 0, v[198:199]
	s_mov_b32 m0, s31
	s_nop 0
	global_load_lds_dwordx4 v[212:213], off
	s_mov_b32 m0, s44
	s_nop 0
	global_load_lds_dwordx4 v[214:215], off
	s_waitcnt vmcnt(8)
	s_waitcnt lgkmcnt(0)
	s_barrier
; #define PG8_STAGE(bufoff, gbase, voff) do { _Pragma("unroll") for (int _i = 0; _i < 2; ++_i) \
;         __builtin_amdgcn_global_load_lds((const unsigned*)((const char*)(gbase) + (voff)[_i]), (LAS unsigned*)(lds + (bufoff) + ldsw + _i * 8192), 16, 0, 0); } while (0)
; #define PG8_LDA(dst, b, h) do { _Pragma("unroll") for (int m = 0; m < 4; ++m) _Pragma("unroll") for (int k = 0; k < 2; ++k) dst[m][k] = *(const LAS bf16x8*)(pA + PG8_SA(b, h) + m * 2048 + k * 1024); } while (0)
; #define PG8_LDB(dst, b, h) do { _Pragma("unroll") for (int n = 0; n < 2; ++n) _Pragma("unroll") for (int k = 0; k < 2; ++k) dst[n][k] = *(const LAS bf16x8*)(pB + (PG8_SB(b, h) - 4 * HTB) + n * 2048 + k * 1024); } while (0)
; #define PG8_MMA(ai, bj, At, Bt) do { __builtin_amdgcn_s_setprio(1); _Pragma("unroll") for (int m = 0; m < 4; ++m) _Pragma("unroll") for (int n = 0; n < 2; ++n) _Pragma("unroll") for (int k = 0; k < 2; ++k) \
;         acc[ai][bj][m][n] = __builtin_amdgcn_mfma_f32_16x16x32_bf16(Bt[n][k], At[m][k], acc[ai][bj][m][n], 0, 0, 0); __builtin_amdgcn_s_setprio(0); } while (0)
; #define PG8_WAIT_V(n) asm volatile("s_waitcnt vmcnt(" #n ")" ::: "memory")
; #define PG8_WAIT_L(n) asm volatile("s_waitcnt lgkmcnt(" #n ")" ::: "memory")
; #define PG8_BAR __builtin_amdgcn_s_barrier()
; #define PG8_SCHED __builtin_amdgcn_sched_barrier(0)
; template <class Desc, class Epi, bool ALIGN_EPI>
; __device__ __forceinline__ void gemm_phase(LAS unsigned char* lds, const Desc& D, const Epi& E, int G, int c) {
;     ...
;             PG8_WAIT_V(8); PG8_WAIT_L(0); PG8_BAR; PG8_MMA(1, 0, At, B0); PG8_MMA(1, 1, At, B1); PG8_BAR; PG8_SCHED;
;             PG8_LDB(B0, 1, 0); PG8_LDB(B1, 1, 1); PG8_SCHED; PG8_LDA(At, 1, 0); PG8_STAGE(PG8_SA(0, 1), a2 + hstepA, voffA);
;             PG8_WAIT_V(8); PG8_WAIT_L(0); PG8_BAR; PG8_MMA(0, 0, At, B0); PG8_MMA(0, 1, At, B1); PG8_BAR; PG8_SCHED;
	v_mfma_f32_16x16x32_bf16 v[64:67], v[116:119], v[164:167], v[64:67]
	v_mfma_f32_16x16x32_bf16 v[64:67], v[128:131], v[168:171], v[64:67]
	v_mfma_f32_16x16x32_bf16 v[48:51], v[116:119], v[172:175], v[48:51]
	v_mfma_f32_16x16x32_bf16 v[48:51], v[128:131], v[176:179], v[48:51]
	v_mfma_f32_16x16x32_bf16 v[32:35], v[116:119], v[180:183], v[32:35]
	v_mfma_f32_16x16x32_bf16 v[32:35], v[128:131], v[184:187], v[32:35]
	v_mfma_f32_16x16x32_bf16 v[16:19], v[116:119], v[188:191], v[16:19]
	v_mfma_f32_16x16x32_bf16 v[16:19], v[128:131], v[204:207], v[16:19]
	v_mfma_f32_16x16x32_bf16 v[60:63], v[132:135], v[164:167], v[60:63]
	v_mfma_f32_16x16x32_bf16 v[60:63], v[136:139], v[168:171], v[60:63]
	v_mfma_f32_16x16x32_bf16 v[44:47], v[132:135], v[172:175], v[44:47]
	v_mfma_f32_16x16x32_bf16 v[44:47], v[136:139], v[176:179], v[44:47]
	v_mfma_f32_16x16x32_bf16 v[28:31], v[132:135], v[180:183], v[28:31]
	v_mfma_f32_16x16x32_bf16 v[28:31], v[136:139], v[184:187], v[28:31]
	v_mfma_f32_16x16x32_bf16 v[12:15], v[132:135], v[188:191], v[12:15]
	v_mfma_f32_16x16x32_bf16 v[12:15], v[136:139], v[204:207], v[12:15]
	v_mfma_f32_16x16x32_bf16 v[56:59], v[140:143], v[164:167], v[56:59]
	v_mfma_f32_16x16x32_bf16 v[56:59], v[144:147], v[168:171], v[56:59]
	v_mfma_f32_16x16x32_bf16 v[40:43], v[140:143], v[172:175], v[40:43]
	v_mfma_f32_16x16x32_bf16 v[40:43], v[144:147], v[176:179], v[40:43]
	v_mfma_f32_16x16x32_bf16 v[24:27], v[140:143], v[180:183], v[24:27]
	v_mfma_f32_16x16x32_bf16 v[24:27], v[144:147], v[184:187], v[24:27]
	v_mfma_f32_16x16x32_bf16 v[8:11], v[140:143], v[188:191], v[8:11]
	v_mfma_f32_16x16x32_bf16 v[8:11], v[144:147], v[204:207], v[8:11]
	v_mfma_f32_16x16x32_bf16 v[52:55], v[148:151], v[164:167], v[52:55]
	v_mfma_f32_16x16x32_bf16 v[52:55], v[152:155], v[168:171], v[52:55]
	v_mfma_f32_16x16x32_bf16 v[36:39], v[148:151], v[172:175], v[36:39]
	v_mfma_f32_16x16x32_bf16 v[36:39], v[152:155], v[176:179], v[36:39]
	v_mfma_f32_16x16x32_bf16 v[20:23], v[148:151], v[180:183], v[20:23]
	v_mfma_f32_16x16x32_bf16 v[20:23], v[152:155], v[184:187], v[20:23]
	v_mfma_f32_16x16x32_bf16 v[4:7], v[148:151], v[188:191], v[4:7]
	v_mfma_f32_16x16x32_bf16 v[4:7], v[152:155], v[204:207], v[4:7]
	s_barrier
	ds_read_b128 v[116:119], v225 offset:32768
	ds_read_b128 v[128:131], v225 offset:33792
	ds_read_b128 v[132:135], v225 offset:34816
	ds_read_b128 v[136:139], v225 offset:35840
	ds_read_b128 v[140:143], v225 offset:49152
	ds_read_b128 v[144:147], v225 offset:50176
	ds_read_b128 v[148:151], v225 offset:51200
	ds_read_b128 v[152:155], v225 offset:52224
	s_add_u32 s16, s16, 0x20000
	s_addc_u32 s17, s17, 0
	s_mov_b32 m0, s45
	v_lshl_add_u64 v[216:217], s[16:17], 0, v[198:199]
	ds_read_b128 v[164:167], v224 offset:32768
	ds_read_b128 v[168:171], v224 offset:33792
	ds_read_b128 v[172:175], v224 offset:34816
	ds_read_b128 v[176:179], v224 offset:35840
	ds_read_b128 v[180:183], v224 offset:36864
	ds_read_b128 v[184:187], v224 offset:37888
	ds_read_b128 v[188:191], v224 offset:38912
	ds_read_b128 v[204:207], v224 offset:39936
	global_load_lds_dwordx4 v[216:217], off
	v_lshl_add_u64 v[216:217], s[16:17], 0, v[194:195]
	s_mov_b32 m0, s46
	s_nop 0
	global_load_lds_dwordx4 v[216:217], off
	s_waitcnt vmcnt(8)
	s_waitcnt lgkmcnt(0)
	s_barrier
	v_mfma_f32_16x16x32_bf16 v[160:163], v[116:119], v[164:167], v[160:163]
	v_mfma_f32_16x16x32_bf16 v[160:163], v[128:131], v[168:171], v[160:163]
	v_mfma_f32_16x16x32_bf16 v[112:115], v[116:119], v[172:175], v[112:115]
	v_mfma_f32_16x16x32_bf16 v[112:115], v[128:131], v[176:179], v[112:115]
	v_mfma_f32_16x16x32_bf16 v[96:99], v[116:119], v[180:183], v[96:99]
	v_mfma_f32_16x16x32_bf16 v[96:99], v[128:131], v[184:187], v[96:99]
	v_mfma_f32_16x16x32_bf16 v[80:83], v[116:119], v[188:191], v[80:83]
	v_mfma_f32_16x16x32_bf16 v[80:83], v[128:131], v[204:207], v[80:83]
	v_mfma_f32_16x16x32_bf16 v[156:159], v[132:135], v[164:167], v[156:159]
	v_mfma_f32_16x16x32_bf16 v[156:159], v[136:139], v[168:171], v[156:159]
	v_mfma_f32_16x16x32_bf16 v[108:111], v[132:135], v[172:175], v[108:111]
	v_mfma_f32_16x16x32_bf16 v[108:111], v[136:139], v[176:179], v[108:111]
	v_mfma_f32_16x16x32_bf16 v[92:95], v[132:135], v[180:183], v[92:95]
	v_mfma_f32_16x16x32_bf16 v[92:95], v[136:139], v[184:187], v[92:95]
	v_mfma_f32_16x16x32_bf16 v[76:79], v[132:135], v[188:191], v[76:79]
	v_mfma_f32_16x16x32_bf16 v[76:79], v[136:139], v[204:207], v[76:79]
	v_mfma_f32_16x16x32_bf16 v[124:127], v[140:143], v[164:167], v[124:127]
	v_mfma_f32_16x16x32_bf16 v[124:127], v[144:147], v[168:171], v[124:127]
	v_mfma_f32_16x16x32_bf16 v[104:107], v[140:143], v[172:175], v[104:107]
	v_mfma_f32_16x16x32_bf16 v[104:107], v[144:147], v[176:179], v[104:107]
	v_mfma_f32_16x16x32_bf16 v[88:91], v[140:143], v[180:183], v[88:91]
	v_mfma_f32_16x16x32_bf16 v[88:91], v[144:147], v[184:187], v[88:91]
	v_mfma_f32_16x16x32_bf16 v[72:75], v[140:143], v[188:191], v[72:75]
	v_mfma_f32_16x16x32_bf16 v[72:75], v[144:147], v[204:207], v[72:75]
	v_mfma_f32_16x16x32_bf16 v[120:123], v[148:151], v[164:167], v[120:123]
	v_mfma_f32_16x16x32_bf16 v[120:123], v[152:155], v[168:171], v[120:123]
	v_mfma_f32_16x16x32_bf16 v[100:103], v[148:151], v[172:175], v[100:103]
	v_mfma_f32_16x16x32_bf16 v[100:103], v[152:155], v[176:179], v[100:103]
	v_mfma_f32_16x16x32_bf16 v[84:87], v[148:151], v[180:183], v[84:87]
	v_mfma_f32_16x16x32_bf16 v[84:87], v[152:155], v[184:187], v[84:87]
	v_mfma_f32_16x16x32_bf16 v[68:71], v[148:151], v[188:191], v[68:71]
	v_mfma_f32_16x16x32_bf16 v[68:71], v[152:155], v[204:207], v[68:71]
	s_barrier
; #define PG8_STAGE(bufoff, gbase, voff) do { _Pragma("unroll") for (int _i = 0; _i < 2; ++_i) \
;         __builtin_amdgcn_global_load_lds((const unsigned*)((const char*)(gbase) + (voff)[_i]), (LAS unsigned*)(lds + (bufoff) + ldsw + _i * 8192), 16, 0, 0); } while (0)
; #define PG8_LDA(dst, b, h) do { _Pragma("unroll") for (int m = 0; m < 4; ++m) _Pragma("unroll") for (int k = 0; k < 2; ++k) dst[m][k] = *(const LAS bf16x8*)(pA + PG8_SA(b, h) + m * 2048 + k * 1024); } while (0)
; #define PG8_MMA(ai, bj, At, Bt) do { __builtin_amdgcn_s_setprio(1); _Pragma("unroll") for (int m = 0; m < 4; ++m) _Pragma("unroll") for (int n = 0; n < 2; ++n) _Pragma("unroll") for (int k = 0; k < 2; ++k) \
;         acc[ai][bj][m][n] = __builtin_amdgcn_mfma_f32_16x16x32_bf16(Bt[n][k], At[m][k], acc[ai][bj][m][n], 0, 0, 0); __builtin_amdgcn_s_setprio(0); } while (0)
; #define PG8_WAIT_V(n) asm volatile("s_waitcnt vmcnt(" #n ")" ::: "memory")
; #define PG8_WAIT_L(n) asm volatile("s_waitcnt lgkmcnt(" #n ")" ::: "memory")
; #define PG8_BAR __builtin_amdgcn_s_barrier()
; #define PG8_SCHED __builtin_amdgcn_sched_barrier(0)
; template <class Desc, class Epi, bool ALIGN_EPI>
; __device__ __forceinline__ void gemm_phase(LAS unsigned char* lds, const Desc& D, const Epi& E, int G, int c) {
;     ...
;             PG8_WAIT_V(8); PG8_WAIT_L(0); PG8_BAR; PG8_MMA(0, 0, At, B0); PG8_MMA(0, 1, At, B1); PG8_BAR; PG8_SCHED;
;             PG8_LDA(At, 1, 1); PG8_STAGE(PG8_SB(1, 0), b3, voffB); PG8_STAGE(PG8_SB(1, 1), b3 + hstepB, voffB); PG8_STAGE(PG8_SA(1, 0), a3, voffA);
;             PG8_WAIT_V(8); PG8_WAIT_L(0); PG8_BAR; PG8_MMA(1, 0, At, B0); PG8_MMA(1, 1, At, B1); PG8_BAR; PG8_SCHED;
;         }
;         if constexpr (ALIGN_EPI) { if (wr == 0) PG8_BAR; }
	s_mov_b32 m0, s47
	v_lshl_add_u64 v[208:209], v[208:209], 0, s[76:77]
	s_add_u32 s12, s12, 0x20080
	ds_read_b128 v[164:167], v224 offset:49152
	ds_read_b128 v[168:171], v224 offset:50176
	ds_read_b128 v[172:175], v224 offset:51200
	ds_read_b128 v[176:179], v224 offset:52224
	ds_read_b128 v[180:183], v224 offset:53248
	ds_read_b128 v[184:187], v224 offset:54272
	ds_read_b128 v[188:191], v224 offset:55296
	ds_read_b128 v[204:207], v224 offset:56320
	global_load_lds_dwordx4 v[208:209], off
	v_lshl_add_u64 v[208:209], v[210:211], 0, s[76:77]
	s_mov_b32 m0, s48
	s_addc_u32 s13, s13, 0
	global_load_lds_dwordx4 v[208:209], off
	v_lshl_add_u64 v[208:209], s[12:13], 0, v[196:197]
	s_mov_b32 m0, s51
	s_nop 0
	global_load_lds_dwordx4 v[208:209], off
	v_lshl_add_u64 v[208:209], s[12:13], 0, v[192:193]
	s_mov_b32 m0, s52
	s_nop 0
	global_load_lds_dwordx4 v[208:209], off
	v_lshl_add_u64 v[208:209], v[212:213], 0, s[76:77]
	s_mov_b32 m0, s49
	s_nop 0
	global_load_lds_dwordx4 v[208:209], off
	v_lshl_add_u64 v[208:209], v[214:215], 0, s[76:77]
	s_mov_b32 m0, s50
	s_nop 0
	global_load_lds_dwordx4 v[208:209], off
	s_waitcnt vmcnt(8)
	s_waitcnt lgkmcnt(0)
	s_barrier
	v_mfma_f32_16x16x32_bf16 v[64:67], v[116:119], v[164:167], v[64:67]
	v_mfma_f32_16x16x32_bf16 v[64:67], v[128:131], v[168:171], v[64:67]
	v_mfma_f32_16x16x32_bf16 v[48:51], v[116:119], v[172:175], v[48:51]
	v_mfma_f32_16x16x32_bf16 v[48:51], v[128:131], v[176:179], v[48:51]
	v_mfma_f32_16x16x32_bf16 v[32:35], v[116:119], v[180:183], v[32:35]
	v_mfma_f32_16x16x32_bf16 v[32:35], v[128:131], v[184:187], v[32:35]
	v_mfma_f32_16x16x32_bf16 v[16:19], v[116:119], v[188:191], v[16:19]
	v_mfma_f32_16x16x32_bf16 v[16:19], v[128:131], v[204:207], v[16:19]
	v_mfma_f32_16x16x32_bf16 v[60:63], v[132:135], v[164:167], v[60:63]
	v_mfma_f32_16x16x32_bf16 v[60:63], v[136:139], v[168:171], v[60:63]
	v_mfma_f32_16x16x32_bf16 v[44:47], v[132:135], v[172:175], v[44:47]
	v_mfma_f32_16x16x32_bf16 v[44:47], v[136:139], v[176:179], v[44:47]
	v_mfma_f32_16x16x32_bf16 v[28:31], v[132:135], v[180:183], v[28:31]
	v_mfma_f32_16x16x32_bf16 v[28:31], v[136:139], v[184:187], v[28:31]
	v_mfma_f32_16x16x32_bf16 v[12:15], v[132:135], v[188:191], v[12:15]
	v_mfma_f32_16x16x32_bf16 v[12:15], v[136:139], v[204:207], v[12:15]
	v_mfma_f32_16x16x32_bf16 v[56:59], v[140:143], v[164:167], v[56:59]
	v_mfma_f32_16x16x32_bf16 v[56:59], v[144:147], v[168:171], v[56:59]
	v_mfma_f32_16x16x32_bf16 v[40:43], v[140:143], v[172:175], v[40:43]
	v_mfma_f32_16x16x32_bf16 v[40:43], v[144:147], v[176:179], v[40:43]
	v_mfma_f32_16x16x32_bf16 v[24:27], v[140:143], v[180:183], v[24:27]
	v_mfma_f32_16x16x32_bf16 v[24:27], v[144:147], v[184:187], v[24:27]
	v_mfma_f32_16x16x32_bf16 v[8:11], v[140:143], v[188:191], v[8:11]
	v_mfma_f32_16x16x32_bf16 v[8:11], v[144:147], v[204:207], v[8:11]
	v_mfma_f32_16x16x32_bf16 v[52:55], v[148:151], v[164:167], v[52:55]
	v_mfma_f32_16x16x32_bf16 v[52:55], v[152:155], v[168:171], v[52:55]
	v_mfma_f32_16x16x32_bf16 v[36:39], v[148:151], v[172:175], v[36:39]
	v_mfma_f32_16x16x32_bf16 v[36:39], v[152:155], v[176:179], v[36:39]
	v_mfma_f32_16x16x32_bf16 v[20:23], v[148:151], v[180:183], v[20:23]
	v_mfma_f32_16x16x32_bf16 v[20:23], v[152:155], v[184:187], v[20:23]
	v_mfma_f32_16x16x32_bf16 v[4:7], v[148:151], v[188:191], v[4:7]
	v_mfma_f32_16x16x32_bf16 v[4:7], v[152:155], v[204:207], v[4:7]
	s_barrier
	s_add_i32 s54, s54, 2
	s_add_u32 s0, s0, 0x100
	s_addc_u32 s1, s1, 0
	s_add_u32 s27, s27, 0x100
	s_addc_u32 s33, s33, 0
	s_cmp_gt_u32 s54, 5
	s_cbranch_scc0 .LBB0_1517
	s_and_b64 vcc, exec, s[10:11]
	s_cbranch_vccz .LBB0_1520
	s_barrier

;     __device__ __forceinline__ int nt(const Unit& u) const { return (u.pn >> 1) < 2 ? 22 : 20; }
; #define PG8_STAGE(bufoff, gbase, voff) do { _Pragma("unroll") for (int _i = 0; _i < 2; ++_i) \
;         __builtin_amdgcn_global_load_lds((const unsigned*)((const char*)(gbase) + (voff)[_i]), (LAS unsigned*)(lds + (bufoff) + ldsw + _i * 8192), 16, 0, 0); } while (0)
; #define PG8_LDA(dst, b, h) do { _Pragma("unroll") for (int m = 0; m < 4; ++m) _Pragma("unroll") for (int k = 0; k < 2; ++k) dst[m][k] = *(const LAS bf16x8*)(pA + PG8_SA(b, h) + m * 2048 + k * 1024); } while (0)
; #define PG8_LDB(dst, b, h) do { _Pragma("unroll") for (int n = 0; n < 2; ++n) _Pragma("unroll") for (int k = 0; k < 2; ++k) dst[n][k] = *(const LAS bf16x8*)(pB + (PG8_SB(b, h) - 4 * HTB) + n * 2048 + k * 1024); } while (0)
; #define PG8_MMA(ai, bj, At, Bt) do { __builtin_amdgcn_s_setprio(1); _Pragma("unroll") for (int m = 0; m < 4; ++m) _Pragma("unroll") for (int n = 0; n < 2; ++n) _Pragma("unroll") for (int k = 0; k < 2; ++k) \
;         acc[ai][bj][m][n] = __builtin_amdgcn_mfma_f32_16x16x32_bf16(Bt[n][k], At[m][k], acc[ai][bj][m][n], 0, 0, 0); __builtin_amdgcn_s_setprio(0); } while (0)
; #define PG8_WAIT_V(n) asm volatile("s_waitcnt vmcnt(" #n ")" ::: "memory")
; #define PG8_BAR __builtin_amdgcn_s_barrier()
; template <class Desc, class Epi, bool ALIGN_EPI>
; __device__ __forceinline__ void gemm_phase(LAS unsigned char* lds, const Desc& D, const Epi& E, int G, int c) {
;     ...
;         for (int t = 0; t < nt; t += 2) {
;             const bool last = (t == nt - 2);
;             if (last && has_next) PG8_AWAIT(nxt);
;             const char* a1 = cA + (size_t)(t + 1) * kstep;
;             const char* a2 = last ? nA : cA + (size_t)(t + 2) * kstep; const char* b2 = last ? nB : cB + (size_t)(t + 2) * kstep;
;             const char* a3 = a2 + kstep; const char* b3 = b2 + kstep;
;             PG8_LDB(B0, 0, 0); PG8_LDB(B1, 0, 1); PG8_SCHED; PG8_LDA(At, 0, 0); PG8_STAGE(PG8_SA(1, 1), a1 + hstepA, voffA);
;             PG8_WAIT_V(8); PG8_WAIT_L(0); PG8_BAR; PG8_MMA(0, 0, At, B0); PG8_MMA(0, 1, At, B1); PG8_BAR; PG8_SCHED;
;             PG8_LDA(At, 0, 1); PG8_STAGE(PG8_SB(0, 0), b2, voffB); PG8_STAGE(PG8_SB(0, 1), b2 + hstepB, voffB); PG8_STAGE(PG8_SA(0, 0), a2, voffA);
;             PG8_WAIT_V(8); PG8_WAIT_L(0); PG8_BAR; PG8_MMA(1, 0, At, B0); PG8_MMA(1, 1, At, B1); PG8_BAR; PG8_SCHED;
.LBB0_1580:
	s_or_b32 s14, s30, 1
	s_add_i32 s30, s30, 2
	s_mov_b32 s31, s15
	s_lshl_b64 s[72:73], s[14:15], 7
	s_lshl_b64 s[74:75], s[30:31], 7
	s_add_u32 s14, s18, s74
	ds_read_b128 v[140:143], v163
	ds_read_b128 v[144:147], v163 offset:1024
	ds_read_b128 v[148:151], v163 offset:2048
	ds_read_b128 v[152:155], v163 offset:3072
	ds_read_b128 v[156:159], v163 offset:16384
	ds_read_b128 v[166:169], v163 offset:17408
	ds_read_b128 v[170:173], v163 offset:18432
	ds_read_b128 v[174:177], v163 offset:19456
	s_addc_u32 s31, s19, s75
	s_and_b64 s[46:47], s[34:35], exec
	s_cselect_b32 s47, s43, s31
	s_cselect_b32 s46, s42, s14
	s_add_u32 s14, s20, s74
	s_addc_u32 s31, s21, s75
	s_and_b64 s[34:35], s[34:35], exec
	s_cselect_b32 s35, s3, s31
	s_cselect_b32 s34, s13, s14
	s_add_u32 s14, s18, s72
	s_addc_u32 s31, s19, s73
	s_add_u32 s72, s14, 0x100000
	s_addc_u32 s73, s31, 0
	s_add_i32 m0, s52, 0xc000
	ds_read_b128 v[178:181], v162
	ds_read_b128 v[182:185], v162 offset:1024
	ds_read_b128 v[186:189], v162 offset:2048
	ds_read_b128 v[190:193], v162 offset:3072
	ds_read_b128 v[194:197], v162 offset:4096
	ds_read_b128 v[198:201], v162 offset:5120
	ds_read_b128 v[202:205], v162 offset:6144
	ds_read_b128 v[206:209], v162 offset:7168
	global_load_lds_dwordx4 v132, s[72:73]
	s_add_i32 m0, s52, 0xe000
	s_nop 0
	global_load_lds_dwordx4 v136, s[72:73]
	s_waitcnt vmcnt(8)
	s_waitcnt lgkmcnt(0)
	s_barrier
	v_mfma_f32_16x16x32_bf16 v[128:131], v[140:143], v[178:181], v[128:131]
	v_mfma_f32_16x16x32_bf16 v[128:131], v[144:147], v[182:185], v[128:131]
	v_mfma_f32_16x16x32_bf16 v[120:123], v[140:143], v[186:189], v[120:123]
	v_mfma_f32_16x16x32_bf16 v[120:123], v[144:147], v[190:193], v[120:123]
	v_mfma_f32_16x16x32_bf16 v[112:115], v[140:143], v[194:197], v[112:115]
	v_mfma_f32_16x16x32_bf16 v[112:115], v[144:147], v[198:201], v[112:115]
	v_mfma_f32_16x16x32_bf16 v[104:107], v[140:143], v[202:205], v[104:107]
	v_mfma_f32_16x16x32_bf16 v[104:107], v[144:147], v[206:209], v[104:107]
	v_mfma_f32_16x16x32_bf16 v[124:127], v[148:151], v[178:181], v[124:127]
	v_mfma_f32_16x16x32_bf16 v[124:127], v[152:155], v[182:185], v[124:127]
	v_mfma_f32_16x16x32_bf16 v[116:119], v[148:151], v[186:189], v[116:119]
	v_mfma_f32_16x16x32_bf16 v[116:119], v[152:155], v[190:193], v[116:119]
	v_mfma_f32_16x16x32_bf16 v[108:111], v[148:151], v[194:197], v[108:111]
	v_mfma_f32_16x16x32_bf16 v[108:111], v[152:155], v[198:201], v[108:111]
	v_mfma_f32_16x16x32_bf16 v[100:103], v[148:151], v[202:205], v[100:103]
	v_mfma_f32_16x16x32_bf16 v[100:103], v[152:155], v[206:209], v[100:103]
	v_mfma_f32_16x16x32_bf16 v[96:99], v[156:159], v[178:181], v[96:99]
	v_mfma_f32_16x16x32_bf16 v[96:99], v[166:169], v[182:185], v[96:99]
	v_mfma_f32_16x16x32_bf16 v[88:91], v[156:159], v[186:189], v[88:91]
	v_mfma_f32_16x16x32_bf16 v[88:91], v[166:169], v[190:193], v[88:91]
	v_mfma_f32_16x16x32_bf16 v[80:83], v[156:159], v[194:197], v[80:83]
	v_mfma_f32_16x16x32_bf16 v[80:83], v[166:169], v[198:201], v[80:83]
	v_mfma_f32_16x16x32_bf16 v[72:75], v[156:159], v[202:205], v[72:75]
	v_mfma_f32_16x16x32_bf16 v[72:75], v[166:169], v[206:209], v[72:75]
	v_mfma_f32_16x16x32_bf16 v[92:95], v[170:173], v[178:181], v[92:95]
	v_mfma_f32_16x16x32_bf16 v[92:95], v[174:177], v[182:185], v[92:95]
	v_mfma_f32_16x16x32_bf16 v[84:87], v[170:173], v[186:189], v[84:87]
	v_mfma_f32_16x16x32_bf16 v[84:87], v[174:177], v[190:193], v[84:87]
	v_mfma_f32_16x16x32_bf16 v[76:79], v[170:173], v[194:197], v[76:79]
	v_mfma_f32_16x16x32_bf16 v[76:79], v[174:177], v[198:201], v[76:79]
	v_mfma_f32_16x16x32_bf16 v[68:71], v[170:173], v[202:205], v[68:71]
	v_mfma_f32_16x16x32_bf16 v[68:71], v[174:177], v[206:209], v[68:71]
	s_barrier
	s_mov_b32 m0, s53
	s_add_u32 s72, s34, 0x100000
	s_addc_u32 s73, s35, 0
	ds_read_b128 v[178:181], v162 offset:16384
	ds_read_b128 v[182:185], v162 offset:17408
	ds_read_b128 v[186:189], v162 offset:18432
	ds_read_b128 v[190:193], v162 offset:19456
	ds_read_b128 v[194:197], v162 offset:20480
	ds_read_b128 v[198:201], v162 offset:21504
	ds_read_b128 v[202:205], v162 offset:22528
	ds_read_b128 v[206:209], v162 offset:23552
	global_load_lds_dwordx4 v134, s[34:35]
	s_mov_b32 m0, s54
	s_nop 0
	global_load_lds_dwordx4 v138, s[34:35]
	s_mov_b32 m0, s55
	s_nop 0
	global_load_lds_dwordx4 v134, s[72:73]
	s_mov_b32 m0, s56
	s_nop 0
	global_load_lds_dwordx4 v138, s[72:73]
	s_mov_b32 m0, s52
	s_nop 0
	global_load_lds_dwordx4 v132, s[46:47]
	s_mov_b32 m0, s57
	s_nop 0
	global_load_lds_dwordx4 v136, s[46:47]
	s_waitcnt vmcnt(8)
	s_waitcnt lgkmcnt(0)
	s_barrier
; #define PG8_STAGE(bufoff, gbase, voff) do { _Pragma("unroll") for (int _i = 0; _i < 2; ++_i) \
;         __builtin_amdgcn_global_load_lds((const unsigned*)((const char*)(gbase) + (voff)[_i]), (LAS unsigned*)(lds + (bufoff) + ldsw + _i * 8192), 16, 0, 0); } while (0)
; #define PG8_LDA(dst, b, h) do { _Pragma("unroll") for (int m = 0; m < 4; ++m) _Pragma("unroll") for (int k = 0; k < 2; ++k) dst[m][k] = *(const LAS bf16x8*)(pA + PG8_SA(b, h) + m * 2048 + k * 1024); } while (0)
; #define PG8_LDB(dst, b, h) do { _Pragma("unroll") for (int n = 0; n < 2; ++n) _Pragma("unroll") for (int k = 0; k < 2; ++k) dst[n][k] = *(const LAS bf16x8*)(pB + (PG8_SB(b, h) - 4 * HTB) + n * 2048 + k * 1024); } while (0)
; #define PG8_MMA(ai, bj, At, Bt) do { __builtin_amdgcn_s_setprio(1); _Pragma("unroll") for (int m = 0; m < 4; ++m) _Pragma("unroll") for (int n = 0; n < 2; ++n) _Pragma("unroll") for (int k = 0; k < 2; ++k) \
;         acc[ai][bj][m][n] = __builtin_amdgcn_mfma_f32_16x16x32_bf16(Bt[n][k], At[m][k], acc[ai][bj][m][n], 0, 0, 0); __builtin_amdgcn_s_setprio(0); } while (0)
; #define PG8_WAIT_V(n) asm volatile("s_waitcnt vmcnt(" #n ")" ::: "memory")
; #define PG8_WAIT_L(n) asm volatile("s_waitcnt lgkmcnt(" #n ")" ::: "memory")
; #define PG8_BAR __builtin_amdgcn_s_barrier()
; #define PG8_SCHED __builtin_amdgcn_sched_barrier(0)
; template <class Desc, class Epi, bool ALIGN_EPI>
; __device__ __forceinline__ void gemm_phase(LAS unsigned char* lds, const Desc& D, const Epi& E, int G, int c) {
;     ...
;             PG8_WAIT_V(8); PG8_WAIT_L(0); PG8_BAR; PG8_MMA(1, 0, At, B0); PG8_MMA(1, 1, At, B1); PG8_BAR; PG8_SCHED;
;             PG8_LDB(B0, 1, 0); PG8_LDB(B1, 1, 1); PG8_SCHED; PG8_LDA(At, 1, 0); PG8_STAGE(PG8_SA(0, 1), a2 + hstepA, voffA);
;             PG8_WAIT_V(8); PG8_WAIT_L(0); PG8_BAR; PG8_MMA(0, 0, At, B0); PG8_MMA(0, 1, At, B1); PG8_BAR; PG8_SCHED;
	v_mfma_f32_16x16x32_bf16 v[64:67], v[140:143], v[178:181], v[64:67]
	v_mfma_f32_16x16x32_bf16 v[64:67], v[144:147], v[182:185], v[64:67]
	v_mfma_f32_16x16x32_bf16 v[32:35], v[140:143], v[186:189], v[32:35]
	v_mfma_f32_16x16x32_bf16 v[32:35], v[144:147], v[190:193], v[32:35]
	v_mfma_f32_16x16x32_bf16 v[16:19], v[140:143], v[194:197], v[16:19]
	v_mfma_f32_16x16x32_bf16 v[16:19], v[144:147], v[198:201], v[16:19]
	v_mfma_f32_16x16x32_bf16 v[8:11], v[140:143], v[202:205], v[8:11]
	v_mfma_f32_16x16x32_bf16 v[8:11], v[144:147], v[206:209], v[8:11]
	v_mfma_f32_16x16x32_bf16 v[52:55], v[148:151], v[178:181], v[52:55]
	v_mfma_f32_16x16x32_bf16 v[52:55], v[152:155], v[182:185], v[52:55]
	v_mfma_f32_16x16x32_bf16 v[20:23], v[148:151], v[186:189], v[20:23]
	v_mfma_f32_16x16x32_bf16 v[20:23], v[152:155], v[190:193], v[20:23]
	v_mfma_f32_16x16x32_bf16 v[12:15], v[148:151], v[194:197], v[12:15]
	v_mfma_f32_16x16x32_bf16 v[12:15], v[152:155], v[198:201], v[12:15]
	v_mfma_f32_16x16x32_bf16 v[4:7], v[148:151], v[202:205], v[4:7]
	v_mfma_f32_16x16x32_bf16 v[4:7], v[152:155], v[206:209], v[4:7]
	v_mfma_f32_16x16x32_bf16 v[60:63], v[156:159], v[178:181], v[60:63]
	v_mfma_f32_16x16x32_bf16 v[60:63], v[166:169], v[182:185], v[60:63]
	v_mfma_f32_16x16x32_bf16 v[48:51], v[156:159], v[186:189], v[48:51]
	v_mfma_f32_16x16x32_bf16 v[48:51], v[166:169], v[190:193], v[48:51]
	v_mfma_f32_16x16x32_bf16 v[40:43], v[156:159], v[194:197], v[40:43]
	v_mfma_f32_16x16x32_bf16 v[40:43], v[166:169], v[198:201], v[40:43]
	v_mfma_f32_16x16x32_bf16 v[28:31], v[156:159], v[202:205], v[28:31]
	v_mfma_f32_16x16x32_bf16 v[28:31], v[166:169], v[206:209], v[28:31]
	v_mfma_f32_16x16x32_bf16 v[56:59], v[170:173], v[178:181], v[56:59]
	v_mfma_f32_16x16x32_bf16 v[56:59], v[174:177], v[182:185], v[56:59]
	v_mfma_f32_16x16x32_bf16 v[44:47], v[170:173], v[186:189], v[44:47]
	v_mfma_f32_16x16x32_bf16 v[44:47], v[174:177], v[190:193], v[44:47]
	v_mfma_f32_16x16x32_bf16 v[36:39], v[170:173], v[194:197], v[36:39]
	v_mfma_f32_16x16x32_bf16 v[36:39], v[174:177], v[198:201], v[36:39]
	v_mfma_f32_16x16x32_bf16 v[24:27], v[170:173], v[202:205], v[24:27]
	v_mfma_f32_16x16x32_bf16 v[24:27], v[174:177], v[206:209], v[24:27]
	s_barrier
	ds_read_b128 v[140:143], v163 offset:32768
	ds_read_b128 v[144:147], v163 offset:33792
	ds_read_b128 v[148:151], v163 offset:34816
	ds_read_b128 v[152:155], v163 offset:35840
	ds_read_b128 v[156:159], v163 offset:49152
	ds_read_b128 v[166:169], v163 offset:50176
	ds_read_b128 v[170:173], v163 offset:51200
	ds_read_b128 v[174:177], v163 offset:52224
	s_add_u32 s46, s46, 0x100000
	s_addc_u32 s47, s47, 0
	s_mov_b32 m0, s58
	ds_read_b128 v[178:181], v162 offset:32768
	ds_read_b128 v[182:185], v162 offset:33792
	ds_read_b128 v[186:189], v162 offset:34816
	ds_read_b128 v[190:193], v162 offset:35840
	ds_read_b128 v[194:197], v162 offset:36864
	ds_read_b128 v[198:201], v162 offset:37888
	ds_read_b128 v[202:205], v162 offset:38912
	ds_read_b128 v[206:209], v162 offset:39936
	global_load_lds_dwordx4 v132, s[46:47]
	s_mov_b32 m0, s59
	s_nop 0
	global_load_lds_dwordx4 v136, s[46:47]
	s_waitcnt vmcnt(8)
	s_waitcnt lgkmcnt(0)
	s_barrier
	v_mfma_f32_16x16x32_bf16 v[128:131], v[140:143], v[178:181], v[128:131]
	v_mfma_f32_16x16x32_bf16 v[128:131], v[144:147], v[182:185], v[128:131]
	v_mfma_f32_16x16x32_bf16 v[120:123], v[140:143], v[186:189], v[120:123]
	v_mfma_f32_16x16x32_bf16 v[120:123], v[144:147], v[190:193], v[120:123]
	v_mfma_f32_16x16x32_bf16 v[112:115], v[140:143], v[194:197], v[112:115]
	v_mfma_f32_16x16x32_bf16 v[112:115], v[144:147], v[198:201], v[112:115]
	v_mfma_f32_16x16x32_bf16 v[104:107], v[140:143], v[202:205], v[104:107]
	v_mfma_f32_16x16x32_bf16 v[104:107], v[144:147], v[206:209], v[104:107]
	v_mfma_f32_16x16x32_bf16 v[124:127], v[148:151], v[178:181], v[124:127]
	v_mfma_f32_16x16x32_bf16 v[124:127], v[152:155], v[182:185], v[124:127]
	v_mfma_f32_16x16x32_bf16 v[116:119], v[148:151], v[186:189], v[116:119]
	v_mfma_f32_16x16x32_bf16 v[116:119], v[152:155], v[190:193], v[116:119]
	v_mfma_f32_16x16x32_bf16 v[108:111], v[148:151], v[194:197], v[108:111]
	v_mfma_f32_16x16x32_bf16 v[108:111], v[152:155], v[198:201], v[108:111]
	v_mfma_f32_16x16x32_bf16 v[100:103], v[148:151], v[202:205], v[100:103]
	v_mfma_f32_16x16x32_bf16 v[100:103], v[152:155], v[206:209], v[100:103]
	v_mfma_f32_16x16x32_bf16 v[96:99], v[156:159], v[178:181], v[96:99]
	v_mfma_f32_16x16x32_bf16 v[96:99], v[166:169], v[182:185], v[96:99]
	v_mfma_f32_16x16x32_bf16 v[88:91], v[156:159], v[186:189], v[88:91]
	v_mfma_f32_16x16x32_bf16 v[88:91], v[166:169], v[190:193], v[88:91]
	v_mfma_f32_16x16x32_bf16 v[80:83], v[156:159], v[194:197], v[80:83]
	v_mfma_f32_16x16x32_bf16 v[80:83], v[166:169], v[198:201], v[80:83]
	v_mfma_f32_16x16x32_bf16 v[72:75], v[156:159], v[202:205], v[72:75]
	v_mfma_f32_16x16x32_bf16 v[72:75], v[166:169], v[206:209], v[72:75]
	v_mfma_f32_16x16x32_bf16 v[92:95], v[170:173], v[178:181], v[92:95]
	v_mfma_f32_16x16x32_bf16 v[92:95], v[174:177], v[182:185], v[92:95]
	v_mfma_f32_16x16x32_bf16 v[84:87], v[170:173], v[186:189], v[84:87]
	v_mfma_f32_16x16x32_bf16 v[84:87], v[174:177], v[190:193], v[84:87]
	v_mfma_f32_16x16x32_bf16 v[76:79], v[170:173], v[194:197], v[76:79]
	v_mfma_f32_16x16x32_bf16 v[76:79], v[174:177], v[198:201], v[76:79]
	v_mfma_f32_16x16x32_bf16 v[68:71], v[170:173], v[202:205], v[68:71]
	v_mfma_f32_16x16x32_bf16 v[68:71], v[174:177], v[206:209], v[68:71]
	s_barrier
; #define PG8_STAGE(bufoff, gbase, voff) do { _Pragma("unroll") for (int _i = 0; _i < 2; ++_i) \
;         __builtin_amdgcn_global_load_lds((const unsigned*)((const char*)(gbase) + (voff)[_i]), (LAS unsigned*)(lds + (bufoff) + ldsw + _i * 8192), 16, 0, 0); } while (0)
; #define PG8_LDA(dst, b, h) do { _Pragma("unroll") for (int m = 0; m < 4; ++m) _Pragma("unroll") for (int k = 0; k < 2; ++k) dst[m][k] = *(const LAS bf16x8*)(pA + PG8_SA(b, h) + m * 2048 + k * 1024); } while (0)
; #define PG8_MMA(ai, bj, At, Bt) do { __builtin_amdgcn_s_setprio(1); _Pragma("unroll") for (int m = 0; m < 4; ++m) _Pragma("unroll") for (int n = 0; n < 2; ++n) _Pragma("unroll") for (int k = 0; k < 2; ++k) \
;         acc[ai][bj][m][n] = __builtin_amdgcn_mfma_f32_16x16x32_bf16(Bt[n][k], At[m][k], acc[ai][bj][m][n], 0, 0, 0); __builtin_amdgcn_s_setprio(0); } while (0)
; #define PG8_WAIT_V(n) asm volatile("s_waitcnt vmcnt(" #n ")" ::: "memory")
; #define PG8_WAIT_L(n) asm volatile("s_waitcnt lgkmcnt(" #n ")" ::: "memory")
; #define PG8_BAR __builtin_amdgcn_s_barrier()
; #define PG8_SCHED __builtin_amdgcn_sched_barrier(0)
; template <class Desc, class Epi, bool ALIGN_EPI>
; __device__ __forceinline__ void gemm_phase(LAS unsigned char* lds, const Desc& D, const Epi& E, int G, int c) {
;     ...
;             PG8_WAIT_V(8); PG8_WAIT_L(0); PG8_BAR; PG8_MMA(0, 0, At, B0); PG8_MMA(0, 1, At, B1); PG8_BAR; PG8_SCHED;
;             PG8_LDA(At, 1, 1); PG8_STAGE(PG8_SB(1, 0), b3, voffB); PG8_STAGE(PG8_SB(1, 1), b3 + hstepB, voffB); PG8_STAGE(PG8_SA(1, 0), a3, voffA);
;             PG8_WAIT_V(8); PG8_WAIT_L(0); PG8_BAR; PG8_MMA(1, 0, At, B0); PG8_MMA(1, 1, At, B1); PG8_BAR; PG8_SCHED;
;         }
	s_mov_b32 m0, s61
	s_add_u32 s74, s34, 0x80
	s_addc_u32 s75, s35, 0
	s_add_u32 s34, s34, 0x100080
	s_addc_u32 s35, s35, 0
	ds_read_b128 v[178:181], v162 offset:49152
	ds_read_b128 v[182:185], v162 offset:50176
	ds_read_b128 v[186:189], v162 offset:51200
	ds_read_b128 v[190:193], v162 offset:52224
	ds_read_b128 v[194:197], v162 offset:53248
	ds_read_b128 v[198:201], v162 offset:54272
	ds_read_b128 v[202:205], v162 offset:55296
	ds_read_b128 v[206:209], v162 offset:56320
	global_load_lds_dwordx4 v134, s[74:75]
	s_mov_b32 m0, s62
	s_nop 0
	global_load_lds_dwordx4 v138, s[74:75]
	s_mov_b32 m0, s65
	s_nop 0
	global_load_lds_dwordx4 v134, s[34:35]
	s_mov_b32 m0, s67
	s_nop 0
	global_load_lds_dwordx4 v138, s[34:35]
	s_sub_u32 s74, s46, 0xfff80
	s_subb_u32 s75, s47, 0
	s_mov_b32 m0, s63
	s_nop 0
	global_load_lds_dwordx4 v132, s[74:75]
	s_mov_b32 m0, s64
	s_nop 0
	global_load_lds_dwordx4 v136, s[74:75]
	s_waitcnt vmcnt(8)
	s_waitcnt lgkmcnt(0)
	s_barrier
	v_mfma_f32_16x16x32_bf16 v[64:67], v[140:143], v[178:181], v[64:67]
	v_mfma_f32_16x16x32_bf16 v[64:67], v[144:147], v[182:185], v[64:67]
	v_mfma_f32_16x16x32_bf16 v[32:35], v[140:143], v[186:189], v[32:35]
	v_mfma_f32_16x16x32_bf16 v[32:35], v[144:147], v[190:193], v[32:35]
	v_mfma_f32_16x16x32_bf16 v[16:19], v[140:143], v[194:197], v[16:19]
	v_mfma_f32_16x16x32_bf16 v[16:19], v[144:147], v[198:201], v[16:19]
	v_mfma_f32_16x16x32_bf16 v[8:11], v[140:143], v[202:205], v[8:11]
	v_mfma_f32_16x16x32_bf16 v[8:11], v[144:147], v[206:209], v[8:11]
	v_mfma_f32_16x16x32_bf16 v[52:55], v[148:151], v[178:181], v[52:55]
	v_mfma_f32_16x16x32_bf16 v[52:55], v[152:155], v[182:185], v[52:55]
	v_mfma_f32_16x16x32_bf16 v[20:23], v[148:151], v[186:189], v[20:23]
	v_mfma_f32_16x16x32_bf16 v[20:23], v[152:155], v[190:193], v[20:23]
	v_mfma_f32_16x16x32_bf16 v[12:15], v[148:151], v[194:197], v[12:15]
	v_mfma_f32_16x16x32_bf16 v[12:15], v[152:155], v[198:201], v[12:15]
	v_mfma_f32_16x16x32_bf16 v[4:7], v[148:151], v[202:205], v[4:7]
	v_mfma_f32_16x16x32_bf16 v[4:7], v[152:155], v[206:209], v[4:7]
	v_mfma_f32_16x16x32_bf16 v[60:63], v[156:159], v[178:181], v[60:63]
	v_mfma_f32_16x16x32_bf16 v[60:63], v[166:169], v[182:185], v[60:63]
	v_mfma_f32_16x16x32_bf16 v[48:51], v[156:159], v[186:189], v[48:51]
	v_mfma_f32_16x16x32_bf16 v[48:51], v[166:169], v[190:193], v[48:51]
	v_mfma_f32_16x16x32_bf16 v[40:43], v[156:159], v[194:197], v[40:43]
	v_mfma_f32_16x16x32_bf16 v[40:43], v[166:169], v[198:201], v[40:43]
	v_mfma_f32_16x16x32_bf16 v[28:31], v[156:159], v[202:205], v[28:31]
	v_mfma_f32_16x16x32_bf16 v[28:31], v[166:169], v[206:209], v[28:31]
	v_mfma_f32_16x16x32_bf16 v[56:59], v[170:173], v[178:181], v[56:59]
	v_mfma_f32_16x16x32_bf16 v[56:59], v[174:177], v[182:185], v[56:59]
	v_mfma_f32_16x16x32_bf16 v[44:47], v[170:173], v[186:189], v[44:47]
	v_mfma_f32_16x16x32_bf16 v[44:47], v[174:177], v[190:193], v[44:47]
	v_mfma_f32_16x16x32_bf16 v[36:39], v[170:173], v[194:197], v[36:39]
	v_mfma_f32_16x16x32_bf16 v[36:39], v[174:177], v[198:201], v[36:39]
	v_mfma_f32_16x16x32_bf16 v[24:27], v[170:173], v[202:205], v[24:27]
	v_mfma_f32_16x16x32_bf16 v[24:27], v[174:177], v[206:209], v[24:27]
	s_barrier
	s_cmp_ge_u32 s30, s2
	s_cbranch_scc1 .LBB0_1591

;     __device__ __forceinline__ int nt(const Unit& u) const { return (u.pn >> 1) < 2 ? 22 : 20; }
; #define PG8_STAGE(bufoff, gbase, voff) do { _Pragma("unroll") for (int _i = 0; _i < 2; ++_i) \
;         __builtin_amdgcn_global_load_lds((const unsigned*)((const char*)(gbase) + (voff)[_i]), (LAS unsigned*)(lds + (bufoff) + ldsw + _i * 8192), 16, 0, 0); } while (0)
; #define PG8_LDA(dst, b, h) do { _Pragma("unroll") for (int m = 0; m < 4; ++m) _Pragma("unroll") for (int k = 0; k < 2; ++k) dst[m][k] = *(const LAS bf16x8*)(pA + PG8_SA(b, h) + m * 2048 + k * 1024); } while (0)
; #define PG8_LDB(dst, b, h) do { _Pragma("unroll") for (int n = 0; n < 2; ++n) _Pragma("unroll") for (int k = 0; k < 2; ++k) dst[n][k] = *(const LAS bf16x8*)(pB + (PG8_SB(b, h) - 4 * HTB) + n * 2048 + k * 1024); } while (0)
; #define PG8_MMA(ai, bj, At, Bt) do { __builtin_amdgcn_s_setprio(1); _Pragma("unroll") for (int m = 0; m < 4; ++m) _Pragma("unroll") for (int n = 0; n < 2; ++n) _Pragma("unroll") for (int k = 0; k < 2; ++k) \
;         acc[ai][bj][m][n] = __builtin_amdgcn_mfma_f32_16x16x32_bf16(Bt[n][k], At[m][k], acc[ai][bj][m][n], 0, 0, 0); __builtin_amdgcn_s_setprio(0); } while (0)
; #define PG8_WAIT_V(n) asm volatile("s_waitcnt vmcnt(" #n ")" ::: "memory")
; #define PG8_BAR __builtin_amdgcn_s_barrier()
; template <class Desc, class Epi, bool ALIGN_EPI>
; __device__ __forceinline__ void gemm_phase(LAS unsigned char* lds, const Desc& D, const Epi& E, int G, int c) {
;     ...
;         for (int t = 0; t < nt; t += 2) {
;             const bool last = (t == nt - 2);
;             if (last && has_next) PG8_AWAIT(nxt);
;             const char* a1 = cA + (size_t)(t + 1) * kstep;
;             const char* a2 = last ? nA : cA + (size_t)(t + 2) * kstep; const char* b2 = last ? nB : cB + (size_t)(t + 2) * kstep;
;             const char* a3 = a2 + kstep; const char* b3 = b2 + kstep;
;             PG8_LDB(B0, 0, 0); PG8_LDB(B1, 0, 1); PG8_SCHED; PG8_LDA(At, 0, 0); PG8_STAGE(PG8_SA(1, 1), a1 + hstepA, voffA);
;             PG8_WAIT_V(8); PG8_WAIT_L(0); PG8_BAR; PG8_MMA(0, 0, At, B0); PG8_MMA(0, 1, At, B1); PG8_BAR; PG8_SCHED;
;             PG8_LDA(At, 0, 1); PG8_STAGE(PG8_SB(0, 0), b2, voffB); PG8_STAGE(PG8_SB(0, 1), b2 + hstepB, voffB); PG8_STAGE(PG8_SA(0, 0), a2, voffA);
;             PG8_WAIT_V(8); PG8_WAIT_L(0); PG8_BAR; PG8_MMA(1, 0, At, B0); PG8_MMA(1, 1, At, B1); PG8_BAR; PG8_SCHED;
.LBB0_1765:
	s_or_b32 s14, s39, 1
	s_lshl_b64 s[40:41], s[14:15], 7
	s_add_i32 s14, s39, 2
	s_lshl_b64 s[42:43], s[14:15], 7
	s_add_u32 s39, s12, s42
	s_waitcnt lgkmcnt(0)
	ds_read_b128 v[132:135], v248
	ds_read_b128 v[136:139], v248 offset:1024
	ds_read_b128 v[140:143], v248 offset:2048
	ds_read_b128 v[144:147], v248 offset:3072
	ds_read_b128 v[148:151], v248 offset:16384
	ds_read_b128 v[152:155], v248 offset:17408
	ds_read_b128 v[156:159], v248 offset:18432
	ds_read_b128 v[160:163], v248 offset:19456
	s_addc_u32 s78, s13, s43
	s_and_b64 s[30:31], s[20:21], exec
	s_cselect_b32 s31, s49, s78
	s_cselect_b32 s30, s48, s39
	s_add_u32 s39, s16, s42
	s_addc_u32 s42, s17, s43
	s_and_b64 s[20:21], s[20:21], exec
	s_cselect_b32 s21, s51, s42
	s_cselect_b32 s20, s50, s39
	s_add_u32 s39, s12, s40
	s_addc_u32 s41, s13, s41
	s_add_u32 s40, s39, 0x2b0000
	s_addc_u32 s41, s41, 0
	v_lshl_add_u64 v[196:197], s[40:41], 0, v[200:201]
	s_add_i32 m0, s56, 0xc000
	ds_read_b128 v[164:167], v247
	ds_read_b128 v[168:171], v247 offset:1024
	ds_read_b128 v[172:175], v247 offset:2048
	ds_read_b128 v[176:179], v247 offset:3072
	ds_read_b128 v[180:183], v247 offset:4096
	ds_read_b128 v[184:187], v247 offset:5120
	ds_read_b128 v[188:191], v247 offset:6144
	ds_read_b128 v[192:195], v247 offset:7168
	global_load_lds_dwordx4 v[196:197], off
	v_lshl_add_u64 v[196:197], s[40:41], 0, v[204:205]
	s_add_i32 m0, s56, 0xe000
	s_nop 0
	global_load_lds_dwordx4 v[196:197], off
	s_waitcnt vmcnt(8)
	s_waitcnt lgkmcnt(0)
	s_barrier
	v_mfma_f32_16x16x32_bf16 v[128:131], v[132:135], v[164:167], v[128:131]
	v_mfma_f32_16x16x32_bf16 v[128:131], v[136:139], v[168:171], v[128:131]
	v_mfma_f32_16x16x32_bf16 v[120:123], v[132:135], v[172:175], v[120:123]
	v_mfma_f32_16x16x32_bf16 v[120:123], v[136:139], v[176:179], v[120:123]
	v_mfma_f32_16x16x32_bf16 v[112:115], v[132:135], v[180:183], v[112:115]
	v_mfma_f32_16x16x32_bf16 v[112:115], v[136:139], v[184:187], v[112:115]
	v_mfma_f32_16x16x32_bf16 v[104:107], v[132:135], v[188:191], v[104:107]
	v_mfma_f32_16x16x32_bf16 v[104:107], v[136:139], v[192:195], v[104:107]
	v_mfma_f32_16x16x32_bf16 v[124:127], v[140:143], v[164:167], v[124:127]
	v_mfma_f32_16x16x32_bf16 v[124:127], v[144:147], v[168:171], v[124:127]
	v_mfma_f32_16x16x32_bf16 v[116:119], v[140:143], v[172:175], v[116:119]
	v_mfma_f32_16x16x32_bf16 v[116:119], v[144:147], v[176:179], v[116:119]
	v_mfma_f32_16x16x32_bf16 v[108:111], v[140:143], v[180:183], v[108:111]
	v_mfma_f32_16x16x32_bf16 v[108:111], v[144:147], v[184:187], v[108:111]
	v_mfma_f32_16x16x32_bf16 v[100:103], v[140:143], v[188:191], v[100:103]
	v_mfma_f32_16x16x32_bf16 v[100:103], v[144:147], v[192:195], v[100:103]
	v_mfma_f32_16x16x32_bf16 v[96:99], v[148:151], v[164:167], v[96:99]
	v_mfma_f32_16x16x32_bf16 v[96:99], v[152:155], v[168:171], v[96:99]
	v_mfma_f32_16x16x32_bf16 v[88:91], v[148:151], v[172:175], v[88:91]
	v_mfma_f32_16x16x32_bf16 v[88:91], v[152:155], v[176:179], v[88:91]
	v_mfma_f32_16x16x32_bf16 v[64:67], v[148:151], v[180:183], v[64:67]
	v_mfma_f32_16x16x32_bf16 v[64:67], v[152:155], v[184:187], v[64:67]
	v_mfma_f32_16x16x32_bf16 v[32:35], v[148:151], v[188:191], v[32:35]
	v_mfma_f32_16x16x32_bf16 v[32:35], v[152:155], v[192:195], v[32:35]
	v_mfma_f32_16x16x32_bf16 v[92:95], v[156:159], v[164:167], v[92:95]
	v_mfma_f32_16x16x32_bf16 v[92:95], v[160:163], v[168:171], v[92:95]
	v_mfma_f32_16x16x32_bf16 v[80:83], v[156:159], v[172:175], v[80:83]
	v_mfma_f32_16x16x32_bf16 v[80:83], v[160:163], v[176:179], v[80:83]
	v_mfma_f32_16x16x32_bf16 v[52:55], v[156:159], v[180:183], v[52:55]
	v_mfma_f32_16x16x32_bf16 v[52:55], v[160:163], v[184:187], v[52:55]
	v_mfma_f32_16x16x32_bf16 v[20:23], v[156:159], v[188:191], v[20:23]
	v_mfma_f32_16x16x32_bf16 v[20:23], v[160:163], v[192:195], v[20:23]
	s_barrier
	s_mov_b32 m0, s57
	v_lshl_add_u64 v[196:197], s[20:21], 0, v[202:203]
	s_add_u32 s40, s20, 0x2b0000
	ds_read_b128 v[164:167], v247 offset:16384
	ds_read_b128 v[168:171], v247 offset:17408
	ds_read_b128 v[172:175], v247 offset:18432
	ds_read_b128 v[176:179], v247 offset:19456
	ds_read_b128 v[180:183], v247 offset:20480
	ds_read_b128 v[184:187], v247 offset:21504
	ds_read_b128 v[188:191], v247 offset:22528
	ds_read_b128 v[192:195], v247 offset:23552
	global_load_lds_dwordx4 v[196:197], off
	v_lshl_add_u64 v[198:199], s[20:21], 0, v[206:207]
	s_mov_b32 m0, s58
	s_addc_u32 s41, s21, 0
	global_load_lds_dwordx4 v[198:199], off
	v_lshl_add_u64 v[208:209], s[40:41], 0, v[202:203]
	s_mov_b32 m0, s59
	v_lshl_add_u64 v[210:211], s[30:31], 0, v[204:205]
	global_load_lds_dwordx4 v[208:209], off
	v_lshl_add_u64 v[208:209], s[40:41], 0, v[206:207]
	s_mov_b32 m0, s60
	s_nop 0
	global_load_lds_dwordx4 v[208:209], off
	v_lshl_add_u64 v[208:209], s[30:31], 0, v[200:201]
	s_mov_b32 m0, s56
	s_nop 0
	global_load_lds_dwordx4 v[208:209], off
	s_mov_b32 m0, s61
	s_nop 0
	global_load_lds_dwordx4 v[210:211], off
	s_waitcnt vmcnt(8)
	s_waitcnt lgkmcnt(0)
	s_barrier
; #define PG8_STAGE(bufoff, gbase, voff) do { _Pragma("unroll") for (int _i = 0; _i < 2; ++_i) \
;         __builtin_amdgcn_global_load_lds((const unsigned*)((const char*)(gbase) + (voff)[_i]), (LAS unsigned*)(lds + (bufoff) + ldsw + _i * 8192), 16, 0, 0); } while (0)
; #define PG8_LDA(dst, b, h) do { _Pragma("unroll") for (int m = 0; m < 4; ++m) _Pragma("unroll") for (int k = 0; k < 2; ++k) dst[m][k] = *(const LAS bf16x8*)(pA + PG8_SA(b, h) + m * 2048 + k * 1024); } while (0)
; #define PG8_LDB(dst, b, h) do { _Pragma("unroll") for (int n = 0; n < 2; ++n) _Pragma("unroll") for (int k = 0; k < 2; ++k) dst[n][k] = *(const LAS bf16x8*)(pB + (PG8_SB(b, h) - 4 * HTB) + n * 2048 + k * 1024); } while (0)
; #define PG8_MMA(ai, bj, At, Bt) do { __builtin_amdgcn_s_setprio(1); _Pragma("unroll") for (int m = 0; m < 4; ++m) _Pragma("unroll") for (int n = 0; n < 2; ++n) _Pragma("unroll") for (int k = 0; k < 2; ++k) \
;         acc[ai][bj][m][n] = __builtin_amdgcn_mfma_f32_16x16x32_bf16(Bt[n][k], At[m][k], acc[ai][bj][m][n], 0, 0, 0); __builtin_amdgcn_s_setprio(0); } while (0)
; #define PG8_WAIT_V(n) asm volatile("s_waitcnt vmcnt(" #n ")" ::: "memory")
; #define PG8_WAIT_L(n) asm volatile("s_waitcnt lgkmcnt(" #n ")" ::: "memory")
; #define PG8_BAR __builtin_amdgcn_s_barrier()
; #define PG8_SCHED __builtin_amdgcn_sched_barrier(0)
; template <class Desc, class Epi, bool ALIGN_EPI>
; __device__ __forceinline__ void gemm_phase(LAS unsigned char* lds, const Desc& D, const Epi& E, int G, int c) {
;     ...
;             PG8_WAIT_V(8); PG8_WAIT_L(0); PG8_BAR; PG8_MMA(1, 0, At, B0); PG8_MMA(1, 1, At, B1); PG8_BAR; PG8_SCHED;
;             PG8_LDB(B0, 1, 0); PG8_LDB(B1, 1, 1); PG8_SCHED; PG8_LDA(At, 1, 0); PG8_STAGE(PG8_SA(0, 1), a2 + hstepA, voffA);
;             PG8_WAIT_V(8); PG8_WAIT_L(0); PG8_BAR; PG8_MMA(0, 0, At, B0); PG8_MMA(0, 1, At, B1); PG8_BAR; PG8_SCHED;
	v_mfma_f32_16x16x32_bf16 v[84:87], v[132:135], v[164:167], v[84:87]
	v_mfma_f32_16x16x32_bf16 v[84:87], v[136:139], v[168:171], v[84:87]
	v_mfma_f32_16x16x32_bf16 v[72:75], v[132:135], v[172:175], v[72:75]
	v_mfma_f32_16x16x32_bf16 v[72:75], v[136:139], v[176:179], v[72:75]
	v_mfma_f32_16x16x32_bf16 v[60:63], v[132:135], v[180:183], v[60:63]
	v_mfma_f32_16x16x32_bf16 v[60:63], v[136:139], v[184:187], v[60:63]
	v_mfma_f32_16x16x32_bf16 v[48:51], v[132:135], v[188:191], v[48:51]
	v_mfma_f32_16x16x32_bf16 v[48:51], v[136:139], v[192:195], v[48:51]
	v_mfma_f32_16x16x32_bf16 v[76:79], v[140:143], v[164:167], v[76:79]
	v_mfma_f32_16x16x32_bf16 v[76:79], v[144:147], v[168:171], v[76:79]
	v_mfma_f32_16x16x32_bf16 v[68:71], v[140:143], v[172:175], v[68:71]
	v_mfma_f32_16x16x32_bf16 v[68:71], v[144:147], v[176:179], v[68:71]
	v_mfma_f32_16x16x32_bf16 v[56:59], v[140:143], v[180:183], v[56:59]
	v_mfma_f32_16x16x32_bf16 v[56:59], v[144:147], v[184:187], v[56:59]
	v_mfma_f32_16x16x32_bf16 v[44:47], v[140:143], v[188:191], v[44:47]
	v_mfma_f32_16x16x32_bf16 v[44:47], v[144:147], v[192:195], v[44:47]
	v_mfma_f32_16x16x32_bf16 v[40:43], v[148:151], v[164:167], v[40:43]
	v_mfma_f32_16x16x32_bf16 v[40:43], v[152:155], v[168:171], v[40:43]
	v_mfma_f32_16x16x32_bf16 v[28:31], v[148:151], v[172:175], v[28:31]
	v_mfma_f32_16x16x32_bf16 v[28:31], v[152:155], v[176:179], v[28:31]
	v_mfma_f32_16x16x32_bf16 v[16:19], v[148:151], v[180:183], v[16:19]
	v_mfma_f32_16x16x32_bf16 v[16:19], v[152:155], v[184:187], v[16:19]
	v_mfma_f32_16x16x32_bf16 v[8:11], v[148:151], v[188:191], v[8:11]
	v_mfma_f32_16x16x32_bf16 v[8:11], v[152:155], v[192:195], v[8:11]
	v_mfma_f32_16x16x32_bf16 v[36:39], v[156:159], v[164:167], v[36:39]
	v_mfma_f32_16x16x32_bf16 v[36:39], v[160:163], v[168:171], v[36:39]
	v_mfma_f32_16x16x32_bf16 v[24:27], v[156:159], v[172:175], v[24:27]
	v_mfma_f32_16x16x32_bf16 v[24:27], v[160:163], v[176:179], v[24:27]
	v_mfma_f32_16x16x32_bf16 v[12:15], v[156:159], v[180:183], v[12:15]
	v_mfma_f32_16x16x32_bf16 v[12:15], v[160:163], v[184:187], v[12:15]
	v_mfma_f32_16x16x32_bf16 v[4:7], v[156:159], v[188:191], v[4:7]
	v_mfma_f32_16x16x32_bf16 v[4:7], v[160:163], v[192:195], v[4:7]
	s_barrier
	ds_read_b128 v[132:135], v248 offset:32768
	ds_read_b128 v[136:139], v248 offset:33792
	ds_read_b128 v[140:143], v248 offset:34816
	ds_read_b128 v[144:147], v248 offset:35840
	ds_read_b128 v[148:151], v248 offset:49152
	ds_read_b128 v[152:155], v248 offset:50176
	ds_read_b128 v[156:159], v248 offset:51200
	ds_read_b128 v[160:163], v248 offset:52224
	s_add_u32 s30, s30, 0x2b0000
	s_addc_u32 s31, s31, 0
	s_mov_b32 m0, s62
	v_lshl_add_u64 v[212:213], s[30:31], 0, v[200:201]
	ds_read_b128 v[164:167], v247 offset:32768
	ds_read_b128 v[168:171], v247 offset:33792
	ds_read_b128 v[172:175], v247 offset:34816
	ds_read_b128 v[176:179], v247 offset:35840
	ds_read_b128 v[180:183], v247 offset:36864
	ds_read_b128 v[184:187], v247 offset:37888
	ds_read_b128 v[188:191], v247 offset:38912
	ds_read_b128 v[192:195], v247 offset:39936
	global_load_lds_dwordx4 v[212:213], off
	v_lshl_add_u64 v[212:213], s[30:31], 0, v[204:205]
	s_mov_b32 m0, s63
	s_nop 0
	global_load_lds_dwordx4 v[212:213], off
	s_waitcnt vmcnt(8)
	s_waitcnt lgkmcnt(0)
	s_barrier
	v_mfma_f32_16x16x32_bf16 v[128:131], v[132:135], v[164:167], v[128:131]
	v_mfma_f32_16x16x32_bf16 v[128:131], v[136:139], v[168:171], v[128:131]
	v_mfma_f32_16x16x32_bf16 v[120:123], v[132:135], v[172:175], v[120:123]
	v_mfma_f32_16x16x32_bf16 v[120:123], v[136:139], v[176:179], v[120:123]
	v_mfma_f32_16x16x32_bf16 v[112:115], v[132:135], v[180:183], v[112:115]
	v_mfma_f32_16x16x32_bf16 v[112:115], v[136:139], v[184:187], v[112:115]
	v_mfma_f32_16x16x32_bf16 v[104:107], v[132:135], v[188:191], v[104:107]
	v_mfma_f32_16x16x32_bf16 v[104:107], v[136:139], v[192:195], v[104:107]
	v_mfma_f32_16x16x32_bf16 v[124:127], v[140:143], v[164:167], v[124:127]
	v_mfma_f32_16x16x32_bf16 v[124:127], v[144:147], v[168:171], v[124:127]
	v_mfma_f32_16x16x32_bf16 v[116:119], v[140:143], v[172:175], v[116:119]
	v_mfma_f32_16x16x32_bf16 v[116:119], v[144:147], v[176:179], v[116:119]
	v_mfma_f32_16x16x32_bf16 v[108:111], v[140:143], v[180:183], v[108:111]
	v_mfma_f32_16x16x32_bf16 v[108:111], v[144:147], v[184:187], v[108:111]
	v_mfma_f32_16x16x32_bf16 v[100:103], v[140:143], v[188:191], v[100:103]
	v_mfma_f32_16x16x32_bf16 v[100:103], v[144:147], v[192:195], v[100:103]
	v_mfma_f32_16x16x32_bf16 v[96:99], v[148:151], v[164:167], v[96:99]
	v_mfma_f32_16x16x32_bf16 v[96:99], v[152:155], v[168:171], v[96:99]
	v_mfma_f32_16x16x32_bf16 v[88:91], v[148:151], v[172:175], v[88:91]
	v_mfma_f32_16x16x32_bf16 v[88:91], v[152:155], v[176:179], v[88:91]
	v_mfma_f32_16x16x32_bf16 v[64:67], v[148:151], v[180:183], v[64:67]
	v_mfma_f32_16x16x32_bf16 v[64:67], v[152:155], v[184:187], v[64:67]
	v_mfma_f32_16x16x32_bf16 v[32:35], v[148:151], v[188:191], v[32:35]
	v_mfma_f32_16x16x32_bf16 v[32:35], v[152:155], v[192:195], v[32:35]
	v_mfma_f32_16x16x32_bf16 v[92:95], v[156:159], v[164:167], v[92:95]
	v_mfma_f32_16x16x32_bf16 v[92:95], v[160:163], v[168:171], v[92:95]
	v_mfma_f32_16x16x32_bf16 v[80:83], v[156:159], v[172:175], v[80:83]
	v_mfma_f32_16x16x32_bf16 v[80:83], v[160:163], v[176:179], v[80:83]
	v_mfma_f32_16x16x32_bf16 v[52:55], v[156:159], v[180:183], v[52:55]
	v_mfma_f32_16x16x32_bf16 v[52:55], v[160:163], v[184:187], v[52:55]
	v_mfma_f32_16x16x32_bf16 v[20:23], v[156:159], v[188:191], v[20:23]
	v_mfma_f32_16x16x32_bf16 v[20:23], v[160:163], v[192:195], v[20:23]
	s_barrier
;     __device__ __forceinline__ int nt(const Unit& u) const { return (u.pn >> 1) < 2 ? 22 : 20; }
; #define PG8_STAGE(bufoff, gbase, voff) do { _Pragma("unroll") for (int _i = 0; _i < 2; ++_i) \
;         __builtin_amdgcn_global_load_lds((const unsigned*)((const char*)(gbase) + (voff)[_i]), (LAS unsigned*)(lds + (bufoff) + ldsw + _i * 8192), 16, 0, 0); } while (0)
; #define PG8_LDA(dst, b, h) do { _Pragma("unroll") for (int m = 0; m < 4; ++m) _Pragma("unroll") for (int k = 0; k < 2; ++k) dst[m][k] = *(const LAS bf16x8*)(pA + PG8_SA(b, h) + m * 2048 + k * 1024); } while (0)
; #define PG8_MMA(ai, bj, At, Bt) do { __builtin_amdgcn_s_setprio(1); _Pragma("unroll") for (int m = 0; m < 4; ++m) _Pragma("unroll") for (int n = 0; n < 2; ++n) _Pragma("unroll") for (int k = 0; k < 2; ++k) \
;         acc[ai][bj][m][n] = __builtin_amdgcn_mfma_f32_16x16x32_bf16(Bt[n][k], At[m][k], acc[ai][bj][m][n], 0, 0, 0); __builtin_amdgcn_s_setprio(0); } while (0)
; #define PG8_WAIT_V(n) asm volatile("s_waitcnt vmcnt(" #n ")" ::: "memory")
; #define PG8_WAIT_L(n) asm volatile("s_waitcnt lgkmcnt(" #n ")" ::: "memory")
; #define PG8_BAR __builtin_amdgcn_s_barrier()
; #define PG8_SCHED __builtin_amdgcn_sched_barrier(0)
; template <class Desc, class Epi, bool ALIGN_EPI>
; __device__ __forceinline__ void gemm_phase(LAS unsigned char* lds, const Desc& D, const Epi& E, int G, int c) {
;     ...
;         for (int t = 0; t < nt; t += 2) {
;     ...
;             PG8_LDA(At, 1, 1); PG8_STAGE(PG8_SB(1, 0), b3, voffB); PG8_STAGE(PG8_SB(1, 1), b3 + hstepB, voffB); PG8_STAGE(PG8_SA(1, 0), a3, voffA);
;             PG8_WAIT_V(8); PG8_WAIT_L(0); PG8_BAR; PG8_MMA(1, 0, At, B0); PG8_MMA(1, 1, At, B1); PG8_BAR; PG8_SCHED;
;         }
	s_mov_b32 m0, s64
	v_lshl_add_u64 v[196:197], v[196:197], 0, s[76:77]
	s_add_u32 s20, s20, 0x2b0080
	ds_read_b128 v[164:167], v247 offset:49152
	ds_read_b128 v[168:171], v247 offset:50176
	ds_read_b128 v[172:175], v247 offset:51200
	ds_read_b128 v[176:179], v247 offset:52224
	ds_read_b128 v[180:183], v247 offset:53248
	ds_read_b128 v[184:187], v247 offset:54272
	ds_read_b128 v[188:191], v247 offset:55296
	ds_read_b128 v[192:195], v247 offset:56320
	global_load_lds_dwordx4 v[196:197], off
	v_lshl_add_u64 v[196:197], v[198:199], 0, s[76:77]
	s_mov_b32 m0, s65
	s_addc_u32 s21, s21, 0
	global_load_lds_dwordx4 v[196:197], off
	v_lshl_add_u64 v[196:197], s[20:21], 0, v[202:203]
	s_mov_b32 m0, s69
	s_nop 0
	global_load_lds_dwordx4 v[196:197], off
	v_lshl_add_u64 v[196:197], s[20:21], 0, v[206:207]
	s_mov_b32 m0, s70
	s_nop 0
	global_load_lds_dwordx4 v[196:197], off
	v_lshl_add_u64 v[196:197], v[208:209], 0, s[76:77]
	s_mov_b32 m0, s66
	s_nop 0
	global_load_lds_dwordx4 v[196:197], off
	v_lshl_add_u64 v[196:197], v[210:211], 0, s[76:77]
	s_mov_b32 m0, s67
	s_nop 0
	global_load_lds_dwordx4 v[196:197], off
	s_waitcnt vmcnt(8)
	s_waitcnt lgkmcnt(0)
	s_barrier
	v_mfma_f32_16x16x32_bf16 v[84:87], v[132:135], v[164:167], v[84:87]
	v_mfma_f32_16x16x32_bf16 v[84:87], v[136:139], v[168:171], v[84:87]
	v_mfma_f32_16x16x32_bf16 v[72:75], v[132:135], v[172:175], v[72:75]
	v_mfma_f32_16x16x32_bf16 v[72:75], v[136:139], v[176:179], v[72:75]
	v_mfma_f32_16x16x32_bf16 v[60:63], v[132:135], v[180:183], v[60:63]
	v_mfma_f32_16x16x32_bf16 v[60:63], v[136:139], v[184:187], v[60:63]
	v_mfma_f32_16x16x32_bf16 v[48:51], v[132:135], v[188:191], v[48:51]
	v_mfma_f32_16x16x32_bf16 v[48:51], v[136:139], v[192:195], v[48:51]
	v_mfma_f32_16x16x32_bf16 v[76:79], v[140:143], v[164:167], v[76:79]
	v_mfma_f32_16x16x32_bf16 v[76:79], v[144:147], v[168:171], v[76:79]
	v_mfma_f32_16x16x32_bf16 v[68:71], v[140:143], v[172:175], v[68:71]
	v_mfma_f32_16x16x32_bf16 v[68:71], v[144:147], v[176:179], v[68:71]
	v_mfma_f32_16x16x32_bf16 v[56:59], v[140:143], v[180:183], v[56:59]
	v_mfma_f32_16x16x32_bf16 v[56:59], v[144:147], v[184:187], v[56:59]
	v_mfma_f32_16x16x32_bf16 v[44:47], v[140:143], v[188:191], v[44:47]
	v_mfma_f32_16x16x32_bf16 v[44:47], v[144:147], v[192:195], v[44:47]
	v_mfma_f32_16x16x32_bf16 v[40:43], v[148:151], v[164:167], v[40:43]
	v_mfma_f32_16x16x32_bf16 v[40:43], v[152:155], v[168:171], v[40:43]
	v_mfma_f32_16x16x32_bf16 v[28:31], v[148:151], v[172:175], v[28:31]
	v_mfma_f32_16x16x32_bf16 v[28:31], v[152:155], v[176:179], v[28:31]
	v_mfma_f32_16x16x32_bf16 v[16:19], v[148:151], v[180:183], v[16:19]
	v_mfma_f32_16x16x32_bf16 v[16:19], v[152:155], v[184:187], v[16:19]
	v_mfma_f32_16x16x32_bf16 v[8:11], v[148:151], v[188:191], v[8:11]
	v_mfma_f32_16x16x32_bf16 v[8:11], v[152:155], v[192:195], v[8:11]
	v_mfma_f32_16x16x32_bf16 v[36:39], v[156:159], v[164:167], v[36:39]
	v_mfma_f32_16x16x32_bf16 v[36:39], v[160:163], v[168:171], v[36:39]
	v_mfma_f32_16x16x32_bf16 v[24:27], v[156:159], v[172:175], v[24:27]
	v_mfma_f32_16x16x32_bf16 v[24:27], v[160:163], v[176:179], v[24:27]
	v_mfma_f32_16x16x32_bf16 v[12:15], v[156:159], v[180:183], v[12:15]
	v_mfma_f32_16x16x32_bf16 v[12:15], v[160:163], v[184:187], v[12:15]
	v_mfma_f32_16x16x32_bf16 v[4:7], v[156:159], v[188:191], v[4:7]
	v_mfma_f32_16x16x32_bf16 v[4:7], v[160:163], v[192:195], v[4:7]
	s_barrier
	s_cmp_ge_u32 s14, s24
	s_mov_b32 s39, s14
	s_cbranch_scc1 .LBB0_1776
